# speedup vs baseline: 1.0476x; 1.0093x over previous
; template <bool FINAL>
; DEVINL void norm_phase(CParams& p, const Ctx& cx, bool from_x, int row0, int nrows, u16* dst, const float* gain, int l, int shi) {
;     ...
;   for (int row = cx.bid * 8 + wave; row < nrows; row += nw) {
;     const int grow = row0 + row;
;     const float4* xr = (const float4*)(from_x ? x_row(p, grow) : p.out + (size_t)grow * DM);
;     float4 v[4]; float ss = 0.f;
; #pragma unroll
;     for (int i = 0; i < 4; ++i) { v[i] = xr[lane + 64 * i]; ss += v[i].x * v[i].x + v[i].y * v[i].y + v[i].z * v[i].z + v[i].w * v[i].w; }
;     ss = wave_sum(ss, lane);
;     const float r = rsqrtf(ss * (1.f / DM) + 1e-6f);
;     if (FINAL) {
; #pragma unroll
;       for (int i = 0; i < 4; ++i) {
;         const int c = (lane + 64 * i) * 4;
;         const float4 g = *(const float4*)(gain + c);
;         float4 o; o.x = v[i].x * r * g.x; o.y = v[i].y * r * g.y; o.z = v[i].z * r * g.z; o.w = v[i].w * r * g.w;
;         *(float4*)(p.out + (size_t)grow * DM + c) = o;
;       }
;     } else {
;       const float* mp = p.mod + (size_t)seq_of_row(grow) * (2 * MODW) + l * MODW + shi * DM;
; #pragma unroll
;       for (int i = 0; i < 4; ++i) {
;         const int c = (lane + 64 * i) * 4;
;         const float4 g = *(const float4*)(gain + c);
;         const float4 sh = *(const float4*)(mp + c);
;         const float4 sc = *(const float4*)(mp + DM + c);
;         *(bf16x4*)(dst + (size_t)row * DM + c) = pack4(v[i].x * r * g.x * (1.f + sc.x) + sh.x, v[i].y * r * g.y * (1.f + sc.y) + sh.y,
;                                                         v[i].z * r * g.z * (1.f + sc.z) + sh.z, v[i].w * r * g.w * (1.f + sc.w) + sh.w);
;       }
.LBB0_88:
	v_lshl_add_u64 v[20:21], v[20:21], 0, v[0:1]
	global_load_dwordx4 v[28:31], v[20:21], off
	global_load_dwordx4 v[32:35], v[20:21], off offset:1024
	global_load_dwordx4 v[36:39], v[20:21], off offset:2048
	global_load_dwordx4 v[40:43], v[20:21], off offset:3072
	v_lshrrev_b32_e32 v15, 11, v11
	v_ashrrev_i32_e32 v13, 12, v6
	v_add_u32_e32 v15, 16, v15
	v_cmp_gt_i32_e32 vcc, s58, v6
	v_mov_b32_e32 v11, v1
	s_mov_b32 s4, 0x800000
	v_cndmask_b32_e32 v13, v15, v13, vcc
	v_mul_hi_i32_i24_e32 v21, 0x12000, v13
	v_mul_i32_i24_e32 v20, 0x12000, v13
	v_lshl_add_u64 v[20:21], s[14:15], 0, v[20:21]
	v_lshl_add_u64 v[56:57], v[20:21], 0, s[62:63]
	v_lshl_add_u64 v[44:45], v[56:57], 0, v[10:11]
	global_load_dwordx4 v[44:47], v[44:45], off
	s_nop 0
	global_load_dwordx4 v[48:51], v[2:3], off
	v_lshl_add_u64 v[58:59], v[20:21], 0, v[10:11]
	global_load_dwordx4 v[52:55], v[58:59], off
	v_lshlrev_b64 v[18:19], 11, v[18:19]
	v_mov_b32_e32 v17, v1
	s_waitcnt vmcnt(0)
	v_mov_b32_e32 v64, v29
	v_mov_b32_e32 v65, v33
	v_mov_b32_e32 v62, v28
	v_mov_b32_e32 v63, v32
	v_mov_b32_e32 v72, v37
	v_mov_b32_e32 v73, v41
	v_pk_mul_f32 v[64:65], v[64:65], v[64:65]
	v_mov_b32_e32 v20, v30
	v_mov_b32_e32 v21, v34
	v_mov_b32_e32 v70, v36
	v_mov_b32_e32 v71, v40
	v_pk_mul_f32 v[72:73], v[72:73], v[72:73]
	v_pk_fma_f32 v[62:63], v[62:63], v[62:63], v[64:65]
	v_mov_b32_e32 v60, v31
	v_mov_b32_e32 v61, v35
	v_mov_b32_e32 v66, v38
	v_mov_b32_e32 v67, v42
	v_pk_fma_f32 v[64:65], v[70:71], v[70:71], v[72:73]
	v_pk_fma_f32 v[20:21], v[20:21], v[20:21], v[62:63]
	v_mov_b32_e32 v68, v39
	v_mov_b32_e32 v69, v43
	v_pk_fma_f32 v[62:63], v[66:67], v[66:67], v[64:65]
	v_pk_fma_f32 v[20:21], v[60:61], v[60:61], v[20:21]
	v_pk_fma_f32 v[60:61], v[68:69], v[68:69], v[62:63]
	v_add_f32_e32 v11, v20, v21
	v_add_f32_e32 v11, v11, v60
	v_add_f32_e32 v11, v11, v61
	v_mov_b32_e32 v13, v11
	s_nop 1
	v_permlane32_swap_b32_e32 v13, v11
	v_lshl_add_u64 v[60:61], v[4:5], 0, v[18:19]
	v_pk_add_f32 v[18:19], v[44:45], 1.0 op_sel_hi:[1,0]
	v_pk_add_f32 v[20:21], v[46:47], 1.0 op_sel_hi:[1,0]
	s_waitcnt lgkmcnt(0)
	v_add_f32_e32 v11, v11, v13
	v_mov_b32_e32 v13, v11
	s_nop 1
	v_permlane16_swap_b32_e32 v11, v13
	s_waitcnt lgkmcnt(0)
	v_add_f32_e32 v11, v11, v13
	s_nop 1
	v_mov_b32_dpp v13, v11 row_ror:8 row_mask:0xf bank_mask:0xf
	s_waitcnt lgkmcnt(0)
	v_add_f32_e32 v11, v11, v13
	s_nop 1
	v_mov_b32_dpp v13, v11 row_shl:4 row_mask:0xf bank_mask:0x5
	v_mov_b32_dpp v13, v11 row_shr:4 row_mask:0xf bank_mask:0xa
	s_waitcnt lgkmcnt(0)
	v_add_f32_e32 v11, v11, v13
	s_nop 1
	v_mov_b32_dpp v13, v11 quad_perm:[2,3,0,1] row_mask:0xf bank_mask:0xf
	s_waitcnt lgkmcnt(0)
	v_add_f32_e32 v11, v11, v13
	s_nop 1
	v_mov_b32_dpp v15, v11 quad_perm:[1,0,3,2] row_mask:0xf bank_mask:0xf
	v_mov_b32_e32 v13, v1
	v_lshl_add_u64 v[62:63], v[56:57], 0, v[12:13]
	s_waitcnt lgkmcnt(0)
	v_add_f32_e32 v11, v11, v15
	v_fmamk_f32 v11, v11, 0x3a800000, v243
	v_mul_f32_e32 v15, 0x4b800000, v11
	v_cmp_gt_f32_e32 vcc, s4, v11
	v_readlane_b32 s4, v255, 36
	v_readlane_b32 s5, v255, 37
	v_cndmask_b32_e32 v11, v11, v15, vcc
	v_rsq_f32_e32 v11, v11
	v_mov_b32_e32 v15, v1
	v_lshl_add_u64 v[6:7], v[6:7], 0, s[4:5]
	v_readlane_b32 s4, v255, 34
	v_mul_f32_e32 v13, 0x45800000, v11
	v_cndmask_b32_e32 v64, v11, v13, vcc
	v_pk_mul_f32 v[28:29], v[28:29], v[64:65] op_sel_hi:[1,0]
	v_pk_mul_f32 v[30:31], v[30:31], v[64:65] op_sel_hi:[1,0]
	v_pk_mul_f32 v[28:29], v[48:49], v[28:29]
	v_pk_mul_f32 v[30:31], v[50:51], v[30:31]
	v_pk_fma_f32 v[18:19], v[18:19], v[28:29], v[52:53]
	v_pk_fma_f32 v[20:21], v[20:21], v[30:31], v[54:55]
	v_cvt_pk_bf16_f32 v18, v18, v19
	v_cvt_pk_bf16_f32 v19, v20, v21
	global_store_dwordx2 v[60:61], v[18:19], off
	global_load_dwordx4 v[18:21], v[2:3], off offset:1024
	s_nop 0
	global_load_dwordx4 v[28:31], v[62:63], off
	global_load_dwordx4 v[44:47], v[58:59], off offset:1024
	v_pk_mul_f32 v[32:33], v[32:33], v[64:65] op_sel_hi:[1,0]
	v_pk_mul_f32 v[34:35], v[34:35], v[64:65] op_sel_hi:[1,0]
	v_lshl_add_u64 v[48:49], v[56:57], 0, v[14:15]
	v_pk_mul_f32 v[36:37], v[36:37], v[64:65] op_sel_hi:[1,0]
	v_pk_mul_f32 v[38:39], v[38:39], v[64:65] op_sel_hi:[1,0]
	v_cmp_lt_i32_e32 vcc, s56, v6
	v_readlane_b32 s5, v255, 35
	s_or_b64 s[18:19], vcc, s[18:19]
	s_waitcnt vmcnt(2)
	v_pk_mul_f32 v[18:19], v[32:33], v[18:19]
	s_waitcnt vmcnt(1)
	v_pk_add_f32 v[28:29], v[28:29], 1.0 op_sel_hi:[1,0]
	v_pk_mul_f32 v[20:21], v[34:35], v[20:21]
	v_pk_add_f32 v[30:31], v[30:31], 1.0 op_sel_hi:[1,0]
	s_waitcnt vmcnt(0)
	v_pk_fma_f32 v[18:19], v[18:19], v[28:29], v[44:45]
	v_pk_fma_f32 v[20:21], v[20:21], v[30:31], v[46:47]
	v_cvt_pk_bf16_f32 v18, v18, v19
	v_cvt_pk_bf16_f32 v19, v20, v21
	global_store_dwordx2 v[60:61], v[18:19], off offset:512
	global_load_dwordx4 v[18:21], v[2:3], off offset:2048
	s_nop 0
	global_load_dwordx4 v[28:31], v[48:49], off
	global_load_dwordx4 v[32:35], v[58:59], off offset:2048
	v_lshl_add_u64 v[44:45], v[56:57], 0, v[16:17]
	v_lshl_add_u64 v[8:9], v[8:9], 0, s[4:5]
	s_waitcnt vmcnt(2)
	v_pk_mul_f32 v[18:19], v[36:37], v[18:19]
	s_waitcnt vmcnt(1)
	v_pk_add_f32 v[28:29], v[28:29], 1.0 op_sel_hi:[1,0]
	v_pk_mul_f32 v[20:21], v[38:39], v[20:21]
	v_pk_add_f32 v[30:31], v[30:31], 1.0 op_sel_hi:[1,0]
	s_waitcnt vmcnt(0)
	v_pk_fma_f32 v[18:19], v[18:19], v[28:29], v[32:33]
	v_pk_fma_f32 v[20:21], v[20:21], v[30:31], v[34:35]
	v_cvt_pk_bf16_f32 v18, v18, v19
	v_cvt_pk_bf16_f32 v19, v20, v21
	global_store_dwordx2 v[60:61], v[18:19], off offset:1024
	global_load_dwordx4 v[18:21], v[2:3], off offset:3072
	s_nop 0
	global_load_dwordx4 v[28:31], v[44:45], off
	global_load_dwordx4 v[32:35], v[58:59], off offset:3072
	v_pk_mul_f32 v[36:37], v[40:41], v[64:65] op_sel_hi:[1,0]
	v_pk_mul_f32 v[38:39], v[42:43], v[64:65] op_sel_hi:[1,0]
	s_waitcnt vmcnt(2)
	v_pk_mul_f32 v[18:19], v[36:37], v[18:19]
	s_waitcnt vmcnt(1)
	v_pk_add_f32 v[28:29], v[28:29], 1.0 op_sel_hi:[1,0]
	v_pk_mul_f32 v[20:21], v[38:39], v[20:21]
	v_pk_add_f32 v[30:31], v[30:31], 1.0 op_sel_hi:[1,0]
	s_waitcnt vmcnt(0)
	v_pk_fma_f32 v[18:19], v[18:19], v[28:29], v[32:33]
	v_pk_fma_f32 v[20:21], v[20:21], v[30:31], v[34:35]
	v_cvt_pk_bf16_f32 v18, v18, v19
	v_cvt_pk_bf16_f32 v19, v20, v21
	global_store_dwordx2 v[60:61], v[18:19], off offset:1536
	s_andn2_b64 exec, exec, s[18:19]
	s_cbranch_execz .LBB0_93

; template <bool FINAL>
; DEVINL void norm_phase(CParams& p, const Ctx& cx, bool from_x, int row0, int nrows, u16* dst, const float* gain, int l, int shi) {
;     ...
;   for (int row = cx.bid * 8 + wave; row < nrows; row += nw) {
;     const int grow = row0 + row;
;     const float4* xr = (const float4*)(from_x ? x_row(p, grow) : p.out + (size_t)grow * DM);
;     float4 v[4]; float ss = 0.f;
; #pragma unroll
;     for (int i = 0; i < 4; ++i) { v[i] = xr[lane + 64 * i]; ss += v[i].x * v[i].x + v[i].y * v[i].y + v[i].z * v[i].z + v[i].w * v[i].w; }
;     ss = wave_sum(ss, lane);
;     const float r = rsqrtf(ss * (1.f / DM) + 1e-6f);
;     if (FINAL) {
; #pragma unroll
;       for (int i = 0; i < 4; ++i) {
;         const int c = (lane + 64 * i) * 4;
;         const float4 g = *(const float4*)(gain + c);
;         float4 o; o.x = v[i].x * r * g.x; o.y = v[i].y * r * g.y; o.z = v[i].z * r * g.z; o.w = v[i].w * r * g.w;
;         *(float4*)(p.out + (size_t)grow * DM + c) = o;
;       }
;     } else {
;       const float* mp = p.mod + (size_t)seq_of_row(grow) * (2 * MODW) + l * MODW + shi * DM;
; #pragma unroll
;       for (int i = 0; i < 4; ++i) {
;         const int c = (lane + 64 * i) * 4;
;         const float4 g = *(const float4*)(gain + c);
;         const float4 sh = *(const float4*)(mp + c);
;         const float4 sc = *(const float4*)(mp + DM + c);
;         *(bf16x4*)(dst + (size_t)row * DM + c) = pack4(v[i].x * r * g.x * (1.f + sc.x) + sh.x, v[i].y * r * g.y * (1.f + sc.y) + sh.y,
;                                                         v[i].z * r * g.z * (1.f + sc.z) + sh.z, v[i].w * r * g.w * (1.f + sc.w) + sh.w);
;       }
.LBB0_107:
	v_add_u32_e32 v2, s5, v50
	v_add_u32_e32 v3, 0xffff0000, v2
	v_lshrrev_b32_e32 v3, 11, v3
	v_cmp_gt_i32_e32 vcc, s58, v2
	v_ashrrev_i32_e32 v2, 12, v2
	v_add_u32_e32 v3, 16, v3
	v_cndmask_b32_e32 v2, v3, v2, vcc
	v_mul_hi_i32_i24_e32 v3, 0x12000, v2
	v_mul_i32_i24_e32 v2, 0x12000, v2
	v_lshl_add_u64 v[2:3], s[12:13], 0, v[2:3]
	v_lshl_add_u64 v[42:43], v[2:3], 0, s[28:29]
	v_lshl_add_u64 v[38:39], v[2:3], 0, v[0:1]
	v_lshl_add_u64 v[2:3], v[42:43], 0, v[0:1]
	global_load_dwordx4 v[18:21], v[28:29], off offset:-2048
	global_load_dwordx4 v[14:17], v[26:27], off
	global_load_dwordx4 v[10:13], v[38:39], off
	s_nop 0
	global_load_dwordx4 v[2:5], v[2:3], off
	v_mov_b32_e32 v33, v1
	global_load_dwordx4 v[6:9], v[28:29], off offset:-1024
	v_lshl_add_u64 v[44:45], v[42:43], 0, v[32:33]
	v_mov_b32_e32 v35, v1
	v_lshl_add_u64 v[40:41], v[42:43], 0, v[34:35]
	v_mov_b32_e32 v37, v1
	v_lshl_add_u64 v[42:43], v[42:43], 0, v[36:37]
	v_add_u32_e32 v50, s22, v50
	s_waitcnt vmcnt(0)
	v_mov_b32_e32 v24, v19
	v_mov_b32_e32 v22, v18
	v_pk_add_f32 v[48:49], v[2:3], 1.0 op_sel_hi:[1,0]
	v_mov_b32_e32 v2, v20
	v_mov_b32_e32 v25, v7
	v_mov_b32_e32 v23, v6
	v_pk_mul_f32 v[24:25], v[24:25], v[24:25]
	v_mov_b32_e32 v3, v8
	v_pk_fma_f32 v[22:23], v[22:23], v[22:23], v[24:25]
	v_pk_add_f32 v[46:47], v[4:5], 1.0 op_sel_hi:[1,0]
	v_mov_b32_e32 v4, v21
	v_mov_b32_e32 v5, v9
	v_pk_fma_f32 v[2:3], v[2:3], v[2:3], v[22:23]
	global_load_dwordx4 v[22:25], v[28:29], off
	v_pk_fma_f32 v[58:59], v[4:5], v[4:5], v[2:3]
	global_load_dwordx4 v[2:5], v[28:29], off offset:1024
	v_add_f32_e32 v33, v58, v59
	v_lshl_add_u64 v[28:29], v[28:29], 0, s[24:25]
	s_waitcnt vmcnt(1)
	v_mov_b32_e32 v66, v23
	v_mov_b32_e32 v64, v22
	s_waitcnt vmcnt(0)
	v_mov_b32_e32 v67, v3
	v_mov_b32_e32 v65, v2
	v_pk_mul_f32 v[66:67], v[66:67], v[66:67]
	v_mov_b32_e32 v60, v24
	v_mov_b32_e32 v61, v4
	v_pk_fma_f32 v[64:65], v[64:65], v[64:65], v[66:67]
	v_mov_b32_e32 v62, v25
	v_mov_b32_e32 v63, v5
	v_pk_fma_f32 v[60:61], v[60:61], v[60:61], v[64:65]
	s_nop 0
	v_pk_fma_f32 v[60:61], v[62:63], v[62:63], v[60:61]
	s_nop 0
	v_add_f32_e32 v33, v33, v60
	v_add_f32_e32 v33, v33, v61
	v_mov_b32_e32 v35, v33
	s_nop 1
	v_permlane32_swap_b32_e32 v35, v33
	s_waitcnt lgkmcnt(0)
	v_add_f32_e32 v33, v33, v35
	v_mov_b32_e32 v35, v33
	s_nop 1
	v_permlane16_swap_b32_e32 v33, v35
	s_waitcnt lgkmcnt(0)
	v_add_f32_e32 v33, v33, v35
	s_nop 1
	v_mov_b32_dpp v35, v33 row_ror:8 row_mask:0xf bank_mask:0xf
	s_waitcnt lgkmcnt(0)
	v_add_f32_e32 v33, v33, v35
	s_nop 1
	v_mov_b32_dpp v35, v33 row_shl:4 row_mask:0xf bank_mask:0x5
	v_mov_b32_dpp v35, v33 row_shr:4 row_mask:0xf bank_mask:0xa
	s_waitcnt lgkmcnt(0)
	v_add_f32_e32 v33, v33, v35
	s_nop 1
	v_mov_b32_dpp v35, v33 quad_perm:[2,3,0,1] row_mask:0xf bank_mask:0xf
	s_waitcnt lgkmcnt(0)
	v_add_f32_e32 v33, v33, v35
	s_nop 1
	v_mov_b32_dpp v35, v33 quad_perm:[1,0,3,2] row_mask:0xf bank_mask:0xf
	s_waitcnt lgkmcnt(0)
	v_add_f32_e32 v33, v33, v35
	v_fmamk_f32 v33, v33, 0x3a800000, v243
	v_cmp_gt_f32_e32 vcc, s23, v33
	v_mul_f32_e32 v35, 0x4b800000, v33
	s_nop 0
	v_cndmask_b32_e32 v33, v33, v35, vcc
	v_rsq_f32_e32 v33, v33
	s_nop 0
	v_mul_f32_e32 v35, 0x45800000, v33
	v_cndmask_b32_e32 v58, v33, v35, vcc
	v_pk_mul_f32 v[18:19], v[18:19], v[58:59] op_sel_hi:[1,0]
	v_pk_mul_f32 v[6:7], v[6:7], v[58:59] op_sel_hi:[1,0]
	v_pk_mul_f32 v[14:15], v[14:15], v[18:19]
	v_pk_mul_f32 v[8:9], v[8:9], v[58:59] op_sel_hi:[1,0]
	v_pk_fma_f32 v[10:11], v[48:49], v[14:15], v[10:11]
	v_pk_mul_f32 v[14:15], v[20:21], v[58:59] op_sel_hi:[1,0]
	v_cvt_pk_bf16_f32 v10, v10, v11
	v_pk_mul_f32 v[14:15], v[16:17], v[14:15]
	v_pk_mul_f32 v[2:3], v[2:3], v[58:59] op_sel_hi:[1,0]
	v_pk_fma_f32 v[12:13], v[46:47], v[14:15], v[12:13]
	v_pk_mul_f32 v[4:5], v[4:5], v[58:59] op_sel_hi:[1,0]
	v_cvt_pk_bf16_f32 v11, v12, v13
	global_store_dwordx2 v[30:31], v[10:11], off offset:-1024
	global_load_dwordx4 v[10:13], v[26:27], off offset:1024
	s_nop 0
	global_load_dwordx4 v[14:17], v[38:39], off offset:1024
	global_load_dwordx4 v[18:21], v[44:45], off
	v_cmp_le_i32_e32 vcc, s63, v50
	s_or_b64 s[14:15], vcc, s[14:15]
	s_waitcnt vmcnt(2)
	v_pk_mul_f32 v[6:7], v[6:7], v[10:11]
	v_pk_mul_f32 v[8:9], v[8:9], v[12:13]
	s_waitcnt vmcnt(0)
	v_pk_add_f32 v[10:11], v[18:19], 1.0 op_sel_hi:[1,0]
	v_pk_mul_f32 v[18:19], v[22:23], v[58:59] op_sel_hi:[1,0]
	v_pk_fma_f32 v[6:7], v[6:7], v[10:11], v[14:15]
	v_pk_add_f32 v[10:11], v[20:21], 1.0 op_sel_hi:[1,0]
	v_cvt_pk_bf16_f32 v6, v6, v7
	v_pk_fma_f32 v[8:9], v[8:9], v[10:11], v[16:17]
	s_nop 0
	v_cvt_pk_bf16_f32 v7, v8, v9
	global_store_dwordx2 v[30:31], v[6:7], off offset:-512
	global_load_dwordx4 v[6:9], v[26:27], off offset:2048
	s_nop 0
	global_load_dwordx4 v[10:13], v[38:39], off offset:2048
	global_load_dwordx4 v[14:17], v[40:41], off
	s_waitcnt vmcnt(2)
	v_pk_mul_f32 v[6:7], v[18:19], v[6:7]
	s_waitcnt vmcnt(0)
	v_pk_add_f32 v[14:15], v[14:15], 1.0 op_sel_hi:[1,0]
	s_nop 0
	v_pk_fma_f32 v[6:7], v[6:7], v[14:15], v[10:11]
	v_pk_mul_f32 v[10:11], v[24:25], v[58:59] op_sel_hi:[1,0]
	v_cvt_pk_bf16_f32 v6, v6, v7
	v_pk_mul_f32 v[8:9], v[10:11], v[8:9]
	v_pk_add_f32 v[10:11], v[16:17], 1.0 op_sel_hi:[1,0]
	s_nop 0
	v_pk_fma_f32 v[8:9], v[8:9], v[10:11], v[12:13]
	s_nop 0
	v_cvt_pk_bf16_f32 v7, v8, v9
	global_store_dwordx2 v[30:31], v[6:7], off
	global_load_dwordx4 v[6:9], v[26:27], off offset:3072
	s_nop 0
	global_load_dwordx4 v[10:13], v[38:39], off offset:3072
	global_load_dwordx4 v[14:17], v[42:43], off
	s_waitcnt vmcnt(2)
	v_pk_mul_f32 v[2:3], v[2:3], v[6:7]
	v_pk_mul_f32 v[4:5], v[4:5], v[8:9]
	s_waitcnt vmcnt(0)
	v_pk_add_f32 v[6:7], v[14:15], 1.0 op_sel_hi:[1,0]
	s_nop 0
	v_pk_fma_f32 v[2:3], v[2:3], v[6:7], v[10:11]
	v_pk_add_f32 v[6:7], v[16:17], 1.0 op_sel_hi:[1,0]
	v_cvt_pk_bf16_f32 v2, v2, v3
	v_pk_fma_f32 v[4:5], v[4:5], v[6:7], v[12:13]
	s_nop 0
	v_cvt_pk_bf16_f32 v3, v4, v5
	global_store_dwordx2 v[30:31], v[2:3], off offset:512
	v_lshl_add_u64 v[30:31], v[30:31], 0, s[26:27]
	s_andn2_b64 exec, exec, s[14:15]
	s_cbranch_execnz .LBB0_107

; template <bool FINAL>
; DEVINL void norm_phase(CParams& p, const Ctx& cx, bool from_x, int row0, int nrows, u16* dst, const float* gain, int l, int shi) {
;     ...
;   for (int row = cx.bid * 8 + wave; row < nrows; row += nw) {
;     const int grow = row0 + row;
;     const float4* xr = (const float4*)(from_x ? x_row(p, grow) : p.out + (size_t)grow * DM);
;     float4 v[4]; float ss = 0.f;
; #pragma unroll
;     for (int i = 0; i < 4; ++i) { v[i] = xr[lane + 64 * i]; ss += v[i].x * v[i].x + v[i].y * v[i].y + v[i].z * v[i].z + v[i].w * v[i].w; }
;     ss = wave_sum(ss, lane);
;     const float r = rsqrtf(ss * (1.f / DM) + 1e-6f);
;     if (FINAL) {
; #pragma unroll
;       for (int i = 0; i < 4; ++i) {
;         const int c = (lane + 64 * i) * 4;
;         const float4 g = *(const float4*)(gain + c);
;         float4 o; o.x = v[i].x * r * g.x; o.y = v[i].y * r * g.y; o.z = v[i].z * r * g.z; o.w = v[i].w * r * g.w;
;         *(float4*)(p.out + (size_t)grow * DM + c) = o;
;       }
;     } else {
;       const float* mp = p.mod + (size_t)seq_of_row(grow) * (2 * MODW) + l * MODW + shi * DM;
; #pragma unroll
;       for (int i = 0; i < 4; ++i) {
;         const int c = (lane + 64 * i) * 4;
;         const float4 g = *(const float4*)(gain + c);
;         const float4 sh = *(const float4*)(mp + c);
;         const float4 sc = *(const float4*)(mp + DM + c);
;         *(bf16x4*)(dst + (size_t)row * DM + c) = pack4(v[i].x * r * g.x * (1.f + sc.x) + sh.x, v[i].y * r * g.y * (1.f + sc.y) + sh.y,
;                                                         v[i].z * r * g.z * (1.f + sc.z) + sh.z, v[i].w * r * g.w * (1.f + sc.w) + sh.w);
;       }
.LBB0_121:
	v_add_u32_e32 v2, s10, v50
	v_add_u32_e32 v3, 0xffff0000, v2
	v_lshrrev_b32_e32 v3, 11, v3
	v_cmp_gt_i32_e32 vcc, s58, v2
	v_ashrrev_i32_e32 v2, 12, v2
	v_add_u32_e32 v3, 16, v3
	v_cndmask_b32_e32 v2, v3, v2, vcc
	v_mul_hi_i32_i24_e32 v3, 0x12000, v2
	v_mul_i32_i24_e32 v2, 0x12000, v2
	v_lshl_add_u64 v[2:3], s[6:7], 0, v[2:3]
	v_lshl_add_u64 v[42:43], v[2:3], 0, s[22:23]
	v_lshl_add_u64 v[38:39], v[2:3], 0, v[0:1]
	v_lshl_add_u64 v[2:3], v[42:43], 0, v[0:1]
	global_load_dwordx4 v[18:21], v[28:29], off offset:-2048
	global_load_dwordx4 v[14:17], v[26:27], off
	global_load_dwordx4 v[10:13], v[38:39], off
	s_nop 0
	global_load_dwordx4 v[2:5], v[2:3], off
	v_mov_b32_e32 v33, v1
	global_load_dwordx4 v[6:9], v[28:29], off offset:-1024
	v_lshl_add_u64 v[44:45], v[42:43], 0, v[32:33]
	v_mov_b32_e32 v35, v1
	v_lshl_add_u64 v[40:41], v[42:43], 0, v[34:35]
	v_mov_b32_e32 v37, v1
	v_lshl_add_u64 v[42:43], v[42:43], 0, v[36:37]
	v_add_u32_e32 v50, s16, v50
	s_waitcnt vmcnt(0)
	v_mov_b32_e32 v24, v19
	v_mov_b32_e32 v22, v18
	v_pk_add_f32 v[48:49], v[2:3], 1.0 op_sel_hi:[1,0]
	v_mov_b32_e32 v2, v20
	v_mov_b32_e32 v25, v7
	v_mov_b32_e32 v23, v6
	v_pk_mul_f32 v[24:25], v[24:25], v[24:25]
	v_mov_b32_e32 v3, v8
	v_pk_fma_f32 v[22:23], v[22:23], v[22:23], v[24:25]
	v_pk_add_f32 v[46:47], v[4:5], 1.0 op_sel_hi:[1,0]
	v_mov_b32_e32 v4, v21
	v_mov_b32_e32 v5, v9
	v_pk_fma_f32 v[2:3], v[2:3], v[2:3], v[22:23]
	global_load_dwordx4 v[22:25], v[28:29], off
	v_pk_fma_f32 v[58:59], v[4:5], v[4:5], v[2:3]
	global_load_dwordx4 v[2:5], v[28:29], off offset:1024
	v_add_f32_e32 v33, v58, v59
	v_lshl_add_u64 v[28:29], v[28:29], 0, s[18:19]
	s_waitcnt vmcnt(1)
	v_mov_b32_e32 v66, v23
	v_mov_b32_e32 v64, v22
	s_waitcnt vmcnt(0)
	v_mov_b32_e32 v67, v3
	v_mov_b32_e32 v65, v2
	v_pk_mul_f32 v[66:67], v[66:67], v[66:67]
	v_mov_b32_e32 v60, v24
	v_mov_b32_e32 v61, v4
	v_pk_fma_f32 v[64:65], v[64:65], v[64:65], v[66:67]
	v_mov_b32_e32 v62, v25
	v_mov_b32_e32 v63, v5
	v_pk_fma_f32 v[60:61], v[60:61], v[60:61], v[64:65]
	s_nop 0
	v_pk_fma_f32 v[60:61], v[62:63], v[62:63], v[60:61]
	s_nop 0
	v_add_f32_e32 v33, v33, v60
	v_add_f32_e32 v33, v33, v61
	v_mov_b32_e32 v35, v33
	s_nop 1
	v_permlane32_swap_b32_e32 v35, v33
	s_waitcnt lgkmcnt(0)
	v_add_f32_e32 v33, v33, v35
	v_mov_b32_e32 v35, v33
	s_nop 1
	v_permlane16_swap_b32_e32 v33, v35
	s_waitcnt lgkmcnt(0)
	v_add_f32_e32 v33, v33, v35
	s_nop 1
	v_mov_b32_dpp v35, v33 row_ror:8 row_mask:0xf bank_mask:0xf
	s_waitcnt lgkmcnt(0)
	v_add_f32_e32 v33, v33, v35
	s_nop 1
	v_mov_b32_dpp v35, v33 row_shl:4 row_mask:0xf bank_mask:0x5
	v_mov_b32_dpp v35, v33 row_shr:4 row_mask:0xf bank_mask:0xa
	s_waitcnt lgkmcnt(0)
	v_add_f32_e32 v33, v33, v35
	s_nop 1
	v_mov_b32_dpp v35, v33 quad_perm:[2,3,0,1] row_mask:0xf bank_mask:0xf
	s_waitcnt lgkmcnt(0)
	v_add_f32_e32 v33, v33, v35
	s_nop 1
	v_mov_b32_dpp v35, v33 quad_perm:[1,0,3,2] row_mask:0xf bank_mask:0xf
	s_waitcnt lgkmcnt(0)
	v_add_f32_e32 v33, v33, v35
	v_fmamk_f32 v33, v33, 0x3a800000, v243
	v_cmp_gt_f32_e32 vcc, s17, v33
	v_mul_f32_e32 v35, 0x4b800000, v33
	s_nop 0
	v_cndmask_b32_e32 v33, v33, v35, vcc
	v_rsq_f32_e32 v33, v33
	s_nop 0
	v_mul_f32_e32 v35, 0x45800000, v33
	v_cndmask_b32_e32 v58, v33, v35, vcc
	v_pk_mul_f32 v[18:19], v[18:19], v[58:59] op_sel_hi:[1,0]
	v_pk_mul_f32 v[6:7], v[6:7], v[58:59] op_sel_hi:[1,0]
	v_pk_mul_f32 v[14:15], v[14:15], v[18:19]
	v_pk_mul_f32 v[8:9], v[8:9], v[58:59] op_sel_hi:[1,0]
	v_pk_fma_f32 v[10:11], v[48:49], v[14:15], v[10:11]
	v_pk_mul_f32 v[14:15], v[20:21], v[58:59] op_sel_hi:[1,0]
	v_cvt_pk_bf16_f32 v10, v10, v11
	v_pk_mul_f32 v[14:15], v[16:17], v[14:15]
	v_pk_mul_f32 v[2:3], v[2:3], v[58:59] op_sel_hi:[1,0]
	v_pk_fma_f32 v[12:13], v[46:47], v[14:15], v[12:13]
	v_pk_mul_f32 v[4:5], v[4:5], v[58:59] op_sel_hi:[1,0]
	v_cvt_pk_bf16_f32 v11, v12, v13
	global_store_dwordx2 v[30:31], v[10:11], off offset:-1024
	global_load_dwordx4 v[10:13], v[26:27], off offset:1024
	s_nop 0
	global_load_dwordx4 v[14:17], v[38:39], off offset:1024
	global_load_dwordx4 v[18:21], v[44:45], off
	v_cmp_le_i32_e32 vcc, s63, v50
	s_or_b64 s[8:9], vcc, s[8:9]
	s_waitcnt vmcnt(2)
	v_pk_mul_f32 v[6:7], v[6:7], v[10:11]
	v_pk_mul_f32 v[8:9], v[8:9], v[12:13]
	s_waitcnt vmcnt(0)
	v_pk_add_f32 v[10:11], v[18:19], 1.0 op_sel_hi:[1,0]
	v_pk_mul_f32 v[18:19], v[22:23], v[58:59] op_sel_hi:[1,0]
	v_pk_fma_f32 v[6:7], v[6:7], v[10:11], v[14:15]
	v_pk_add_f32 v[10:11], v[20:21], 1.0 op_sel_hi:[1,0]
	v_cvt_pk_bf16_f32 v6, v6, v7
	v_pk_fma_f32 v[8:9], v[8:9], v[10:11], v[16:17]
	s_nop 0
	v_cvt_pk_bf16_f32 v7, v8, v9
	global_store_dwordx2 v[30:31], v[6:7], off offset:-512
	global_load_dwordx4 v[6:9], v[26:27], off offset:2048
	s_nop 0
	global_load_dwordx4 v[10:13], v[38:39], off offset:2048
	global_load_dwordx4 v[14:17], v[40:41], off
	s_waitcnt vmcnt(2)
	v_pk_mul_f32 v[6:7], v[18:19], v[6:7]
	s_waitcnt vmcnt(0)
	v_pk_add_f32 v[14:15], v[14:15], 1.0 op_sel_hi:[1,0]
	s_nop 0
	v_pk_fma_f32 v[6:7], v[6:7], v[14:15], v[10:11]
	v_pk_mul_f32 v[10:11], v[24:25], v[58:59] op_sel_hi:[1,0]
	v_cvt_pk_bf16_f32 v6, v6, v7
	v_pk_mul_f32 v[8:9], v[10:11], v[8:9]
	v_pk_add_f32 v[10:11], v[16:17], 1.0 op_sel_hi:[1,0]
	s_nop 0
	v_pk_fma_f32 v[8:9], v[8:9], v[10:11], v[12:13]
	s_nop 0
	v_cvt_pk_bf16_f32 v7, v8, v9
	global_store_dwordx2 v[30:31], v[6:7], off
	global_load_dwordx4 v[6:9], v[26:27], off offset:3072
	s_nop 0
	global_load_dwordx4 v[10:13], v[38:39], off offset:3072
	global_load_dwordx4 v[14:17], v[42:43], off
	s_waitcnt vmcnt(2)
	v_pk_mul_f32 v[2:3], v[2:3], v[6:7]
	v_pk_mul_f32 v[4:5], v[4:5], v[8:9]
	s_waitcnt vmcnt(0)
	v_pk_add_f32 v[6:7], v[14:15], 1.0 op_sel_hi:[1,0]
	s_nop 0
	v_pk_fma_f32 v[2:3], v[2:3], v[6:7], v[10:11]
	v_pk_add_f32 v[6:7], v[16:17], 1.0 op_sel_hi:[1,0]
	v_cvt_pk_bf16_f32 v2, v2, v3
	v_pk_fma_f32 v[4:5], v[4:5], v[6:7], v[12:13]
	s_nop 0
	v_cvt_pk_bf16_f32 v3, v4, v5
	global_store_dwordx2 v[30:31], v[2:3], off offset:512
	v_lshl_add_u64 v[30:31], v[30:31], 0, s[20:21]
	s_andn2_b64 exec, exec, s[8:9]
	s_cbranch_execnz .LBB0_121

; DEVINL float bf2f(u16 h) { return __uint_as_float(((unsigned)h) << 16); }
; DEVINL void ret_out_phase(CParams& p, const Ctx& cx, int l, const GI& gi) {
;     ...
;     const float* gn = p.gn_gain + (size_t)l * DM + h * 256 + fr * 16;
;     float gv[16];
; #pragma unroll
;     for (int q4 = 0; q4 < 4; ++q4) { const float4 g4 = *(const float4*)(gn + q4 * 4); gv[q4 * 4] = g4.x; gv[q4 * 4 + 1] = g4.y; gv[q4 * 4 + 2] = g4.z; gv[q4 * 4 + 3] = g4.w; }
; #pragma unroll
;     for (int j = 0; j < 4; ++j) {
;       float sm = 0.f;
; #pragma unroll
;       for (int et = 0; et < 16; ++et) sm += o[et][j];
; #pragma unroll
;       for (int x = 1; x < 16; x <<= 1) sm += shflx(sm, x, lane);
;       const float mu = sm * (1.f / 256.f);
;       float vs = 0.f;
; #pragma unroll
;       for (int et = 0; et < 16; ++et) { const float d = o[et][j] - mu; vs += d * d; }
; #pragma unroll
;       for (int x = 1; x < 16; x <<= 1) vs += shflx(vs, x, lane);
;       const float rsd = rsqrtf(vs * (1.f / 256.f) + 1e-5f);
;       const size_t ro = (size_t)(row0 + wave * 16 + fq * 4 + j) * DM + h * 256 + fr * 16;
;       const bf16x8 s0 = *(const bf16x8*)(p.sg + ro), s1 = *(const bf16x8*)(p.sg + ro + 8);
;       bf16x8 y0, y1;
; #pragma unroll
;       for (int et = 0; et < 8; ++et) {
;         y0[et] = (short)f2bf(bf2f((u16)s0[et]) * ((o[et][j] - mu) * rsd * gv[et]));
;         y1[et] = (short)f2bf(bf2f((u16)s1[et]) * ((o[et + 8][j] - mu) * rsd * gv[et + 8]));
;       }
;       *(bf16x8*)(p.y + ro) = y0; *(bf16x8*)(p.y + ro + 8) = y1;
.LBB0_268:
	v_add_u32_e32 v0, s28, v99
	s_waitcnt vmcnt(2)
	v_or_b32_e32 v22, v0, v137
	v_ashrrev_i32_e32 v23, 31, v22
	v_lshlrev_b64 v[2:3], 10, v[22:23]
	v_or3_b32 v2, v2, v98, s96
	v_lshlrev_b64 v[24:25], 1, v[2:3]
	s_waitcnt vmcnt(1)
	v_lshl_add_u64 v[26:27], s[6:7], 0, v[24:25]
	v_mov_b32_e32 v170, v26
	v_mov_b32_e32 v171, v27
	global_load_dwordx4 v[18:21], v[26:27], off offset:16
	v_add_f32_e32 v0, 0, v94
	v_lshlrev_b32_e32 v2, 2, v134
	v_add_f32_e32 v3, 0, v95
	v_add_f32_e32 v4, v0, v90
	v_bfrev_b32_e32 v0, 0.5
	v_mov_b32_e32 v104, v94
	v_bitop3_b32 v99, v2, 4, v0 bitop3:0x6c
	v_bitop3_b32 v94, v2, 8, v0 bitop3:0x6c
	v_bitop3_b32 v23, v2, 16, v0 bitop3:0x6c
	v_bitop3_b32 v0, v2, 32, v0 bitop3:0x6c
	v_add_f32_e32 v2, v3, v91
	v_add_f32_e32 v3, v4, v86
	v_add_f32_e32 v11, v3, v78
	v_add_f32_e32 v11, v11, v70
	v_add_f32_e32 v11, v11, v62
	v_add_f32_e32 v11, v11, v54
	v_add_f32_e32 v11, v11, v46
	v_add_f32_e32 v11, v11, v82
	v_add_f32_e32 v11, v11, v74
	v_add_f32_e32 v11, v11, v66
	v_add_f32_e32 v11, v11, v58
	v_add_f32_e32 v11, v11, v50
	v_add_f32_e32 v11, v11, v42
	v_add_f32_e32 v11, v11, v38
	v_add_f32_e32 v11, v11, v34
	s_nop 1
	v_mov_b32_dpp v12, v11 quad_perm:[1,0,3,2] row_mask:0xf bank_mask:0xf
	v_add_f32_e32 v10, v2, v87
	v_add_f32_e32 v10, v10, v79
	v_add_f32_e32 v10, v10, v71
	v_add_f32_e32 v10, v10, v63
	s_waitcnt lgkmcnt(0)
	v_add_f32_e32 v11, v11, v12
	s_nop 1
	v_mov_b32_dpp v12, v11 quad_perm:[2,3,0,1] row_mask:0xf bank_mask:0xf
	v_add_f32_e32 v10, v10, v55
	v_add_f32_e32 v10, v10, v47
	v_add_f32_e32 v10, v10, v83
	v_add_f32_e32 v10, v10, v75
	s_waitcnt lgkmcnt(0)
	v_add_f32_e32 v11, v11, v12
	v_add_f32_e32 v10, v10, v67
	ds_bpermute_b32 v12, v23, v11
	v_add_f32_e32 v10, v10, v59
	s_lshl_b32 s16, s27, 10
	v_add_f32_e32 v10, v10, v51
	s_add_u32 s16, s24, s16
	v_add_f32_e32 v10, v10, v43
	v_lshlrev_b32_e32 v14, 2, v98
	s_addc_u32 s17, s25, 0
	v_add_f32_e32 v10, v10, v39
	v_mov_b32_e32 v101, v42
	v_mov_b32_e32 v103, v34
	global_load_dwordx4 v[2:5], v14, s[16:17] offset:48
	global_load_dwordx4 v[6:9], v14, s[16:17] offset:32
	v_add_f32_e32 v34, v10, v35
	s_waitcnt lgkmcnt(0)
	v_add_f32_e32 v42, v11, v12
	global_load_dwordx4 v[10:13], v14, s[16:17] offset:16
	s_nop 0
	global_load_dwordx4 v[14:17], v14, s[16:17]
	s_nop 0
	global_load_dwordx4 v[26:29], v[26:27], off
	v_mov_b32_e32 v102, v38
	ds_bpermute_b32 v38, v99, v34
	s_waitcnt vmcnt(6)
	v_mov_b32_e32 v33, v58
	v_mov_b32_e32 v100, v50
	ds_bpermute_b32 v50, v0, v42
	v_mov_b32_e32 v105, v90
	s_waitcnt lgkmcnt(1)
	v_add_f32_e32 v38, v34, v38
	s_nop 1
	v_mov_b32_dpp v58, v38 quad_perm:[2,3,0,1] row_mask:0xf bank_mask:0xf
	v_mov_b32_e32 v90, v95
	s_waitcnt lgkmcnt(1)
	v_add_f32_e32 v34, v42, v50
	v_mul_f32_e32 v34, 0x3b800000, v34
	v_mov_b32_e32 v30, v82
	s_waitcnt lgkmcnt(0)
	v_add_f32_e32 v38, v38, v58
	s_nop 1
	v_mov_b32_dpp v42, v38 row_shl:4 row_mask:0xf bank_mask:0x5
	v_mov_b32_dpp v42, v38 row_shr:4 row_mask:0xf bank_mask:0xa
	v_mov_b32_e32 v31, v74
	v_pk_add_f32 v[104:105], v[104:105], v[34:35] op_sel_hi:[1,0] neg_lo:[0,1] neg_hi:[0,1]
	v_mov_b32_e32 v74, v83
	v_mov_b32_e32 v32, v66
	s_waitcnt lgkmcnt(0)
	v_add_f32_e32 v38, v38, v42
	ds_bpermute_b32 v42, v0, v38
	v_pk_add_f32 v[30:31], v[30:31], v[34:35] op_sel_hi:[1,0] neg_lo:[0,1] neg_hi:[0,1]
	v_pk_add_f32 v[32:33], v[32:33], v[34:35] op_sel_hi:[1,0] neg_lo:[0,1] neg_hi:[0,1]
	v_pk_add_f32 v[100:101], v[100:101], v[34:35] op_sel_hi:[1,0] neg_lo:[0,1] neg_hi:[0,1]
	v_pk_add_f32 v[102:103], v[102:103], v[34:35] op_sel_hi:[1,0] neg_lo:[0,1] neg_hi:[0,1]
	v_mov_b32_e32 v58, v67
	v_pk_mul_f32 v[106:107], v[32:33], v[32:33]
	s_waitcnt vmcnt(5)
	s_mov_b32 s100, 0x1000
	s_mov_b32 s101, 0
	v_lshl_add_u64 v[168:169], v[170:171], 0, s[100:101]
	global_load_dwordx4 v[172:175], v[170:171], off offset:2064
	global_load_dwordx4 v[176:179], v[170:171], off offset:2048
	global_load_dwordx4 v[180:183], v[168:169], off offset:16
	global_load_dwordx4 v[184:187], v[168:169], off
	global_load_dwordx4 v[188:191], v[168:169], off offset:2064
	global_load_dwordx4 v[192:195], v[168:169], off offset:2048
	v_and_b32_e32 v113, 0xffff0000, v18
	v_lshlrev_b32_e32 v112, 16, v18
	v_and_b32_e32 v115, 0xffff0000, v19
	v_lshlrev_b32_e32 v114, 16, v19
	v_mov_b32_e32 v18, v86
	v_mov_b32_e32 v19, v78
	v_pk_add_f32 v[116:117], v[18:19], v[34:35] op_sel_hi:[1,0] neg_lo:[0,1] neg_hi:[0,1]
	v_mov_b32_e32 v18, v70
	v_mov_b32_e32 v19, v62
	v_pk_add_f32 v[118:119], v[18:19], v[34:35] op_sel_hi:[1,0] neg_lo:[0,1] neg_hi:[0,1]
	v_mov_b32_e32 v18, v54
	v_mov_b32_e32 v19, v46
	v_pk_add_f32 v[120:121], v[18:19], v[34:35] op_sel_hi:[1,0] neg_lo:[0,1] neg_hi:[0,1]
	s_waitcnt lgkmcnt(0)
; DEVINL float bf2f(u16 h) { return __uint_as_float(((unsigned)h) << 16); }
; DEVINL void ret_out_phase(CParams& p, const Ctx& cx, int l, const GI& gi) {
;     ...
;     for (int j = 0; j < 4; ++j) {
;       float sm = 0.f;
; #pragma unroll
;       for (int et = 0; et < 16; ++et) sm += o[et][j];
; #pragma unroll
;       for (int x = 1; x < 16; x <<= 1) sm += shflx(sm, x, lane);
;       const float mu = sm * (1.f / 256.f);
;       float vs = 0.f;
; #pragma unroll
;       for (int et = 0; et < 16; ++et) { const float d = o[et][j] - mu; vs += d * d; }
; #pragma unroll
;       for (int x = 1; x < 16; x <<= 1) vs += shflx(vs, x, lane);
;       const float rsd = rsqrtf(vs * (1.f / 256.f) + 1e-5f);
;       const size_t ro = (size_t)(row0 + wave * 16 + fq * 4 + j) * DM + h * 256 + fr * 16;
;       const bf16x8 s0 = *(const bf16x8*)(p.sg + ro), s1 = *(const bf16x8*)(p.sg + ro + 8);
;       bf16x8 y0, y1;
; #pragma unroll
;       for (int et = 0; et < 8; ++et) {
;         y0[et] = (short)f2bf(bf2f((u16)s0[et]) * ((o[et][j] - mu) * rsd * gv[et]));
;         y1[et] = (short)f2bf(bf2f((u16)s1[et]) * ((o[et + 8][j] - mu) * rsd * gv[et + 8]));
;       }
;       *(bf16x8*)(p.y + ro) = y0; *(bf16x8*)(p.y + ro + 8) = y1;
	v_add_f32_e32 v18, v38, v42
	v_mul_f32_e32 v18, 0x3b800000, v18
	v_pk_add_f32 v[82:83], v[90:91], v[18:19] op_sel_hi:[1,0] neg_lo:[0,1] neg_hi:[0,1]
	v_mov_b32_e32 v78, v87
	v_mov_b32_e32 v86, v83
	v_mov_b32_e32 v87, v105
	v_pk_add_f32 v[78:79], v[78:79], v[18:19] op_sel_hi:[1,0] neg_lo:[0,1] neg_hi:[0,1]
	v_mov_b32_e32 v62, v71
	v_mov_b32_e32 v70, v82
	v_mov_b32_e32 v71, v104
	v_pk_mul_f32 v[86:87], v[86:87], v[86:87]
	v_pk_add_f32 v[62:63], v[62:63], v[18:19] op_sel_hi:[1,0] neg_lo:[0,1] neg_hi:[0,1]
	v_pk_fma_f32 v[70:71], v[70:71], v[70:71], v[86:87]
	v_mov_b32_e32 v86, v78
	v_mov_b32_e32 v87, v116
	v_mov_b32_e32 v90, v79
	v_mov_b32_e32 v91, v117
	v_pk_fma_f32 v[70:71], v[86:87], v[86:87], v[70:71]
	v_mov_b32_e32 v46, v55
	v_pk_fma_f32 v[70:71], v[90:91], v[90:91], v[70:71]
	v_mov_b32_e32 v86, v62
	v_mov_b32_e32 v87, v118
	v_pk_add_f32 v[46:47], v[46:47], v[18:19] op_sel_hi:[1,0] neg_lo:[0,1] neg_hi:[0,1]
	v_mov_b32_e32 v90, v63
	v_mov_b32_e32 v91, v119
	v_pk_fma_f32 v[70:71], v[86:87], v[86:87], v[70:71]
	v_mov_b32_e32 v86, v46
	v_pk_fma_f32 v[70:71], v[90:91], v[90:91], v[70:71]
	v_mov_b32_e32 v87, v120
	v_pk_add_f32 v[74:75], v[74:75], v[18:19] op_sel_hi:[1,0] neg_lo:[0,1] neg_hi:[0,1]
	v_mov_b32_e32 v42, v51
	v_mov_b32_e32 v34, v39
	v_mov_b32_e32 v90, v47
	v_mov_b32_e32 v91, v121
	v_pk_fma_f32 v[70:71], v[86:87], v[86:87], v[70:71]
	v_pk_add_f32 v[58:59], v[58:59], v[18:19] op_sel_hi:[1,0] neg_lo:[0,1] neg_hi:[0,1]
	v_pk_add_f32 v[42:43], v[42:43], v[18:19] op_sel_hi:[1,0] neg_lo:[0,1] neg_hi:[0,1]
	v_pk_add_f32 v[34:35], v[34:35], v[18:19] op_sel_hi:[1,0] neg_lo:[0,1] neg_hi:[0,1]
	v_mov_b32_e32 v18, v74
	v_mov_b32_e32 v19, v30
	v_pk_fma_f32 v[70:71], v[90:91], v[90:91], v[70:71]
	v_pk_mul_f32 v[66:67], v[58:59], v[58:59]
	v_mov_b32_e32 v54, v75
	v_mov_b32_e32 v55, v31
	v_pk_fma_f32 v[18:19], v[18:19], v[18:19], v[70:71]
	v_pk_mul_f32 v[108:109], v[100:101], v[100:101]
	v_pk_fma_f32 v[18:19], v[54:55], v[54:55], v[18:19]
	v_mov_b32_e32 v54, v66
	v_mov_b32_e32 v55, v106
	v_pk_mul_f32 v[50:51], v[42:43], v[42:43]
	v_pk_add_f32 v[18:19], v[54:55], v[18:19]
	v_mov_b32_e32 v106, v67
	v_pk_add_f32 v[18:19], v[106:107], v[18:19]
	v_mov_b32_e32 v54, v50
	v_mov_b32_e32 v55, v108
	v_pk_mul_f32 v[110:111], v[102:103], v[102:103]
	v_pk_mul_f32 v[38:39], v[34:35], v[34:35]
	v_pk_add_f32 v[18:19], v[54:55], v[18:19]
	v_mov_b32_e32 v108, v51
	v_pk_add_f32 v[18:19], v[108:109], v[18:19]
	v_mov_b32_e32 v50, v38
	v_mov_b32_e32 v51, v110
	v_pk_add_f32 v[18:19], v[50:51], v[18:19]
	v_mov_b32_e32 v110, v39
	v_pk_add_f32 v[18:19], v[110:111], v[18:19]
	ds_bpermute_b32 v39, v99, v19
	ds_bpermute_b32 v38, v99, v18
	s_waitcnt vmcnt(0)
	v_and_b32_e32 v55, 0xffff0000, v26
	v_lshlrev_b32_e32 v54, 16, v26
	v_and_b32_e32 v67, 0xffff0000, v27
	v_lshlrev_b32_e32 v66, 16, v27
	s_waitcnt lgkmcnt(0)
	v_pk_add_f32 v[18:19], v[18:19], v[38:39]
	ds_bpermute_b32 v39, v94, v19
	ds_bpermute_b32 v38, v94, v18
	v_and_b32_e32 v51, 0xffff0000, v20
	v_lshlrev_b32_e32 v50, 16, v20
	v_lshl_add_u64 v[90:91], s[14:15], 0, v[24:25]
	v_or_b32_e32 v24, 1, v22
	s_waitcnt lgkmcnt(0)
	v_pk_add_f32 v[18:19], v[18:19], v[38:39]
	ds_bpermute_b32 v27, v23, v19
	ds_bpermute_b32 v26, v23, v18
	v_and_b32_e32 v39, 0xffff0000, v21
	v_lshlrev_b32_e32 v38, 16, v21
	v_ashrrev_i32_e32 v25, 31, v24
	s_mov_b32 s16, 0x3727c5ac
	s_waitcnt lgkmcnt(0)
	v_pk_add_f32 v[18:19], v[18:19], v[26:27]
	ds_bpermute_b32 v21, v0, v19
	ds_bpermute_b32 v20, v0, v18
	v_lshlrev_b64 v[26:27], 10, v[24:25]
	v_mov_b64_e32 v[24:25], s[16:17]
	v_or3_b32 v26, v26, v98, s96
	v_lshlrev_b64 v[108:109], 1, v[26:27]
	s_waitcnt lgkmcnt(0)
	v_pk_add_f32 v[18:19], v[18:19], v[20:21]
	v_and_b32_e32 v71, 0xffff0000, v28
	v_pk_fma_f32 v[106:107], v[18:19], s[38:39], v[24:25] op_sel_hi:[1,0,0]
	v_lshlrev_b32_e32 v70, 16, v28
	v_mul_f32_e32 v18, 0x4b800000, v107
	v_cmp_gt_f32_e32 vcc, s35, v107
	v_and_b32_e32 v87, 0xffff0000, v29
	v_lshlrev_b32_e32 v86, 16, v29
	v_cndmask_b32_e32 v18, v107, v18, vcc
	v_rsq_f32_e32 v18, v18
	v_lshl_add_u64 v[110:111], s[6:7], 0, v[108:109]
	s_add_i32 s26, s26, s33
	s_cmp_ge_i32 s26, s22
	v_mul_f32_e32 v19, 0x45800000, v18
	v_cndmask_b32_e32 v122, v18, v19, vcc
	v_pk_mul_f32 v[20:21], v[30:31], v[122:123] op_sel_hi:[1,0]
	v_pk_mul_f32 v[18:19], v[104:105], v[122:123] op_sel_hi:[1,0]
	v_pk_mul_f32 v[20:21], v[6:7], v[20:21]
	v_pk_mul_f32 v[18:19], v[14:15], v[18:19]
	v_pk_mul_f32 v[20:21], v[20:21], v[112:113]
	v_pk_mul_f32 v[18:19], v[18:19], v[54:55]
	v_cvt_pk_bf16_f32 v26, v20, v21
	v_pk_mul_f32 v[20:21], v[116:117], v[122:123] op_sel_hi:[1,0]
	v_cvt_pk_bf16_f32 v18, v18, v19
	v_pk_mul_f32 v[20:21], v[16:17], v[20:21]
	v_pk_mul_f32 v[30:31], v[120:121], v[122:123] op_sel_hi:[1,0]
	v_pk_mul_f32 v[20:21], v[20:21], v[66:67]
	v_pk_mul_f32 v[30:31], v[12:13], v[30:31]
	v_cvt_pk_bf16_f32 v19, v20, v21
	v_pk_mul_f32 v[20:21], v[32:33], v[122:123] op_sel_hi:[1,0]
	v_pk_mul_f32 v[30:31], v[30:31], v[86:87]
	v_pk_mul_f32 v[20:21], v[8:9], v[20:21]
	v_pk_mul_f32 v[28:29], v[100:101], v[122:123] op_sel_hi:[1,0]
	v_pk_mul_f32 v[20:21], v[20:21], v[114:115]
	v_pk_mul_f32 v[28:29], v[2:3], v[28:29]
	v_cvt_pk_bf16_f32 v27, v20, v21
	v_pk_mul_f32 v[20:21], v[118:119], v[122:123] op_sel_hi:[1,0]
	v_pk_mul_f32 v[28:29], v[28:29], v[50:51]
	v_pk_mul_f32 v[20:21], v[10:11], v[20:21]
	v_cvt_pk_bf16_f32 v28, v28, v29
	v_pk_mul_f32 v[20:21], v[20:21], v[70:71]
	v_cmp_gt_f32_e32 vcc, s35, v106
	v_cvt_pk_bf16_f32 v20, v20, v21
	v_cvt_pk_bf16_f32 v21, v30, v31
	v_pk_mul_f32 v[30:31], v[102:103], v[122:123] op_sel_hi:[1,0]
	s_nop 0
	v_pk_mul_f32 v[30:31], v[4:5], v[30:31]
	s_nop 0
	v_pk_mul_f32 v[30:31], v[30:31], v[38:39]
; DEVINL float bf2f(u16 h) { return __uint_as_float(((unsigned)h) << 16); }
; DEVINL void ret_out_phase(CParams& p, const Ctx& cx, int l, const GI& gi) {
;     ...
;     for (int j = 0; j < 4; ++j) {
;       float sm = 0.f;
; #pragma unroll
;       for (int et = 0; et < 16; ++et) sm += o[et][j];
; #pragma unroll
;       for (int x = 1; x < 16; x <<= 1) sm += shflx(sm, x, lane);
;       const float mu = sm * (1.f / 256.f);
;       float vs = 0.f;
; #pragma unroll
;       for (int et = 0; et < 16; ++et) { const float d = o[et][j] - mu; vs += d * d; }
; #pragma unroll
;       for (int x = 1; x < 16; x <<= 1) vs += shflx(vs, x, lane);
;       const float rsd = rsqrtf(vs * (1.f / 256.f) + 1e-5f);
;       const size_t ro = (size_t)(row0 + wave * 16 + fq * 4 + j) * DM + h * 256 + fr * 16;
;       const bf16x8 s0 = *(const bf16x8*)(p.sg + ro), s1 = *(const bf16x8*)(p.sg + ro + 8);
;       bf16x8 y0, y1;
; #pragma unroll
;       for (int et = 0; et < 8; ++et) {
;         y0[et] = (short)f2bf(bf2f((u16)s0[et]) * ((o[et][j] - mu) * rsd * gv[et]));
;         y1[et] = (short)f2bf(bf2f((u16)s1[et]) * ((o[et + 8][j] - mu) * rsd * gv[et + 8]));
;       }
;       *(bf16x8*)(p.y + ro) = y0; *(bf16x8*)(p.y + ro + 8) = y1;
	s_nop 0
	v_cvt_pk_bf16_f32 v29, v30, v31
	global_store_dwordx4 v[90:91], v[18:21], off
	global_store_dwordx4 v[90:91], v[26:29], off offset:16
	s_nop 1
	v_mov_b32_e32 v18, v172
	v_mov_b32_e32 v19, v173
	v_mov_b32_e32 v20, v174
	v_mov_b32_e32 v21, v175
	v_mov_b32_e32 v26, v176
	v_mov_b32_e32 v27, v177
	v_mov_b32_e32 v28, v178
	v_mov_b32_e32 v29, v179
	v_and_b32_e32 v39, 0xffff0000, v20
	v_lshlrev_b32_e32 v38, 16, v20
	v_mul_f32_e32 v20, 0x4b800000, v106
	v_cndmask_b32_e32 v20, v106, v20, vcc
	v_rsq_f32_e32 v20, v20
	v_and_b32_e32 v67, 0xffff0000, v21
	v_lshlrev_b32_e32 v66, 16, v21
	v_and_b32_e32 v31, 0xffff0000, v18
	v_mul_f32_e32 v21, 0x45800000, v20
	v_cndmask_b32_e32 v86, v20, v21, vcc
	v_pk_mul_f32 v[20:21], v[82:83], v[86:87] op_sel_hi:[1,0]
	v_lshlrev_b32_e32 v30, 16, v18
	v_and_b32_e32 v33, 0xffff0000, v19
	v_lshlrev_b32_e32 v32, 16, v19
	v_and_b32_e32 v19, 0xffff0000, v26
	v_lshlrev_b32_e32 v18, 16, v26
	v_pk_mul_f32 v[20:21], v[14:15], v[20:21]
	v_and_b32_e32 v51, 0xffff0000, v27
	v_pk_mul_f32 v[18:19], v[20:21], v[18:19]
	v_pk_mul_f32 v[20:21], v[74:75], v[86:87] op_sel_hi:[1,0]
	v_lshlrev_b32_e32 v50, 16, v27
	v_pk_mul_f32 v[20:21], v[6:7], v[20:21]
	v_cvt_pk_bf16_f32 v18, v18, v19
	v_pk_mul_f32 v[20:21], v[20:21], v[30:31]
	v_pk_mul_f32 v[30:31], v[46:47], v[86:87] op_sel_hi:[1,0]
	v_cvt_pk_bf16_f32 v26, v20, v21
	v_pk_mul_f32 v[20:21], v[78:79], v[86:87] op_sel_hi:[1,0]
	v_and_b32_e32 v55, 0xffff0000, v28
	v_pk_mul_f32 v[20:21], v[16:17], v[20:21]
	v_lshlrev_b32_e32 v54, 16, v28
	v_pk_mul_f32 v[20:21], v[20:21], v[50:51]
	v_and_b32_e32 v71, 0xffff0000, v29
	v_cvt_pk_bf16_f32 v19, v20, v21
	v_pk_mul_f32 v[20:21], v[58:59], v[86:87] op_sel_hi:[1,0]
	v_lshlrev_b32_e32 v70, 16, v29
	v_pk_mul_f32 v[20:21], v[8:9], v[20:21]
	v_pk_mul_f32 v[30:31], v[12:13], v[30:31]
	v_pk_mul_f32 v[20:21], v[20:21], v[32:33]
	v_pk_mul_f32 v[30:31], v[30:31], v[70:71]
	v_cvt_pk_bf16_f32 v27, v20, v21
	v_pk_mul_f32 v[20:21], v[62:63], v[86:87] op_sel_hi:[1,0]
	v_pk_mul_f32 v[28:29], v[42:43], v[86:87] op_sel_hi:[1,0]
	v_pk_mul_f32 v[20:21], v[10:11], v[20:21]
	v_pk_mul_f32 v[28:29], v[2:3], v[28:29]
	v_pk_mul_f32 v[20:21], v[20:21], v[54:55]
	v_pk_mul_f32 v[28:29], v[28:29], v[38:39]
	v_cvt_pk_bf16_f32 v20, v20, v21
	v_cvt_pk_bf16_f32 v21, v30, v31
	v_pk_mul_f32 v[30:31], v[34:35], v[86:87] op_sel_hi:[1,0]
	v_cvt_pk_bf16_f32 v28, v28, v29
	v_pk_mul_f32 v[30:31], v[4:5], v[30:31]
	v_mov_b32_e32 v32, v68
	v_pk_mul_f32 v[30:31], v[30:31], v[66:67]
	v_mov_b32_e32 v33, v60
	v_cvt_pk_bf16_f32 v29, v30, v31
	v_lshl_add_u64 v[30:31], s[14:15], 0, v[108:109]
	global_store_dwordx4 v[30:31], v[18:21], off
	global_store_dwordx4 v[30:31], v[26:29], off offset:16
	v_add_f32_e32 v30, 0, v96
	v_or_b32_e32 v18, 2, v22
	v_ashrrev_i32_e32 v19, 31, v18
	v_lshlrev_b64 v[18:19], 10, v[18:19]
	v_or3_b32 v18, v18, v98, s96
	v_lshlrev_b64 v[26:27], 1, v[18:19]
	v_lshl_add_u64 v[28:29], s[6:7], 0, v[26:27]
	s_nop 1
	v_mov_b32_e32 v18, v180
	v_mov_b32_e32 v19, v181
	v_mov_b32_e32 v20, v182
	v_mov_b32_e32 v21, v183
	v_mov_b32_e32 v100, v184
	v_mov_b32_e32 v101, v185
	v_mov_b32_e32 v102, v186
	v_mov_b32_e32 v103, v187
	v_add_f32_e32 v30, v30, v92
	v_add_f32_e32 v30, v30, v88
	v_add_f32_e32 v30, v30, v80
	v_add_f32_e32 v30, v30, v72
	v_add_f32_e32 v30, v30, v64
	v_add_f32_e32 v30, v30, v56
	v_add_f32_e32 v30, v30, v48
	v_add_f32_e32 v30, v30, v84
	v_add_f32_e32 v30, v30, v76
	v_add_f32_e32 v30, v30, v68
	v_add_f32_e32 v30, v30, v60
	v_add_f32_e32 v30, v30, v52
	v_add_f32_e32 v30, v30, v44
	v_add_f32_e32 v30, v30, v40
	v_add_f32_e32 v30, v30, v36
	s_nop 1
	v_mov_b32_dpp v31, v30 quad_perm:[1,0,3,2] row_mask:0xf bank_mask:0xf
	v_mov_b32_e32 v29, v76
	v_mov_b32_e32 v50, v40
	v_mov_b32_e32 v51, v36
	v_mov_b32_e32 v58, v96
	s_waitcnt lgkmcnt(0)
	v_add_f32_e32 v30, v30, v31
	s_nop 1
	v_mov_b32_dpp v31, v30 quad_perm:[2,3,0,1] row_mask:0xf bank_mask:0xf
	v_mov_b32_e32 v59, v92
	v_mov_b32_e32 v62, v88
	v_mov_b32_e32 v63, v80
	v_mov_b32_e32 v66, v72
	s_waitcnt lgkmcnt(0)
	v_add_f32_e32 v30, v30, v31
	s_nop 1
	v_mov_b32_dpp v31, v30 row_shl:4 row_mask:0xf bank_mask:0x5
	v_mov_b32_dpp v31, v30 row_shr:4 row_mask:0xf bank_mask:0xa
	v_mov_b32_e32 v67, v64
	v_mov_b32_e32 v70, v56
	v_mov_b32_e32 v71, v48
	v_mov_b32_e32 v76, v85
	s_waitcnt lgkmcnt(0)
	v_add_f32_e32 v30, v30, v31
	ds_bpermute_b32 v31, v0, v30
	v_mov_b32_e32 v92, v97
	v_mov_b32_e32 v80, v89
	v_mov_b32_e32 v64, v73
	v_mov_b32_e32 v60, v69
	s_waitcnt lgkmcnt(0)
	v_add_f32_e32 v28, v30, v31
	v_mul_f32_e32 v38, 0x3b800000, v28
	v_mov_b32_e32 v28, v84
	v_pk_add_f32 v[30:31], v[28:29], v[38:39] op_sel_hi:[1,0] neg_lo:[0,1] neg_hi:[0,1]
	v_pk_add_f32 v[32:33], v[32:33], v[38:39] op_sel_hi:[1,0] neg_lo:[0,1] neg_hi:[0,1]
	v_mov_b32_e32 v48, v57
	v_pk_mul_f32 v[42:43], v[32:33], v[32:33]
	v_or_b32_e32 v22, 3, v22
	v_and_b32_e32 v29, 0xffff0000, v18
	v_lshlrev_b32_e32 v28, 16, v18
	v_and_b32_e32 v35, 0xffff0000, v19
	v_lshlrev_b32_e32 v34, 16, v19
	v_mov_b32_e32 v18, v52
	v_mov_b32_e32 v19, v44
	v_pk_add_f32 v[18:19], v[18:19], v[38:39] op_sel_hi:[1,0] neg_lo:[0,1] neg_hi:[0,1]
	v_add_f32_e32 v39, 0, v97
	v_add_f32_e32 v39, v39, v93
	v_add_f32_e32 v39, v39, v89
	v_add_f32_e32 v39, v39, v81
	v_add_f32_e32 v39, v39, v73
	v_add_f32_e32 v39, v39, v65
	v_add_f32_e32 v39, v39, v57
	v_add_f32_e32 v39, v39, v49
	v_add_f32_e32 v39, v39, v85
	v_add_f32_e32 v39, v39, v77
	v_add_f32_e32 v39, v39, v69
	v_add_f32_e32 v39, v39, v61
	v_add_f32_e32 v39, v39, v53
	v_add_f32_e32 v39, v39, v45
	v_add_f32_e32 v39, v39, v41
	v_add_f32_e32 v39, v39, v37
	ds_bpermute_b32 v44, v99, v39
	v_pk_add_f32 v[50:51], v[50:51], v[38:39] op_sel_hi:[1,0] neg_lo:[0,1] neg_hi:[0,1]
	v_mov_b32_e32 v57, v31
	v_pk_mul_f32 v[46:47], v[18:19], v[18:19]
	v_pk_mul_f32 v[54:55], v[50:51], v[50:51]
	s_waitcnt lgkmcnt(0)
; DEVINL float bf2f(u16 h) { return __uint_as_float(((unsigned)h) << 16); }
; DEVINL void ret_out_phase(CParams& p, const Ctx& cx, int l, const GI& gi) {
;     ...
;     for (int j = 0; j < 4; ++j) {
;       float sm = 0.f;
; #pragma unroll
;       for (int et = 0; et < 16; ++et) sm += o[et][j];
; #pragma unroll
;       for (int x = 1; x < 16; x <<= 1) sm += shflx(sm, x, lane);
;       const float mu = sm * (1.f / 256.f);
;       float vs = 0.f;
; #pragma unroll
;       for (int et = 0; et < 16; ++et) { const float d = o[et][j] - mu; vs += d * d; }
; #pragma unroll
;       for (int x = 1; x < 16; x <<= 1) vs += shflx(vs, x, lane);
;       const float rsd = rsqrtf(vs * (1.f / 256.f) + 1e-5f);
;       const size_t ro = (size_t)(row0 + wave * 16 + fq * 4 + j) * DM + h * 256 + fr * 16;
;       const bf16x8 s0 = *(const bf16x8*)(p.sg + ro), s1 = *(const bf16x8*)(p.sg + ro + 8);
;       bf16x8 y0, y1;
; #pragma unroll
;       for (int et = 0; et < 8; ++et) {
;         y0[et] = (short)f2bf(bf2f((u16)s0[et]) * ((o[et][j] - mu) * rsd * gv[et]));
;         y1[et] = (short)f2bf(bf2f((u16)s1[et]) * ((o[et + 8][j] - mu) * rsd * gv[et + 8]));
;       }
;       *(bf16x8*)(p.y + ro) = y0; *(bf16x8*)(p.y + ro + 8) = y1;
	v_add_f32_e32 v36, v39, v44
	s_nop 1
	v_mov_b32_dpp v39, v36 quad_perm:[2,3,0,1] row_mask:0xf bank_mask:0xf
	v_mov_b32_e32 v44, v53
	s_waitcnt lgkmcnt(0)
	v_add_f32_e32 v36, v36, v39
	v_pk_add_f32 v[58:59], v[58:59], v[38:39] op_sel_hi:[1,0] neg_lo:[0,1] neg_hi:[0,1]
	s_nop 1
	v_mov_b32_dpp v39, v36 row_shl:4 row_mask:0xf bank_mask:0x5
	v_mov_b32_dpp v39, v36 row_shr:4 row_mask:0xf bank_mask:0xa
	v_mov_b32_e32 v73, v58
	s_waitcnt lgkmcnt(0)
	v_add_f32_e32 v36, v36, v39
	s_nop 1
	v_mov_b32_dpp v40, v36 row_ror:8 row_mask:0xf bank_mask:0xf
	v_pk_add_f32 v[62:63], v[62:63], v[38:39] op_sel_hi:[1,0] neg_lo:[0,1] neg_hi:[0,1]
	v_pk_add_f32 v[66:67], v[66:67], v[38:39] op_sel_hi:[1,0] neg_lo:[0,1] neg_hi:[0,1]
	v_pk_add_f32 v[38:39], v[70:71], v[38:39] op_sel_hi:[1,0] neg_lo:[0,1] neg_hi:[0,1]
	v_mov_b32_e32 v83, v63
	s_waitcnt lgkmcnt(0)
	v_add_f32_e32 v36, v36, v40
	v_mul_f32_e32 v40, 0x3b800000, v36
	v_pk_add_f32 v[70:71], v[76:77], v[40:41] op_sel_hi:[1,0] neg_lo:[0,1] neg_hi:[0,1]
	v_pk_add_f32 v[76:77], v[92:93], v[40:41] op_sel_hi:[1,0] neg_lo:[0,1] neg_hi:[0,1]
	v_pk_add_f32 v[78:79], v[80:81], v[40:41] op_sel_hi:[1,0] neg_lo:[0,1] neg_hi:[0,1]
	v_mov_b32_e32 v80, v77
	v_mov_b32_e32 v81, v59
	v_mov_b32_e32 v72, v76
	v_pk_mul_f32 v[80:81], v[80:81], v[80:81]
	v_pk_add_f32 v[64:65], v[64:65], v[40:41] op_sel_hi:[1,0] neg_lo:[0,1] neg_hi:[0,1]
	v_pk_fma_f32 v[72:73], v[72:73], v[72:73], v[80:81]
	v_mov_b32_e32 v80, v78
	v_mov_b32_e32 v81, v62
	v_mov_b32_e32 v82, v79
	v_pk_fma_f32 v[72:73], v[80:81], v[80:81], v[72:73]
	v_mov_b32_e32 v36, v41
	v_pk_fma_f32 v[72:73], v[82:83], v[82:83], v[72:73]
	v_mov_b32_e32 v80, v64
	v_mov_b32_e32 v81, v66
	v_pk_add_f32 v[60:61], v[60:61], v[40:41] op_sel_hi:[1,0] neg_lo:[0,1] neg_hi:[0,1]
	v_pk_add_f32 v[44:45], v[44:45], v[40:41] op_sel_hi:[1,0] neg_lo:[0,1] neg_hi:[0,1]
	v_pk_add_f32 v[36:37], v[36:37], v[40:41] op_sel_hi:[1,0] neg_lo:[0,1] neg_hi:[0,1]
	v_pk_add_f32 v[40:41], v[48:49], v[40:41] op_sel_hi:[1,0] neg_lo:[0,1] neg_hi:[0,1]
	v_mov_b32_e32 v82, v65
	v_mov_b32_e32 v83, v67
	v_pk_fma_f32 v[72:73], v[80:81], v[80:81], v[72:73]
	v_mov_b32_e32 v80, v40
	v_pk_fma_f32 v[72:73], v[82:83], v[82:83], v[72:73]
	v_mov_b32_e32 v81, v38
	v_mov_b32_e32 v82, v41
	v_mov_b32_e32 v83, v39
	v_pk_fma_f32 v[72:73], v[80:81], v[80:81], v[72:73]
	v_mov_b32_e32 v48, v70
	v_mov_b32_e32 v49, v30
	v_pk_fma_f32 v[72:73], v[82:83], v[82:83], v[72:73]
	v_pk_mul_f32 v[68:69], v[60:61], v[60:61]
	v_mov_b32_e32 v56, v71
	v_pk_fma_f32 v[48:49], v[48:49], v[48:49], v[72:73]
	v_pk_mul_f32 v[52:53], v[44:45], v[44:45]
	v_pk_fma_f32 v[48:49], v[56:57], v[56:57], v[48:49]
	v_mov_b32_e32 v56, v68
	v_mov_b32_e32 v57, v42
	v_pk_add_f32 v[48:49], v[56:57], v[48:49]
	v_mov_b32_e32 v42, v69
	v_pk_add_f32 v[42:43], v[42:43], v[48:49]
	v_mov_b32_e32 v48, v52
	v_mov_b32_e32 v49, v46
	v_pk_mul_f32 v[74:75], v[36:37], v[36:37]
	v_pk_add_f32 v[42:43], v[48:49], v[42:43]
	v_mov_b32_e32 v46, v53
	v_pk_add_f32 v[42:43], v[46:47], v[42:43]
	v_mov_b32_e32 v46, v74
	v_mov_b32_e32 v47, v54
	v_pk_add_f32 v[42:43], v[46:47], v[42:43]
	v_mov_b32_e32 v54, v75
	v_pk_add_f32 v[42:43], v[54:55], v[42:43]
	ds_bpermute_b32 v47, v99, v43
	ds_bpermute_b32 v46, v99, v42
	v_and_b32_e32 v49, 0xffff0000, v20
	v_lshlrev_b32_e32 v48, 16, v20
	v_and_b32_e32 v69, 0xffff0000, v21
	v_lshlrev_b32_e32 v68, 16, v21
	s_waitcnt lgkmcnt(0)
	v_pk_add_f32 v[42:43], v[42:43], v[46:47]
	ds_bpermute_b32 v47, v94, v43
	ds_bpermute_b32 v46, v94, v42
	v_and_b32_e32 v53, 0xffff0000, v100
	v_lshlrev_b32_e32 v52, 16, v100
	v_and_b32_e32 v55, 0xffff0000, v101
	v_lshlrev_b32_e32 v54, 16, v101
	s_waitcnt lgkmcnt(0)
	v_pk_add_f32 v[42:43], v[42:43], v[46:47]
	ds_bpermute_b32 v47, v23, v43
	ds_bpermute_b32 v46, v23, v42
	v_ashrrev_i32_e32 v23, 31, v22
	v_lshlrev_b64 v[22:23], 10, v[22:23]
	v_or3_b32 v22, v22, v98, s96
	v_lshlrev_b64 v[74:75], 1, v[22:23]
	s_waitcnt lgkmcnt(0)
	v_pk_add_f32 v[20:21], v[42:43], v[46:47]
	ds_bpermute_b32 v43, v0, v21
	ds_bpermute_b32 v42, v0, v20
	v_lshl_add_u64 v[46:47], s[14:15], 0, v[26:27]
	v_and_b32_e32 v57, 0xffff0000, v102
	v_lshlrev_b32_e32 v56, 16, v102
	v_and_b32_e32 v73, 0xffff0000, v103
	s_waitcnt lgkmcnt(0)
; DEVINL float bf2f(u16 h) { return __uint_as_float(((unsigned)h) << 16); }
; DEVINL void ret_out_phase(CParams& p, const Ctx& cx, int l, const GI& gi) {
;     ...
;       const float rsd = rsqrtf(vs * (1.f / 256.f) + 1e-5f);
;       const size_t ro = (size_t)(row0 + wave * 16 + fq * 4 + j) * DM + h * 256 + fr * 16;
;       const bf16x8 s0 = *(const bf16x8*)(p.sg + ro), s1 = *(const bf16x8*)(p.sg + ro + 8);
;       bf16x8 y0, y1;
; #pragma unroll
;       for (int et = 0; et < 8; ++et) {
;         y0[et] = (short)f2bf(bf2f((u16)s0[et]) * ((o[et][j] - mu) * rsd * gv[et]));
;         y1[et] = (short)f2bf(bf2f((u16)s1[et]) * ((o[et + 8][j] - mu) * rsd * gv[et + 8]));
;       }
;       *(bf16x8*)(p.y + ro) = y0; *(bf16x8*)(p.y + ro + 8) = y1;
	v_pk_add_f32 v[20:21], v[20:21], v[42:43]
	v_lshlrev_b32_e32 v72, 16, v103
	v_pk_fma_f32 v[42:43], v[20:21], s[38:39], v[24:25] op_sel_hi:[1,0,0]
	v_lshl_add_u64 v[80:81], s[6:7], 0, v[74:75]
	v_mul_f32_e32 v0, 0x4b800000, v43
	v_cmp_gt_f32_e32 vcc, s35, v43
	s_nop 1
	v_cndmask_b32_e32 v0, v43, v0, vcc
	v_rsq_f32_e32 v0, v0
	s_nop 0
	v_mul_f32_e32 v20, 0x45800000, v0
	v_cndmask_b32_e32 v0, v0, v20, vcc
	v_pk_mul_f32 v[22:23], v[30:31], v[0:1] op_sel_hi:[1,0]
	v_pk_mul_f32 v[20:21], v[58:59], v[0:1] op_sel_hi:[1,0]
	v_pk_mul_f32 v[22:23], v[6:7], v[22:23]
	v_pk_mul_f32 v[20:21], v[14:15], v[20:21]
	v_pk_mul_f32 v[22:23], v[22:23], v[28:29]
	v_pk_mul_f32 v[20:21], v[20:21], v[52:53]
	v_cvt_pk_bf16_f32 v24, v22, v23
	v_pk_mul_f32 v[22:23], v[62:63], v[0:1] op_sel_hi:[1,0]
	v_cvt_pk_bf16_f32 v20, v20, v21
	v_pk_mul_f32 v[22:23], v[16:17], v[22:23]
	v_pk_mul_f32 v[18:19], v[18:19], v[0:1] op_sel_hi:[1,0]
	v_pk_mul_f32 v[22:23], v[22:23], v[54:55]
	v_pk_mul_f32 v[18:19], v[2:3], v[18:19]
	v_cvt_pk_bf16_f32 v21, v22, v23
	v_pk_mul_f32 v[22:23], v[32:33], v[0:1] op_sel_hi:[1,0]
	v_pk_mul_f32 v[18:19], v[18:19], v[48:49]
	v_pk_mul_f32 v[22:23], v[8:9], v[22:23]
	v_cvt_pk_bf16_f32 v26, v18, v19
	v_pk_mul_f32 v[22:23], v[22:23], v[34:35]
	v_pk_mul_f32 v[18:19], v[38:39], v[0:1] op_sel_hi:[1,0]
	v_cvt_pk_bf16_f32 v25, v22, v23
	v_pk_mul_f32 v[22:23], v[66:67], v[0:1] op_sel_hi:[1,0]
	v_pk_mul_f32 v[18:19], v[12:13], v[18:19]
	v_pk_mul_f32 v[22:23], v[10:11], v[22:23]
	v_pk_mul_f32 v[18:19], v[18:19], v[72:73]
	v_pk_mul_f32 v[22:23], v[22:23], v[56:57]
	v_cmp_gt_f32_e32 vcc, s35, v42
	v_cvt_pk_bf16_f32 v22, v22, v23
	v_cvt_pk_bf16_f32 v23, v18, v19
	v_pk_mul_f32 v[18:19], v[50:51], v[0:1] op_sel_hi:[1,0]
	v_mul_f32_e32 v0, 0x4b800000, v42
	v_pk_mul_f32 v[18:19], v[4:5], v[18:19]
	v_cndmask_b32_e32 v0, v42, v0, vcc
	v_pk_mul_f32 v[18:19], v[18:19], v[68:69]
	v_rsq_f32_e32 v0, v0
	v_cvt_pk_bf16_f32 v27, v18, v19
	global_store_dwordx4 v[46:47], v[20:23], off
	global_store_dwordx4 v[46:47], v[24:27], off offset:16
	s_nop 1
	v_mov_b32_e32 v18, v188
	v_mov_b32_e32 v19, v189
	v_mov_b32_e32 v20, v190
	v_mov_b32_e32 v21, v191
	v_mov_b32_e32 v22, v192
	v_mov_b32_e32 v23, v193
	v_mov_b32_e32 v24, v194
	v_mov_b32_e32 v25, v195
	v_and_b32_e32 v27, 0xffff0000, v18
	v_and_b32_e32 v31, 0xffff0000, v22
	v_lshlrev_b32_e32 v30, 16, v22
	v_and_b32_e32 v33, 0xffff0000, v23
	v_lshlrev_b32_e32 v32, 16, v23
	v_and_b32_e32 v23, 0xffff0000, v24
	v_lshlrev_b32_e32 v22, 16, v24
	v_mul_f32_e32 v24, 0x45800000, v0
	v_cndmask_b32_e32 v0, v0, v24, vcc
	v_lshlrev_b32_e32 v26, 16, v18
	v_and_b32_e32 v29, 0xffff0000, v19
	v_lshlrev_b32_e32 v28, 16, v19
	v_and_b32_e32 v19, 0xffff0000, v20
	v_lshlrev_b32_e32 v18, 16, v20
	v_and_b32_e32 v35, 0xffff0000, v21
	v_lshlrev_b32_e32 v34, 16, v21
	v_and_b32_e32 v21, 0xffff0000, v25
	v_lshlrev_b32_e32 v20, 16, v25
	v_pk_mul_f32 v[24:25], v[76:77], v[0:1] op_sel_hi:[1,0]
	s_nop 0
	v_pk_mul_f32 v[14:15], v[14:15], v[24:25]
	v_pk_mul_f32 v[24:25], v[70:71], v[0:1] op_sel_hi:[1,0]
	v_pk_mul_f32 v[14:15], v[14:15], v[30:31]
	v_pk_mul_f32 v[6:7], v[6:7], v[24:25]
	v_pk_mul_f32 v[24:25], v[78:79], v[0:1] op_sel_hi:[1,0]
	v_cvt_pk_bf16_f32 v14, v14, v15
	v_pk_mul_f32 v[16:17], v[16:17], v[24:25]
	v_pk_mul_f32 v[6:7], v[6:7], v[26:27]
	v_pk_mul_f32 v[16:17], v[16:17], v[32:33]
	v_cvt_pk_bf16_f32 v6, v6, v7
	v_cvt_pk_bf16_f32 v15, v16, v17
	v_pk_mul_f32 v[16:17], v[60:61], v[0:1] op_sel_hi:[1,0]
	s_nop 0
	v_pk_mul_f32 v[8:9], v[8:9], v[16:17]
	s_nop 0
	v_pk_mul_f32 v[8:9], v[8:9], v[28:29]
	s_nop 0
	v_cvt_pk_bf16_f32 v7, v8, v9
	v_pk_mul_f32 v[8:9], v[64:65], v[0:1] op_sel_hi:[1,0]
	s_nop 0
	v_pk_mul_f32 v[8:9], v[10:11], v[8:9]
	s_nop 0
	v_pk_mul_f32 v[8:9], v[8:9], v[22:23]
	s_nop 0
	v_cvt_pk_bf16_f32 v16, v8, v9
	v_pk_mul_f32 v[8:9], v[44:45], v[0:1] op_sel_hi:[1,0]
	s_nop 0
	v_pk_mul_f32 v[2:3], v[2:3], v[8:9]
	s_nop 0
	v_pk_mul_f32 v[2:3], v[2:3], v[18:19]
	s_nop 0
	v_cvt_pk_bf16_f32 v8, v2, v3
	v_pk_mul_f32 v[2:3], v[40:41], v[0:1] op_sel_hi:[1,0]
	s_nop 0
	v_pk_mul_f32 v[2:3], v[12:13], v[2:3]
	s_nop 0
	v_pk_mul_f32 v[2:3], v[2:3], v[20:21]
	s_nop 0
	v_cvt_pk_bf16_f32 v17, v2, v3
	v_pk_mul_f32 v[2:3], v[36:37], v[0:1] op_sel_hi:[1,0]
	s_nop 0
	v_pk_mul_f32 v[2:3], v[4:5], v[2:3]
	s_nop 0
	v_pk_mul_f32 v[2:3], v[2:3], v[34:35]
	s_nop 0
	v_cvt_pk_bf16_f32 v9, v2, v3
	v_lshl_add_u64 v[2:3], s[14:15], 0, v[74:75]
	global_store_dwordx4 v[2:3], v[14:17], off
	global_store_dwordx4 v[2:3], v[6:9], off offset:16
	s_cbranch_scc1 .LBB0_275

; DEVINL void na_phase(CParams& p, const Ctx& cx, int l, const GI& gi) {
;     ...
;     const int c = cb * 16 + fr, cs = min(max(c - 8, 0), 48);
;     float mx = -1e30f;
; #pragma unroll
;     for (int t = 0; t < 16; ++t) {
;       const int ro = rs + (t >> 1) - r + 7;
; #pragma unroll
;       for (int j = 0; j < 4; ++j) {
;         const int kc = kstart + (t & 1) * 16 + fq * 4 + j;
;         const bool valid = kc >= cs && kc < cs + 16;
;         const int ci = min(max(kc - c + 15, 0), 30);
;         const float bv = rp[ro * 31 + ci];
;         const float v = valid ? s[t][j] + bv : -1e30f;
;         s[t][j] = v; mx = fmaxf(mx, v);
;       }
;     }
;     mx = fmaxf(mx, shflx(mx, 16, lane)); mx = fmaxf(mx, shflx(mx, 32, lane));
;     float sum = 0.f;
; #pragma unroll
;     for (int t = 0; t < 16; ++t)
; #pragma unroll
;       for (int j = 0; j < 4; ++j) { const float e = s[t][j] > -1e29f ? __expf(s[t][j] - mx) : 0.f; s[t][j] = e; sum += e; }
.LBB0_305:
	s_or_b64 exec, exec, s[6:7]
	s_mov_b32 s4, 0xf149f2ca
	v_max3_f32 v4, v67, s4, v66
	v_max3_f32 v4, v4, v63, v62
	v_max3_f32 v4, v4, v65, v64
	v_max3_f32 v4, v4, v58, v59
	v_max3_f32 v4, v4, v61, v60
	v_max3_f32 v4, v4, v55, v54
	v_max3_f32 v4, v4, v57, v56
	v_max3_f32 v4, v4, v51, v50
	v_max3_f32 v4, v4, v53, v52
	v_max3_f32 v4, v4, v47, v46
	v_max3_f32 v4, v4, v49, v48
	v_max3_f32 v4, v4, v43, v42
	v_max3_f32 v4, v4, v45, v44
	v_max3_f32 v4, v4, v39, v38
	v_max3_f32 v4, v4, v41, v40
	v_max3_f32 v4, v4, v35, v34
	v_max3_f32 v4, v4, v37, v36
	v_max3_f32 v4, v4, v31, v30
	v_max3_f32 v4, v4, v33, v32
	v_max3_f32 v4, v4, v27, v26
	v_max3_f32 v4, v4, v29, v28
	v_max3_f32 v4, v4, v23, v22
	v_max3_f32 v4, v4, v25, v24
	v_max3_f32 v4, v4, v19, v18
	v_max3_f32 v4, v4, v21, v20
	v_max3_f32 v4, v4, v15, v14
	v_max3_f32 v4, v4, v17, v16
	v_max3_f32 v4, v4, v11, v10
	v_max3_f32 v4, v4, v13, v12
	v_max3_f32 v4, v4, v69, v7
	v_max3_f32 v4, v4, v8, v6
	v_max3_f32 v4, v4, v2, v3
	ds_bpermute_b32 v5, v136, v4
	s_mov_b32 s93, 0xefa18f08
	v_cmp_lt_f32_e32 vcc, s93, v67
	v_cmp_lt_f32_e64 s[76:77], s93, v60
	v_cmp_lt_f32_e64 s[56:57], s93, v38
	s_waitcnt lgkmcnt(0)
	v_max_f32_e32 v5, v5, v5
	v_max_f32_e32 v4, v4, v5
	ds_bpermute_b32 v5, v137, v4
	v_cmp_lt_f32_e64 s[6:7], s93, v7
	v_cmp_lt_f32_e64 s[44:45], s93, v30
	v_cmp_lt_f32_e64 s[64:65], s93, v52
	v_cmp_lt_f32_e64 s[62:63], s93, v35
	s_waitcnt lgkmcnt(0)
	v_max_f32_e32 v5, v5, v5
	v_max_f32_e32 v4, v4, v5
	v_sub_f32_e32 v5, v67, v4
	v_mul_f32_e32 v5, 0x3fb8aa3b, v5
	v_exp_f32_e32 v5, v5
	v_sub_f32_e32 v76, v59, v4
	v_mul_f32_e32 v76, 0x3fb8aa3b, v76
	v_exp_f32_e32 v76, v76
	v_sub_f32_e32 v77, v61, v4
	v_cndmask_b32_e32 v143, 0, v5, vcc
	v_mul_f32_e32 v77, 0x3fb8aa3b, v77
	v_cmp_lt_f32_e32 vcc, s93, v59
	v_sub_f32_e32 v59, v60, v4
	v_sub_f32_e32 v60, v50, v4
	v_exp_f32_e32 v77, v77
	v_mul_f32_e32 v60, 0x3fb8aa3b, v60
	v_cndmask_b32_e32 v144, 0, v76, vcc
	v_cmp_lt_f32_e32 vcc, s93, v61
	v_exp_f32_e32 v60, v60
	v_sub_f32_e32 v61, v53, v4
	v_mul_f32_e32 v61, 0x3fb8aa3b, v61
	v_exp_f32_e32 v61, v61
	v_sub_f32_e32 v38, v38, v4
	v_cndmask_b32_e32 v142, 0, v77, vcc
	v_cmp_lt_f32_e32 vcc, s93, v50
	v_mul_f32_e32 v38, 0x3fb8aa3b, v38
	v_sub_f32_e32 v7, v7, v4
	v_cndmask_b32_e32 v146, 0, v60, vcc
	v_exp_f32_e32 v60, v38
	v_sub_f32_e32 v38, v41, v4
	v_sub_f32_e32 v30, v30, v4
	v_mul_f32_e32 v7, 0x3fb8aa3b, v7
	v_cmp_lt_f32_e32 vcc, s93, v53
	v_sub_f32_e32 v50, v52, v4
	v_sub_f32_e32 v52, v42, v4
	v_mul_f32_e32 v38, 0x3fb8aa3b, v38
	v_sub_f32_e32 v35, v35, v4
	v_mul_f32_e32 v30, 0x3fb8aa3b, v30
	v_cmp_lt_f32_e64 s[8:9], s93, v8
	v_exp_f32_e32 v202, v7
	v_sub_f32_e32 v7, v8, v4
	v_sub_f32_e32 v8, v3, v4
	v_sub_f32_e32 v68, v63, v4
	v_cndmask_b32_e32 v145, 0, v61, vcc
	v_mul_f32_e32 v52, 0x3fb8aa3b, v52
	v_sub_f32_e32 v53, v45, v4
	v_exp_f32_e32 v61, v38
	v_sub_f32_e32 v38, v40, v4
	v_mul_f32_e32 v35, 0x3fb8aa3b, v35
	v_exp_f32_e32 v80, v30
	v_sub_f32_e32 v30, v33, v4
	v_cmp_lt_f32_e64 s[28:29], s93, v22
	v_sub_f32_e32 v22, v22, v4
	v_mul_f32_e32 v8, 0x3fb8aa3b, v8
	v_sub_f32_e32 v9, v66, v4
	v_mul_f32_e32 v68, 0x3fb8aa3b, v68
	v_exp_f32_e32 v52, v52
	v_mul_f32_e32 v53, 0x3fb8aa3b, v53
	v_mul_f32_e32 v38, 0x3fb8aa3b, v38
	v_exp_f32_e32 v77, v35
	v_sub_f32_e32 v35, v34, v4
	v_mul_f32_e32 v30, 0x3fb8aa3b, v30
	v_cmp_lt_f32_e64 s[50:51], s93, v27
	v_sub_f32_e32 v27, v27, v4
	v_mul_f32_e32 v22, 0x3fb8aa3b, v22
	v_exp_f32_e32 v8, v8
	v_sub_f32_e32 v74, v65, v4
	v_mul_f32_e32 v9, 0x3fb8aa3b, v9
	v_exp_f32_e32 v68, v68
	v_exp_f32_e32 v53, v53
	v_exp_f32_e32 v76, v38
	v_mul_f32_e32 v35, 0x3fb8aa3b, v35
	v_sub_f32_e32 v38, v37, v4
	v_exp_f32_e32 v81, v30
	v_sub_f32_e32 v30, v32, v4
	v_mul_f32_e32 v27, 0x3fb8aa3b, v27
	v_exp_f32_e32 v124, v22
	v_sub_f32_e32 v22, v25, v4
	v_cmp_lt_f32_e64 s[16:17], s93, v14
	v_sub_f32_e32 v14, v14, v4
	v_sub_f32_e32 v73, v62, v4
	v_exp_f32_e32 v9, v9
	v_mul_f32_e32 v67, 0x3fb8aa3b, v74
	v_exp_f32_e32 v35, v35
	v_mul_f32_e32 v38, 0x3fb8aa3b, v38
	v_mul_f32_e32 v30, 0x3fb8aa3b, v30
	v_exp_f32_e32 v83, v27
	v_sub_f32_e32 v27, v26, v4
	v_mul_f32_e32 v22, 0x3fb8aa3b, v22
	v_cmp_lt_f32_e64 s[36:37], s93, v19
	v_sub_f32_e32 v19, v19, v4
	v_mul_f32_e32 v14, 0x3fb8aa3b, v14
	v_mul_f32_e32 v73, 0x3fb8aa3b, v73
	v_exp_f32_e32 v67, v67
	v_sub_f32_e32 v75, v58, v4
	v_cmp_lt_f32_e32 vcc, s93, v42
	v_exp_f32_e32 v38, v38
	v_exp_f32_e32 v82, v30
	v_mul_f32_e32 v27, 0x3fb8aa3b, v27
	v_sub_f32_e32 v30, v29, v4
	v_exp_f32_e32 v125, v22
	v_sub_f32_e32 v22, v24, v4
	v_mul_f32_e32 v19, 0x3fb8aa3b, v19
	v_exp_f32_e32 v179, v14
	v_sub_f32_e32 v14, v17, v4
	v_cmp_lt_f32_e64 s[38:39], s93, v3
	v_exp_f32_e32 v73, v73
	v_sub_f32_e32 v74, v64, v4
	v_mul_f32_e32 v75, 0x3fb8aa3b, v75
	v_cndmask_b32_e32 v148, 0, v52, vcc
	v_cmp_lt_f32_e32 vcc, s93, v45
	v_exp_f32_e32 v27, v27
	v_mul_f32_e32 v30, 0x3fb8aa3b, v30
	v_mul_f32_e32 v22, 0x3fb8aa3b, v22
	v_exp_f32_e32 v127, v19
	v_sub_f32_e32 v19, v18, v4
	v_mul_f32_e32 v14, 0x3fb8aa3b, v14
	v_cmp_lt_f32_e64 s[22:23], s93, v11
	v_sub_f32_e32 v11, v11, v4
	v_cndmask_b32_e64 v158, 0, v8, s[38:39]
	v_cmp_lt_f32_e64 s[38:39], s93, v63
	v_mul_f32_e32 v74, 0x3fb8aa3b, v74
	v_exp_f32_e32 v75, v75
	v_cndmask_b32_e32 v147, 0, v53, vcc
	v_cmp_lt_f32_e32 vcc, s93, v34
	v_exp_f32_e32 v30, v30
	v_exp_f32_e32 v126, v22
	v_mul_f32_e32 v19, 0x3fb8aa3b, v19
	v_sub_f32_e32 v22, v21, v4
	v_exp_f32_e32 v180, v14
	v_sub_f32_e32 v14, v16, v4
	v_mul_f32_e32 v11, 0x3fb8aa3b, v11
	v_cndmask_b32_e64 v93, 0, v68, s[38:39]
	v_cmp_lt_f32_e64 s[38:39], s93, v66
	v_exp_f32_e32 v74, v74
	v_cndmask_b32_e32 v151, 0, v35, vcc
	v_cmp_lt_f32_e32 vcc, s93, v37
	v_exp_f32_e32 v19, v19
	v_mul_f32_e32 v22, 0x3fb8aa3b, v22
; DEVINL void na_phase(CParams& p, const Ctx& cx, int l, const GI& gi) {
;     ...
;     float sum = 0.f;
; #pragma unroll
;     for (int t = 0; t < 16; ++t)
; #pragma unroll
;       for (int j = 0; j < 4; ++j) { const float e = s[t][j] > -1e29f ? __expf(s[t][j] - mx) : 0.f; s[t][j] = e; sum += e; }
;     sum += shflx(sum, 16, lane); sum += shflx(sum, 32, lane);
;     const float inv = 1.f / sum;
;     f32x4 o[4];
; #pragma unroll
;     for (int dt = 0; dt < 4; ++dt) o[dt] = f32x4{0.f, 0.f, 0.f, 0.f};
;     const int gq = (kstart >> 2) + fq, sx = (fr & 7) << 1;
;     const char* vb0 = Vb + (wb * 64 + fr) * 128 + ((gq ^ sx) * 8);
;     const char* vb1 = Vb + (wb * 64 + fr) * 128 + (((gq + 4) ^ sx) * 8);
; #pragma unroll
;     for (int i = 0; i < 8; ++i) {
;       bf16x8 a;
; #pragma unroll
;       for (int j = 0; j < 4; ++j) { a[j] = (short)f2bf(s[2 * i][j] * inv); a[4 + j] = (short)f2bf(s[2 * i + 1][j] * inv); }
; #pragma unroll
;       for (int dt = 0; dt < 4; ++dt) {
;         const bf16x4 b0 = *(const bf16x4*)(vb0 + (i * 64 + dt * 16) * 128), b1 = *(const bf16x4*)(vb1 + (i * 64 + dt * 16) * 128);
	v_mul_f32_e32 v14, 0x3fb8aa3b, v14
	v_exp_f32_e32 v182, v11
	v_sub_f32_e32 v11, v10, v4
	v_cndmask_b32_e64 v92, 0, v9, s[38:39]
	v_cmp_lt_f32_e64 s[38:39], s93, v65
	v_cndmask_b32_e32 v149, 0, v38, vcc
	v_cmp_lt_f32_e32 vcc, s93, v26
	v_exp_f32_e32 v22, v22
	v_exp_f32_e32 v181, v14
	v_mul_f32_e32 v11, 0x3fb8aa3b, v11
	v_sub_f32_e32 v14, v13, v4
	v_cndmask_b32_e64 v95, 0, v67, s[38:39]
	v_cmp_lt_f32_e64 s[38:39], s93, v62
	v_cndmask_b32_e32 v153, 0, v27, vcc
	v_cmp_lt_f32_e32 vcc, s93, v29
	v_exp_f32_e32 v11, v11
	v_mul_f32_e32 v14, 0x3fb8aa3b, v14
	v_cndmask_b32_e64 v94, 0, v73, s[38:39]
	v_cmp_lt_f32_e64 s[38:39], s93, v58
	v_cndmask_b32_e32 v152, 0, v30, vcc
	v_cmp_lt_f32_e32 vcc, s93, v18
	v_exp_f32_e32 v14, v14
	v_cndmask_b32_e64 v97, 0, v75, s[38:39]
	v_cmp_lt_f32_e64 s[38:39], s93, v64
	v_cndmask_b32_e32 v155, 0, v19, vcc
	v_cmp_lt_f32_e32 vcc, s93, v21
	v_cndmask_b32_e64 v96, 0, v74, s[38:39]
	v_cmp_lt_f32_e64 s[38:39], s93, v2
	v_sub_f32_e32 v3, v6, v4
	v_sub_f32_e32 v2, v2, v4
	v_cndmask_b32_e32 v154, 0, v22, vcc
	v_cmp_lt_f32_e32 vcc, s93, v10
	v_sub_f32_e32 v10, v12, v4
	v_mul_f32_e32 v3, 0x3fb8aa3b, v3
	v_mul_f32_e32 v2, 0x3fb8aa3b, v2
	v_cndmask_b32_e32 v157, 0, v11, vcc
	v_cmp_lt_f32_e32 vcc, s93, v13
	v_mul_f32_e32 v10, 0x3fb8aa3b, v10
	v_exp_f32_e32 v204, v3
	v_exp_f32_e32 v205, v2
	v_add_u32_e32 v2, v71, v138
	v_lshlrev_b32_e32 v3, 1, v70
	v_cmp_lt_f32_e64 s[78:79], s93, v55
	v_sub_f32_e32 v55, v55, v4
	v_cmp_lt_f32_e64 s[80:81], s93, v54
	v_cmp_lt_f32_e64 s[82:83], s93, v57
	v_sub_f32_e32 v54, v54, v4
	v_sub_f32_e32 v57, v57, v4
	v_cmp_lt_f32_e64 s[84:85], s93, v56
	v_cmp_lt_f32_e64 s[86:87], s93, v51
	v_sub_f32_e32 v56, v56, v4
	v_sub_f32_e32 v51, v51, v4
	v_cmp_lt_f32_e64 s[66:67], s93, v47
	v_sub_f32_e32 v47, v47, v4
	v_cmp_lt_f32_e64 s[68:69], s93, v46
	v_cmp_lt_f32_e64 s[70:71], s93, v49
	v_sub_f32_e32 v46, v46, v4
	v_sub_f32_e32 v49, v49, v4
	v_cmp_lt_f32_e64 s[72:73], s93, v48
	v_cmp_lt_f32_e64 s[74:75], s93, v43
	v_sub_f32_e32 v48, v48, v4
	v_sub_f32_e32 v43, v43, v4
	v_cmp_lt_f32_e64 s[52:53], s93, v44
	v_cmp_lt_f32_e64 s[54:55], s93, v39
	v_sub_f32_e32 v42, v44, v4
	v_sub_f32_e32 v39, v39, v4
	v_cmp_lt_f32_e64 s[58:59], s93, v41
	v_cmp_lt_f32_e64 s[60:61], s93, v40
	v_cmp_lt_f32_e64 s[40:41], s93, v36
	v_cmp_lt_f32_e64 s[42:43], s93, v31
	v_sub_f32_e32 v34, v36, v4
	v_sub_f32_e32 v31, v31, v4
	v_cmp_lt_f32_e64 s[46:47], s93, v33
	v_cmp_lt_f32_e64 s[48:49], s93, v32
	v_cmp_lt_f32_e64 s[24:25], s93, v28
	v_cmp_lt_f32_e64 s[26:27], s93, v23
	v_sub_f32_e32 v26, v28, v4
	v_sub_f32_e32 v23, v23, v4
	v_cmp_lt_f32_e64 s[30:31], s93, v25
	v_cmp_lt_f32_e64 s[34:35], s93, v24
	v_cmp_lt_f32_e64 s[12:13], s93, v20
	v_cmp_lt_f32_e64 s[14:15], s93, v15
	v_sub_f32_e32 v18, v20, v4
	v_sub_f32_e32 v15, v15, v4
	v_cmp_lt_f32_e64 s[18:19], s93, v17
	v_cmp_lt_f32_e64 s[20:21], s93, v16
	v_cndmask_b32_e32 v156, 0, v14, vcc
	v_cmp_lt_f32_e32 vcc, s93, v12
	v_cmp_lt_f32_e64 s[4:5], s93, v69
	v_exp_f32_e32 v200, v10
	v_sub_f32_e32 v10, v69, v4
	v_cmp_lt_f32_e64 s[10:11], s93, v6
	v_or_b32_e32 v4, v0, v72
	v_readlane_b32 s93, v255, 48
	v_bitop3_b32 v6, v2, v3, 14 bitop3:0x78
	v_add_u32_e32 v2, 4, v2
	v_add_f32_e32 v5, 0, v143
	v_lshl_add_u32 v4, v4, 7, s93
	v_bitop3_b32 v2, v2, v3, 14 bitop3:0x78
	v_lshl_add_u32 v159, v2, 3, v4
	v_add_f32_e32 v2, v92, v5
	v_mul_f32_e32 v15, 0x3fb8aa3b, v15
	v_lshl_add_u32 v160, v6, 3, v4
	v_add_f32_e32 v2, v93, v2
	v_exp_f32_e32 v178, v15
	v_add_f32_e32 v2, v94, v2
	ds_read2st64_b64 v[12:15], v160 offset1:4
	v_add_f32_e32 v2, v95, v2
	v_add_f32_e32 v2, v96, v2
	v_add_f32_e32 v6, v97, v2
	v_mul_f32_e32 v18, 0x3fb8aa3b, v18
	v_mul_f32_e32 v10, 0x3fb8aa3b, v10
	v_mul_f32_e32 v7, 0x3fb8aa3b, v7
	v_add_f32_e32 v6, v144, v6
	v_exp_f32_e32 v161, v18
	v_exp_f32_e32 v201, v10
	v_exp_f32_e32 v203, v7
	ds_read2st64_b64 v[2:5], v159 offset1:4
	v_add_f32_e32 v20, v142, v6
	s_waitcnt lgkmcnt(1)
	v_mov_b32_e32 v6, v12
	v_mov_b32_e32 v7, v13
	ds_read2st64_b64 v[16:19], v160 offset0:8 offset1:12
	ds_read2st64_b64 v[10:13], v159 offset0:8 offset1:12
	v_mul_f32_e32 v59, 0x3fb8aa3b, v59
	v_mul_f32_e32 v55, 0x3fb8aa3b, v55
	v_mul_f32_e32 v54, 0x3fb8aa3b, v54
	v_mul_f32_e32 v57, 0x3fb8aa3b, v57
	v_mul_f32_e32 v56, 0x3fb8aa3b, v56
	v_mul_f32_e32 v51, 0x3fb8aa3b, v51
	v_mul_f32_e32 v50, 0x3fb8aa3b, v50
	v_mul_f32_e32 v47, 0x3fb8aa3b, v47
	v_mul_f32_e32 v46, 0x3fb8aa3b, v46
	v_mul_f32_e32 v49, 0x3fb8aa3b, v49
	v_mul_f32_e32 v48, 0x3fb8aa3b, v48
	v_mul_f32_e32 v43, 0x3fb8aa3b, v43
	v_mul_f32_e32 v42, 0x3fb8aa3b, v42
	v_mul_f32_e32 v39, 0x3fb8aa3b, v39
	v_mul_f32_e32 v34, 0x3fb8aa3b, v34
	v_mul_f32_e32 v31, 0x3fb8aa3b, v31
	v_mul_f32_e32 v26, 0x3fb8aa3b, v26
	v_mul_f32_e32 v23, 0x3fb8aa3b, v23
	v_exp_f32_e32 v59, v59
	v_exp_f32_e32 v55, v55
	v_exp_f32_e32 v54, v54
	v_exp_f32_e32 v57, v57
	v_exp_f32_e32 v56, v56
	v_exp_f32_e32 v51, v51
	v_exp_f32_e32 v50, v50
	v_exp_f32_e32 v47, v47
	v_exp_f32_e32 v46, v46
	v_exp_f32_e32 v49, v49
	v_exp_f32_e32 v48, v48
	v_exp_f32_e32 v43, v43
	v_exp_f32_e32 v52, v42
	v_exp_f32_e32 v53, v39
	v_exp_f32_e32 v78, v34
	v_exp_f32_e32 v79, v31
	v_exp_f32_e32 v84, v26
	v_exp_f32_e32 v85, v23
	s_waitcnt lgkmcnt(2)
	v_mov_b32_e32 v8, v2
	v_mov_b32_e32 v9, v3
	v_mov_b32_e32 v2, v14
	v_mov_b32_e32 v3, v15
	s_waitcnt lgkmcnt(1)
	v_mov_b32_e32 v14, v16
	v_mov_b32_e32 v15, v17
	s_waitcnt lgkmcnt(0)
; DEVINL void na_phase(CParams& p, const Ctx& cx, int l, const GI& gi) {
;     ...
; #pragma unroll
;     for (int t = 0; t < 16; ++t)
; #pragma unroll
;       for (int j = 0; j < 4; ++j) { const float e = s[t][j] > -1e29f ? __expf(s[t][j] - mx) : 0.f; s[t][j] = e; sum += e; }
;     sum += shflx(sum, 16, lane); sum += shflx(sum, 32, lane);
;     const float inv = 1.f / sum;
;     f32x4 o[4];
; #pragma unroll
;     for (int dt = 0; dt < 4; ++dt) o[dt] = f32x4{0.f, 0.f, 0.f, 0.f};
;     const int gq = (kstart >> 2) + fq, sx = (fr & 7) << 1;
;     const char* vb0 = Vb + (wb * 64 + fr) * 128 + ((gq ^ sx) * 8);
;     const char* vb1 = Vb + (wb * 64 + fr) * 128 + (((gq + 4) ^ sx) * 8);
; #pragma unroll
;     for (int i = 0; i < 8; ++i) {
;       bf16x8 a;
; #pragma unroll
;       for (int j = 0; j < 4; ++j) { a[j] = (short)f2bf(s[2 * i][j] * inv); a[4 + j] = (short)f2bf(s[2 * i + 1][j] * inv); }
; #pragma unroll
;       for (int dt = 0; dt < 4; ++dt) {
;         const bf16x4 b0 = *(const bf16x4*)(vb0 + (i * 64 + dt * 16) * 128), b1 = *(const bf16x4*)(vb1 + (i * 64 + dt * 16) * 128);
;         bf16x8 bb;
;         bb[0] = b0[0]; bb[1] = b0[1]; bb[2] = b0[2]; bb[3] = b0[3]; bb[4] = b1[0]; bb[5] = b1[1]; bb[6] = b1[2]; bb[7] = b1[3];
	v_mov_b32_e32 v16, v10
	v_mov_b32_e32 v17, v11
	v_mov_b32_e32 v10, v18
	v_mov_b32_e32 v11, v19
	v_cndmask_b32_e64 v98, 0, v59, s[76:77]
	v_cndmask_b32_e64 v99, 0, v55, s[78:79]
	v_add_f32_e32 v18, v98, v20
	v_add_f32_e32 v18, v99, v18
	v_cndmask_b32_e64 v100, 0, v54, s[80:81]
	v_cndmask_b32_e64 v101, 0, v57, s[82:83]
	v_add_f32_e32 v18, v100, v18
	ds_read2st64_b64 v[28:31], v160 offset0:16 offset1:20
	v_add_f32_e32 v18, v101, v18
	v_cndmask_b32_e64 v102, 0, v56, s[84:85]
	v_cndmask_b32_e64 v103, 0, v51, s[86:87]
	v_add_f32_e32 v18, v102, v18
	v_add_f32_e32 v22, v103, v18
	v_add_f32_e32 v22, v146, v22
	ds_read2st64_b64 v[18:21], v159 offset0:16 offset1:20
	v_add_f32_e32 v36, v145, v22
	s_waitcnt lgkmcnt(1)
	v_mov_b32_e32 v22, v28
	v_mov_b32_e32 v23, v29
	ds_read2st64_b64 v[32:35], v160 offset0:24 offset1:28
	ds_read2st64_b64 v[26:29], v159 offset0:24 offset1:28
	s_waitcnt lgkmcnt(2)
	v_mov_b32_e32 v24, v18
	v_mov_b32_e32 v25, v19
	v_mov_b32_e32 v18, v30
	v_mov_b32_e32 v19, v31
	s_waitcnt lgkmcnt(1)
	v_mov_b32_e32 v30, v32
	v_mov_b32_e32 v31, v33
	s_waitcnt lgkmcnt(0)
	v_mov_b32_e32 v32, v26
	v_mov_b32_e32 v33, v27
	v_mov_b32_e32 v26, v34
	v_mov_b32_e32 v27, v35
	v_cndmask_b32_e64 v104, 0, v50, s[64:65]
	v_cndmask_b32_e64 v105, 0, v47, s[66:67]
	v_add_f32_e32 v34, v104, v36
	v_add_f32_e32 v34, v105, v34
	v_cndmask_b32_e64 v106, 0, v46, s[68:69]
	v_cndmask_b32_e64 v107, 0, v49, s[70:71]
	v_add_f32_e32 v34, v106, v34
	ds_read2st64_b64 v[44:47], v160 offset0:32 offset1:36
	v_add_f32_e32 v34, v107, v34
	v_cndmask_b32_e64 v108, 0, v48, s[72:73]
	v_cndmask_b32_e64 v109, 0, v43, s[74:75]
	v_add_f32_e32 v34, v108, v34
	v_add_f32_e32 v38, v109, v34
	v_add_f32_e32 v38, v148, v38
	ds_read2st64_b64 v[34:37], v159 offset0:32 offset1:36
	v_add_f32_e32 v54, v147, v38
	s_waitcnt lgkmcnt(1)
	v_mov_b32_e32 v38, v44
	v_mov_b32_e32 v39, v45
	ds_read2st64_b64 v[48:51], v160 offset0:40 offset1:44
	ds_read2st64_b64 v[42:45], v159 offset0:40 offset1:44
	s_waitcnt lgkmcnt(2)
	v_mov_b32_e32 v40, v34
	v_mov_b32_e32 v41, v35
	v_mov_b32_e32 v34, v46
	v_mov_b32_e32 v35, v47
	s_waitcnt lgkmcnt(1)
	v_mov_b32_e32 v46, v48
	v_mov_b32_e32 v47, v49
	s_waitcnt lgkmcnt(0)
	v_mov_b32_e32 v48, v42
	v_mov_b32_e32 v49, v43
	v_mov_b32_e32 v42, v50
	v_mov_b32_e32 v43, v51
	v_cndmask_b32_e64 v110, 0, v52, s[52:53]
	v_cndmask_b32_e64 v111, 0, v53, s[54:55]
	v_add_f32_e32 v50, v110, v54
	v_add_f32_e32 v50, v111, v50
	v_cndmask_b32_e64 v112, 0, v60, s[56:57]
	v_cndmask_b32_e64 v113, 0, v61, s[58:59]
	v_add_f32_e32 v50, v112, v50
	ds_read2st64_b64 v[60:63], v160 offset0:48 offset1:52
	v_add_f32_e32 v50, v113, v50
	v_cndmask_b32_e64 v114, 0, v76, s[60:61]
	v_cndmask_b32_e64 v115, 0, v77, s[62:63]
	v_add_f32_e32 v50, v114, v50
	v_add_f32_e32 v54, v115, v50
	v_add_f32_e32 v54, v151, v54
	ds_read2st64_b64 v[50:53], v159 offset0:48 offset1:52
	v_add_f32_e32 v68, v149, v54
	s_waitcnt lgkmcnt(1)
	v_mov_b32_e32 v54, v60
	v_mov_b32_e32 v55, v61
	ds_read2st64_b64 v[64:67], v160 offset0:56 offset1:60
	ds_read2st64_b64 v[58:61], v159 offset0:56 offset1:60
	s_waitcnt lgkmcnt(2)
	v_mov_b32_e32 v56, v50
	v_mov_b32_e32 v57, v51
	v_mov_b32_e32 v50, v62
	v_mov_b32_e32 v51, v63
	s_waitcnt lgkmcnt(1)
	v_mov_b32_e32 v62, v64
	v_mov_b32_e32 v63, v65
	s_waitcnt lgkmcnt(0)
	v_mov_b32_e32 v64, v58
	v_mov_b32_e32 v65, v59
	v_mov_b32_e32 v58, v66
	v_mov_b32_e32 v59, v67
	v_cndmask_b32_e64 v116, 0, v78, s[40:41]
	v_cndmask_b32_e64 v117, 0, v79, s[42:43]
	v_add_f32_e32 v66, v116, v68
	v_add_f32_e32 v66, v117, v66
	v_cndmask_b32_e64 v118, 0, v80, s[44:45]
	v_cndmask_b32_e64 v119, 0, v81, s[46:47]
	v_add_f32_e32 v66, v118, v66
	ds_read2st64_b64 v[76:79], v160 offset0:64 offset1:68
	v_add_f32_e32 v66, v119, v66
	v_cndmask_b32_e64 v120, 0, v82, s[48:49]
	v_cndmask_b32_e64 v121, 0, v83, s[50:51]
	v_add_f32_e32 v66, v120, v66
	v_add_f32_e32 v70, v121, v66
	v_add_f32_e32 v70, v153, v70
	ds_read2st64_b64 v[66:69], v159 offset0:64 offset1:68
	v_add_f32_e32 v162, v152, v70
	s_waitcnt lgkmcnt(1)
	v_mov_b32_e32 v70, v76
	v_mov_b32_e32 v71, v77
	ds_read2st64_b64 v[80:83], v160 offset0:72 offset1:76
	ds_read2st64_b64 v[74:77], v159 offset0:72 offset1:76
	s_waitcnt lgkmcnt(2)
	v_mov_b32_e32 v72, v66
	v_mov_b32_e32 v73, v67
	v_mov_b32_e32 v66, v78
	v_mov_b32_e32 v67, v79
	s_waitcnt lgkmcnt(1)
	v_mov_b32_e32 v78, v80
	v_mov_b32_e32 v79, v81
	s_waitcnt lgkmcnt(0)
	v_mov_b32_e32 v80, v74
	v_mov_b32_e32 v81, v75
	v_mov_b32_e32 v74, v82
	v_mov_b32_e32 v75, v83
	v_cndmask_b32_e64 v122, 0, v84, s[24:25]
	v_cndmask_b32_e64 v123, 0, v85, s[26:27]
	v_add_f32_e32 v82, v122, v162
	v_add_f32_e32 v82, v123, v82
	v_cndmask_b32_e64 v124, 0, v124, s[28:29]
	v_cndmask_b32_e64 v125, 0, v125, s[30:31]
	v_add_f32_e32 v82, v124, v82
	v_add_f32_e32 v82, v125, v82
	v_cndmask_b32_e64 v126, 0, v126, s[34:35]
	v_cndmask_b32_e64 v127, 0, v127, s[36:37]
	v_add_f32_e32 v82, v126, v82
	ds_read2st64_b64 v[162:165], v160 offset0:80 offset1:84
	v_add_f32_e32 v166, v127, v82
	ds_read2st64_b64 v[82:85], v159 offset0:80 offset1:84
	ds_read2st64_b64 v[170:173], v160 offset0:88 offset1:92
	ds_read2st64_b64 v[174:177], v159 offset0:88 offset1:92
	v_add_f32_e32 v166, v155, v166
	v_add_f32_e32 v183, v154, v166
	s_waitcnt lgkmcnt(3)
	v_mov_b32_e32 v166, v162
	v_mov_b32_e32 v167, v163
	s_waitcnt lgkmcnt(2)
	v_mov_b32_e32 v168, v82
	v_mov_b32_e32 v169, v83
	v_mov_b32_e32 v82, v164
	v_mov_b32_e32 v83, v165
	s_waitcnt lgkmcnt(1)
	v_mov_b32_e32 v162, v170
	v_mov_b32_e32 v163, v171
	s_waitcnt lgkmcnt(0)
; DEVINL void na_phase(CParams& p, const Ctx& cx, int l, const GI& gi) {
;     ...
;     sum += shflx(sum, 16, lane); sum += shflx(sum, 32, lane);
;     const float inv = 1.f / sum;
;     f32x4 o[4];
; #pragma unroll
;     for (int dt = 0; dt < 4; ++dt) o[dt] = f32x4{0.f, 0.f, 0.f, 0.f};
;     const int gq = (kstart >> 2) + fq, sx = (fr & 7) << 1;
;     const char* vb0 = Vb + (wb * 64 + fr) * 128 + ((gq ^ sx) * 8);
;     const char* vb1 = Vb + (wb * 64 + fr) * 128 + (((gq + 4) ^ sx) * 8);
; #pragma unroll
;     for (int i = 0; i < 8; ++i) {
;       bf16x8 a;
; #pragma unroll
;       for (int j = 0; j < 4; ++j) { a[j] = (short)f2bf(s[2 * i][j] * inv); a[4 + j] = (short)f2bf(s[2 * i + 1][j] * inv); }
; #pragma unroll
;       for (int dt = 0; dt < 4; ++dt) {
;         const bf16x4 b0 = *(const bf16x4*)(vb0 + (i * 64 + dt * 16) * 128), b1 = *(const bf16x4*)(vb1 + (i * 64 + dt * 16) * 128);
;         bf16x8 bb;
;         bb[0] = b0[0]; bb[1] = b0[1]; bb[2] = b0[2]; bb[3] = b0[3]; bb[4] = b1[0]; bb[5] = b1[1]; bb[6] = b1[2]; bb[7] = b1[3];
;         o[dt] = __builtin_amdgcn_mfma_f32_16x16x32_bf16(a, bb, o[dt], 0, 0, 0);
	v_mov_b32_e32 v164, v174
	v_mov_b32_e32 v165, v175
	v_mov_b32_e32 v174, v172
	v_mov_b32_e32 v175, v173
	v_cndmask_b32_e64 v194, 0, v161, s[12:13]
	v_cndmask_b32_e64 v195, 0, v178, s[14:15]
	v_add_f32_e32 v161, v194, v183
	v_add_f32_e32 v161, v195, v161
	v_cndmask_b32_e64 v196, 0, v179, s[16:17]
	v_cndmask_b32_e64 v197, 0, v180, s[18:19]
	v_add_f32_e32 v161, v196, v161
	v_cndmask_b32_e64 v198, 0, v181, s[20:21]
	ds_read2st64_b64 v[170:173], v160 offset0:96 offset1:100
	ds_read2st64_b64 v[178:181], v159 offset0:96 offset1:100
	ds_read2st64_b64 v[186:189], v160 offset0:104 offset1:108
	ds_read2st64_b64 v[190:193], v159 offset0:104 offset1:108
	v_add_f32_e32 v161, v197, v161
	v_cndmask_b32_e64 v199, 0, v182, s[22:23]
	v_add_f32_e32 v161, v198, v161
	v_add_f32_e32 v161, v199, v161
	v_add_f32_e32 v161, v157, v161
	v_add_f32_e32 v161, v156, v161
	s_waitcnt lgkmcnt(3)
	v_mov_b32_e32 v182, v170
	v_mov_b32_e32 v183, v171
	s_waitcnt lgkmcnt(2)
	v_mov_b32_e32 v184, v178
	v_mov_b32_e32 v185, v179
	v_mov_b32_e32 v178, v172
	v_mov_b32_e32 v179, v173
	s_waitcnt lgkmcnt(1)
	v_mov_b32_e32 v170, v186
	v_mov_b32_e32 v171, v187
	s_waitcnt lgkmcnt(0)
	v_mov_b32_e32 v172, v190
	v_mov_b32_e32 v173, v191
	v_mov_b32_e32 v190, v188
	v_mov_b32_e32 v191, v189
	v_cndmask_b32_e32 v186, 0, v200, vcc
	v_cndmask_b32_e64 v187, 0, v201, s[4:5]
	v_add_f32_e32 v161, v186, v161
	v_add_f32_e32 v161, v187, v161
	v_cndmask_b32_e64 v188, 0, v202, s[6:7]
	v_cndmask_b32_e64 v189, 0, v203, s[8:9]
	v_add_f32_e32 v161, v188, v161
	v_add_f32_e32 v161, v189, v161
	v_cndmask_b32_e64 v200, 0, v204, s[10:11]
	v_cndmask_b32_e64 v201, 0, v205, s[38:39]
	v_add_f32_e32 v161, v200, v161
	v_add_f32_e32 v161, v201, v161
	v_add_f32_e32 v161, v158, v161
	v_mov_b32_e32 v202, v161
	s_nop 1
	v_permlane16_swap_b32_e32 v161, v202
	s_waitcnt lgkmcnt(0)
	v_add_f32_e32 v161, v161, v202
	v_mov_b32_e32 v202, v161
	s_nop 1
	v_permlane32_swap_b32_e32 v202, v161
	s_waitcnt lgkmcnt(0)
	v_add_f32_e32 v161, v161, v202
	s_mov_b32 s4, 0x5040100
	v_rcp_f32_e32 v202, v161
	s_nop 0
	v_pk_mul_f32 v[94:95], v[94:95], v[202:203] op_sel_hi:[1,0]
	v_mul_f32_e32 v143, v143, v202
	v_pk_mul_f32 v[92:93], v[92:93], v[202:203] op_sel_hi:[1,0]
	v_pk_mul_f32 v[96:97], v[96:97], v[202:203] op_sel_hi:[1,0]
	v_cvt_pk_bf16_f32 v94, v94, v95
	v_mul_f32_e32 v95, v144, v202
	v_cvt_pk_bf16_f32 v143, v143, s0
	v_cvt_pk_bf16_f32 v93, v92, v93
	v_cvt_pk_bf16_f32 v96, v96, v97
	v_cvt_pk_bf16_f32 v95, v95, s0
	v_perm_b32 v92, v93, v143, s4
	v_alignbit_b32 v93, v94, v93, 16
	v_alignbit_b32 v94, v96, v94, 16
	v_alignbit_b32 v95, v95, v96, 16
	s_nop 1
	v_mfma_f32_16x16x32_bf16 v[6:9], v[92:95], v[6:9], 0
	v_mfma_f32_16x16x32_bf16 v[2:5], v[92:95], v[2:5], 0
	v_mfma_f32_16x16x32_bf16 v[14:17], v[92:95], v[14:17], 0
	v_mfma_f32_16x16x32_bf16 v[10:13], v[92:95], v[10:13], 0
	v_mul_f32_e32 v92, v142, v202
	v_cvt_pk_bf16_f32 v94, v92, s0
	v_pk_mul_f32 v[92:93], v[98:99], v[202:203] op_sel_hi:[1,0]
	s_nop 0
	v_cvt_pk_bf16_f32 v93, v92, v93
	v_perm_b32 v92, v93, v94, s4
	v_pk_mul_f32 v[94:95], v[102:103], v[202:203] op_sel_hi:[1,0]
	s_nop 0
	v_cvt_pk_bf16_f32 v96, v94, v95
	v_pk_mul_f32 v[94:95], v[100:101], v[202:203] op_sel_hi:[1,0]
	s_nop 0
	v_cvt_pk_bf16_f32 v94, v94, v95
	v_mul_f32_e32 v95, v146, v202
	v_cvt_pk_bf16_f32 v95, v95, s0
	v_alignbit_b32 v93, v94, v93, 16
	v_alignbit_b32 v94, v96, v94, 16
	v_alignbit_b32 v95, v95, v96, 16
	s_nop 1
	v_mfma_f32_16x16x32_bf16 v[2:5], v[92:95], v[18:21], v[2:5]
	v_mul_f32_e32 v18, v145, v202
	v_cvt_pk_bf16_f32 v20, v18, s0
	v_pk_mul_f32 v[18:19], v[104:105], v[202:203] op_sel_hi:[1,0]
	v_mfma_f32_16x16x32_bf16 v[6:9], v[92:95], v[22:25], v[6:9]
	v_cvt_pk_bf16_f32 v19, v18, v19
	v_perm_b32 v18, v19, v20, s4
	v_pk_mul_f32 v[20:21], v[108:109], v[202:203] op_sel_hi:[1,0]
	v_mfma_f32_16x16x32_bf16 v[14:17], v[92:95], v[30:33], v[14:17]
	v_cvt_pk_bf16_f32 v22, v20, v21
	v_pk_mul_f32 v[20:21], v[106:107], v[202:203] op_sel_hi:[1,0]
	s_nop 0
	v_cvt_pk_bf16_f32 v20, v20, v21
	v_mul_f32_e32 v21, v148, v202
	v_cvt_pk_bf16_f32 v21, v21, s0
	v_alignbit_b32 v19, v20, v19, 16
	v_alignbit_b32 v20, v22, v20, 16
	v_alignbit_b32 v21, v21, v22, 16
	v_mfma_f32_16x16x32_bf16 v[10:13], v[92:95], v[26:29], v[10:13]
	ds_read2st64_b64 v[26:29], v159 offset0:112 offset1:116
	s_waitcnt lgkmcnt(0)
; DEVINL void na_phase(CParams& p, const Ctx& cx, int l, const GI& gi) {
;     ...
; #pragma unroll
;     for (int i = 0; i < 8; ++i) {
;       bf16x8 a;
; #pragma unroll
;       for (int j = 0; j < 4; ++j) { a[j] = (short)f2bf(s[2 * i][j] * inv); a[4 + j] = (short)f2bf(s[2 * i + 1][j] * inv); }
; #pragma unroll
;       for (int dt = 0; dt < 4; ++dt) {
;         const bf16x4 b0 = *(const bf16x4*)(vb0 + (i * 64 + dt * 16) * 128), b1 = *(const bf16x4*)(vb1 + (i * 64 + dt * 16) * 128);
;         bf16x8 bb;
;         bb[0] = b0[0]; bb[1] = b0[1]; bb[2] = b0[2]; bb[3] = b0[3]; bb[4] = b1[0]; bb[5] = b1[1]; bb[6] = b1[2]; bb[7] = b1[3];
;         o[dt] = __builtin_amdgcn_mfma_f32_16x16x32_bf16(a, bb, o[dt], 0, 0, 0);
;       }
;       __builtin_amdgcn_sched_barrier(0);
;     }
; #pragma unroll
;     for (int dt = 0; dt < 4; ++dt)
; #pragma unroll
;       for (int j = 0; j < 4; ++j) p.nao[(size_t)(tok0 + fq * 4 + j) * 512 + h * 64 + dt * 16 + fr] = f2bf(o[dt][j]);
;     __syncthreads();
	v_mov_b32_e32 v32, v26
	v_mfma_f32_16x16x32_bf16 v[6:9], v[18:21], v[38:41], v[6:9]
	v_mov_b32_e32 v33, v27
	v_mfma_f32_16x16x32_bf16 v[2:5], v[18:21], v[34:37], v[2:5]
	ds_read2st64_b64 v[34:37], v159 offset0:120 offset1:124
	v_mfma_f32_16x16x32_bf16 v[14:17], v[18:21], v[46:49], v[14:17]
	v_mfma_f32_16x16x32_bf16 v[10:13], v[18:21], v[42:45], v[10:13]
	v_mul_f32_e32 v18, v147, v202
	v_cvt_pk_bf16_f32 v20, v18, s0
	v_pk_mul_f32 v[18:19], v[110:111], v[202:203] op_sel_hi:[1,0]
	s_nop 0
	v_cvt_pk_bf16_f32 v19, v18, v19
	v_perm_b32 v18, v19, v20, s4
	v_pk_mul_f32 v[20:21], v[114:115], v[202:203] op_sel_hi:[1,0]
	s_nop 0
	v_cvt_pk_bf16_f32 v22, v20, v21
	v_pk_mul_f32 v[20:21], v[112:113], v[202:203] op_sel_hi:[1,0]
	s_nop 0
	v_cvt_pk_bf16_f32 v20, v20, v21
	v_mul_f32_e32 v21, v151, v202
	v_cvt_pk_bf16_f32 v21, v21, s0
	v_alignbit_b32 v19, v20, v19, 16
	v_alignbit_b32 v20, v22, v20, 16
	v_alignbit_b32 v21, v21, v22, 16
	s_nop 1
	v_mfma_f32_16x16x32_bf16 v[6:9], v[18:21], v[54:57], v[6:9]
	v_mfma_f32_16x16x32_bf16 v[2:5], v[18:21], v[50:53], v[2:5]
	v_mfma_f32_16x16x32_bf16 v[14:17], v[18:21], v[62:65], v[14:17]
	v_mfma_f32_16x16x32_bf16 v[10:13], v[18:21], v[58:61], v[10:13]
	v_mul_f32_e32 v18, v149, v202
	v_cvt_pk_bf16_f32 v20, v18, s0
	v_pk_mul_f32 v[18:19], v[116:117], v[202:203] op_sel_hi:[1,0]
	s_nop 0
	v_cvt_pk_bf16_f32 v19, v18, v19
	v_perm_b32 v18, v19, v20, s4
	v_pk_mul_f32 v[20:21], v[120:121], v[202:203] op_sel_hi:[1,0]
	s_nop 0
	v_cvt_pk_bf16_f32 v22, v20, v21
	v_pk_mul_f32 v[20:21], v[118:119], v[202:203] op_sel_hi:[1,0]
	s_nop 0
	v_cvt_pk_bf16_f32 v20, v20, v21
	v_mul_f32_e32 v21, v153, v202
	v_cvt_pk_bf16_f32 v21, v21, s0
	v_alignbit_b32 v19, v20, v19, 16
	v_alignbit_b32 v20, v22, v20, 16
	v_alignbit_b32 v21, v21, v22, 16
	s_nop 1
	v_mfma_f32_16x16x32_bf16 v[6:9], v[18:21], v[70:73], v[6:9]
	v_mfma_f32_16x16x32_bf16 v[2:5], v[18:21], v[66:69], v[2:5]
	v_mfma_f32_16x16x32_bf16 v[14:17], v[18:21], v[78:81], v[14:17]
	v_mfma_f32_16x16x32_bf16 v[10:13], v[18:21], v[74:77], v[10:13]
	v_mul_f32_e32 v18, v152, v202
	v_cvt_pk_bf16_f32 v20, v18, s0
	v_pk_mul_f32 v[18:19], v[122:123], v[202:203] op_sel_hi:[1,0]
	s_nop 0
	v_cvt_pk_bf16_f32 v19, v18, v19
	v_perm_b32 v18, v19, v20, s4
	v_pk_mul_f32 v[20:21], v[126:127], v[202:203] op_sel_hi:[1,0]
	s_nop 0
	v_cvt_pk_bf16_f32 v22, v20, v21
	v_pk_mul_f32 v[20:21], v[124:125], v[202:203] op_sel_hi:[1,0]
	s_nop 0
	v_cvt_pk_bf16_f32 v20, v20, v21
	v_mul_f32_e32 v21, v155, v202
	v_cvt_pk_bf16_f32 v21, v21, s0
	v_alignbit_b32 v19, v20, v19, 16
	v_alignbit_b32 v20, v22, v20, 16
	v_alignbit_b32 v21, v21, v22, 16
	s_nop 1
	v_mfma_f32_16x16x32_bf16 v[6:9], v[18:21], v[166:169], v[6:9]
	v_mfma_f32_16x16x32_bf16 v[2:5], v[18:21], v[82:85], v[2:5]
	v_mfma_f32_16x16x32_bf16 v[14:17], v[18:21], v[162:165], v[14:17]
	v_mfma_f32_16x16x32_bf16 v[10:13], v[18:21], v[174:177], v[10:13]
	v_mul_f32_e32 v18, v154, v202
	v_cvt_pk_bf16_f32 v20, v18, s0
	v_pk_mul_f32 v[18:19], v[194:195], v[202:203] op_sel_hi:[1,0]
	s_nop 0
	v_cvt_pk_bf16_f32 v19, v18, v19
	v_perm_b32 v18, v19, v20, s4
	v_pk_mul_f32 v[20:21], v[198:199], v[202:203] op_sel_hi:[1,0]
	s_nop 0
	v_cvt_pk_bf16_f32 v22, v20, v21
	v_pk_mul_f32 v[20:21], v[196:197], v[202:203] op_sel_hi:[1,0]
	s_nop 0
	v_cvt_pk_bf16_f32 v20, v20, v21
	v_mul_f32_e32 v21, v157, v202
	v_cvt_pk_bf16_f32 v21, v21, s0
	v_alignbit_b32 v19, v20, v19, 16
	v_alignbit_b32 v20, v22, v20, 16
	v_alignbit_b32 v21, v21, v22, 16
	ds_read2st64_b64 v[22:25], v160 offset0:112 offset1:116
	s_waitcnt lgkmcnt(0)
	v_mov_b32_e32 v31, v23
	v_mfma_f32_16x16x32_bf16 v[6:9], v[18:21], v[182:185], v[6:9]
	v_mov_b32_e32 v26, v24
	v_mov_b32_e32 v27, v25
	v_mov_b32_e32 v24, v34
	v_mfma_f32_16x16x32_bf16 v[2:5], v[18:21], v[178:181], v[2:5]
	v_mov_b32_e32 v25, v35
	v_mfma_f32_16x16x32_bf16 v[14:17], v[18:21], v[170:173], v[14:17]
	v_mfma_f32_16x16x32_bf16 v[10:13], v[18:21], v[190:193], v[10:13]
	v_mul_f32_e32 v18, v156, v202
	v_cvt_pk_bf16_f32 v20, v18, s0
	v_pk_mul_f32 v[18:19], v[186:187], v[202:203] op_sel_hi:[1,0]
	s_nop 0
	v_cvt_pk_bf16_f32 v19, v18, v19
	v_perm_b32 v18, v19, v20, s4
	v_pk_mul_f32 v[20:21], v[200:201], v[202:203] op_sel_hi:[1,0]
	s_nop 0
	v_cvt_pk_bf16_f32 v30, v20, v21
	v_pk_mul_f32 v[20:21], v[188:189], v[202:203] op_sel_hi:[1,0]
	s_nop 0
	v_cvt_pk_bf16_f32 v20, v20, v21
	v_mul_f32_e32 v21, v158, v202
	v_cvt_pk_bf16_f32 v21, v21, s0
	v_alignbit_b32 v19, v20, v19, 16
	v_alignbit_b32 v20, v30, v20, 16
	v_alignbit_b32 v21, v21, v30, 16
	v_mov_b32_e32 v30, v22
	s_nop 0
	v_mfma_f32_16x16x32_bf16 v[2:5], v[18:21], v[26:29], v[2:5]
	v_mfma_f32_16x16x32_bf16 v[6:9], v[18:21], v[30:33], v[6:9]
	ds_read2st64_b64 v[30:33], v160 offset0:120 offset1:124
	s_waitcnt lgkmcnt(0)
	v_mov_b32_e32 v22, v30
	v_mov_b32_e32 v23, v31
	v_mov_b32_e32 v34, v32
	v_mov_b32_e32 v35, v33
	v_mfma_f32_16x16x32_bf16 v[14:17], v[18:21], v[22:25], v[14:17]
	s_nop 0
	v_mfma_f32_16x16x32_bf16 v[10:13], v[18:21], v[34:37], v[10:13]
	v_add3_u32 v18, v129, s96, v141
	v_readlane_b32 s4, v255, 49
	v_lshlrev_b32_e32 v0, 1, v0
	v_readlane_b32 s5, v255, 50
	v_ashrrev_i32_e32 v19, 31, v18
	v_lshlrev_b64 v[22:23], 10, v[18:19]
	v_lshl_add_u64 v[20:21], s[4:5], 0, v[0:1]
	v_cvt_pk_bf16_f32 v0, v6, s0
	v_lshl_add_u64 v[22:23], v[20:21], 0, v[22:23]
	v_add_u32_e32 v6, 1, v18
	global_store_short v[22:23], v0, off
	v_cvt_pk_bf16_f32 v0, v7, s0
	v_ashrrev_i32_e32 v7, 31, v6
	v_add_u32_e32 v24, 2, v18
	v_lshlrev_b64 v[6:7], 10, v[6:7]
	v_ashrrev_i32_e32 v25, 31, v24
	v_lshl_add_u64 v[6:7], v[20:21], 0, v[6:7]
	v_lshlrev_b64 v[24:25], 10, v[24:25]
	global_store_short v[6:7], v0, off
	v_cvt_pk_bf16_f32 v0, v8, s0
	v_lshl_add_u64 v[24:25], v[20:21], 0, v[24:25]
	v_add_u32_e32 v8, 3, v18
	global_store_short v[24:25], v0, off
	v_cvt_pk_bf16_f32 v0, v9, s0
	v_ashrrev_i32_e32 v9, 31, v8
	v_lshlrev_b64 v[8:9], 10, v[8:9]
	v_lshl_add_u64 v[8:9], v[20:21], 0, v[8:9]
	global_store_short v[8:9], v0, off
	v_cvt_pk_bf16_f32 v0, v2, s0
	global_store_short v[22:23], v0, off offset:32
	v_cvt_pk_bf16_f32 v0, v3, s0
	global_store_short v[6:7], v0, off offset:32
	v_cvt_pk_bf16_f32 v0, v4, s0
	global_store_short v[24:25], v0, off offset:32
	v_cvt_pk_bf16_f32 v0, v5, s0
	global_store_short v[8:9], v0, off offset:32
	v_cvt_pk_bf16_f32 v0, v14, s0
	global_store_short v[22:23], v0, off offset:64
	v_cvt_pk_bf16_f32 v0, v15, s0
	global_store_short v[6:7], v0, off offset:64
	v_cvt_pk_bf16_f32 v0, v16, s0
	global_store_short v[24:25], v0, off offset:64
	v_cvt_pk_bf16_f32 v0, v17, s0
	global_store_short v[8:9], v0, off offset:64
	v_cvt_pk_bf16_f32 v0, v10, s0
	v_readlane_b32 s4, v255, 19
	v_readlane_b32 s24, v255, 52
	global_store_short v[22:23], v0, off offset:96
	v_cvt_pk_bf16_f32 v0, v11, s0
	s_add_i32 s24, s24, s4
	v_readlane_b32 s4, v255, 20
	global_store_short v[6:7], v0, off offset:96
	v_cvt_pk_bf16_f32 v0, v12, s0
	s_add_i32 s96, s96, s4
	v_readlane_b32 s4, v255, 46
	global_store_short v[24:25], v0, off offset:96
	v_cvt_pk_bf16_f32 v0, v13, s0
	s_cmp_lt_i32 s24, s4
	global_store_short v[8:9], v0, off offset:96
	s_barrier
; DEVINL void na_phase(CParams& p, const Ctx& cx, int l, const GI& gi) {
;     ...
;   for (int pr = cx.bid >> 3; pr < npairs; pr += nbh) {
	s_cbranch_scc0 .LBB0_434

; DEVINL float sigmoidf_(float x) { return __fdividef(1.f, 1.f + __expf(-x)); }
; DEVINL float siluf_(float x) { return __fdividef(x, 1.f + __expf(-x)); }
;   DEVINL void operator()(Acc& acc, int brow, int bcol) const {
;     ...
;       const int c0 = cbase + wc * 64 + fr * 4;
;       _Pragma("unroll") for (int ai = 0; ai < 2; ++ai) _Pragma("unroll") for (int m = 0; m < 4; ++m) _Pragma("unroll") for (int j = 0; j < 4; ++j) {
;         const int row = brow + ai * 128 + wr * 64 + m * 16 + fq * 4 + j;
;         float v[4] = {acc[ai][0][m][0][j], acc[ai][0][m][1][j], acc[ai][1][m][0][j], acc[ai][1][m][1][j]};
;         _Pragma("unroll") for (int k = 0; k < 4; ++k) v[k] = fn == 1 ? siluf_(v[k]) : (fn == 2 ? sigmoidf_(v[k]) : (fn == 3 ? v[k] * 0.125f : v[k]));
;         *(bf16x4*)(dst + (size_t)row * ld + c0) = pack4(v[0], v[1], v[2], v[3]);
;       }
.Lgw_silu:
	s_add_u32 s24, s88, s24
	s_addc_u32 s25, s89, s25
	s_load_dwordx2 s[24:25], s[24:25], 0x0
	s_add_i32 s13, s13, s22
	s_mov_b32 s100, 0xbfb8aa3b
	s_mov_b32 s101, 0xbfb8aa3b
	v_lshlrev_b32_e32 v0, 6, v149
	v_lshlrev_b32_e32 v142, 2, v146
	v_or3_b32 v142, v0, v142, s13
	v_lshl_add_u32 v0, v144, 6, s12
	v_lshl_or_b32 v0, v145, 2, v0
	v_lshlrev_b32_e32 v0, 10, v0
	v_add_lshl_u32 v200, v0, v142, 1
	s_waitcnt lgkmcnt(0)
	v_pk_mul_f32 v[184:185], v[118:119], s[100:101] op_sel_hi:[1,0]
	v_pk_mul_f32 v[186:187], v[114:115], s[100:101] op_sel_hi:[1,0]
	v_pk_mul_f32 v[188:189], v[126:127], s[100:101] op_sel_hi:[1,0]
	v_pk_mul_f32 v[190:191], v[122:123], s[100:101] op_sel_hi:[1,0]
	v_exp_f32_e32 v184, v184
	v_exp_f32_e32 v185, v185
	v_exp_f32_e32 v186, v186
	v_exp_f32_e32 v187, v187
	v_exp_f32_e32 v188, v188
	v_exp_f32_e32 v189, v189
	v_exp_f32_e32 v190, v190
	v_exp_f32_e32 v191, v191
	v_pk_add_f32 v[184:185], v[184:185], 1.0 op_sel_hi:[1,0]
	v_pk_add_f32 v[186:187], v[186:187], 1.0 op_sel_hi:[1,0]
	v_pk_add_f32 v[188:189], v[188:189], 1.0 op_sel_hi:[1,0]
	v_pk_add_f32 v[190:191], v[190:191], 1.0 op_sel_hi:[1,0]
	v_rcp_f32_e32 v184, v184
	v_rcp_f32_e32 v185, v185
	v_rcp_f32_e32 v186, v186
	v_rcp_f32_e32 v187, v187
	v_rcp_f32_e32 v188, v188
	v_rcp_f32_e32 v189, v189
	v_rcp_f32_e32 v190, v190
	v_rcp_f32_e32 v191, v191
	v_pk_mul_f32 v[184:185], v[118:119], v[184:185]
	v_pk_mul_f32 v[186:187], v[114:115], v[186:187]
	v_pk_mul_f32 v[188:189], v[126:127], v[188:189]
	v_pk_mul_f32 v[190:191], v[122:123], v[190:191]
	v_cvt_pk_bf16_f32 v204, v184, v186
	v_cvt_pk_bf16_f32 v205, v188, v190
	v_mov_b32_e32 v201, v200
	global_store_dwordx2 v201, v[204:205], s[24:25]
	v_cvt_pk_bf16_f32 v212, v185, v187
	v_cvt_pk_bf16_f32 v213, v189, v191
	global_store_dwordx2 v201, v[212:213], s[24:25] offset:2048
	v_pk_mul_f32 v[192:193], v[120:121], s[100:101] op_sel_hi:[1,0]
	v_pk_mul_f32 v[194:195], v[116:117], s[100:101] op_sel_hi:[1,0]
	v_pk_mul_f32 v[196:197], v[128:129], s[100:101] op_sel_hi:[1,0]
	v_pk_mul_f32 v[198:199], v[124:125], s[100:101] op_sel_hi:[1,0]
	v_exp_f32_e32 v192, v192
	v_exp_f32_e32 v193, v193
	v_exp_f32_e32 v194, v194
	v_exp_f32_e32 v195, v195
	v_exp_f32_e32 v196, v196
	v_exp_f32_e32 v197, v197
	v_exp_f32_e32 v198, v198
	v_exp_f32_e32 v199, v199
	v_pk_add_f32 v[192:193], v[192:193], 1.0 op_sel_hi:[1,0]
	v_pk_add_f32 v[194:195], v[194:195], 1.0 op_sel_hi:[1,0]
	v_pk_add_f32 v[196:197], v[196:197], 1.0 op_sel_hi:[1,0]
	v_pk_add_f32 v[198:199], v[198:199], 1.0 op_sel_hi:[1,0]
	v_rcp_f32_e32 v192, v192
	v_rcp_f32_e32 v193, v193
	v_rcp_f32_e32 v194, v194
	v_rcp_f32_e32 v195, v195
	v_rcp_f32_e32 v196, v196
	v_rcp_f32_e32 v197, v197
	v_rcp_f32_e32 v198, v198
	v_rcp_f32_e32 v199, v199
	v_pk_mul_f32 v[192:193], v[120:121], v[192:193]
	v_pk_mul_f32 v[194:195], v[116:117], v[194:195]
	v_pk_mul_f32 v[196:197], v[128:129], v[196:197]
	v_pk_mul_f32 v[198:199], v[124:125], v[198:199]
	v_cvt_pk_bf16_f32 v206, v192, v194
	v_cvt_pk_bf16_f32 v207, v196, v198
	v_add_u32_e32 v202, 0x1000, v200
	global_store_dwordx2 v202, v[206:207], s[24:25]
	v_cvt_pk_bf16_f32 v214, v193, v195
	v_cvt_pk_bf16_f32 v215, v197, v199
	global_store_dwordx2 v202, v[214:215], s[24:25] offset:2048
	v_pk_mul_f32 v[184:185], v[102:103], s[100:101] op_sel_hi:[1,0]
	v_pk_mul_f32 v[186:187], v[98:99], s[100:101] op_sel_hi:[1,0]
	v_pk_mul_f32 v[188:189], v[110:111], s[100:101] op_sel_hi:[1,0]
	v_pk_mul_f32 v[190:191], v[106:107], s[100:101] op_sel_hi:[1,0]
	v_exp_f32_e32 v184, v184
	v_exp_f32_e32 v185, v185
	v_exp_f32_e32 v186, v186
	v_exp_f32_e32 v187, v187
	v_exp_f32_e32 v188, v188
	v_exp_f32_e32 v189, v189
	v_exp_f32_e32 v190, v190
	v_exp_f32_e32 v191, v191
	v_pk_add_f32 v[184:185], v[184:185], 1.0 op_sel_hi:[1,0]
	v_pk_add_f32 v[186:187], v[186:187], 1.0 op_sel_hi:[1,0]
	v_pk_add_f32 v[188:189], v[188:189], 1.0 op_sel_hi:[1,0]
	v_pk_add_f32 v[190:191], v[190:191], 1.0 op_sel_hi:[1,0]
	v_rcp_f32_e32 v184, v184
	v_rcp_f32_e32 v185, v185
	v_rcp_f32_e32 v186, v186
	v_rcp_f32_e32 v187, v187
	v_rcp_f32_e32 v188, v188
	v_rcp_f32_e32 v189, v189
	v_rcp_f32_e32 v190, v190
	v_rcp_f32_e32 v191, v191
	v_pk_mul_f32 v[184:185], v[102:103], v[184:185]
	v_pk_mul_f32 v[186:187], v[98:99], v[186:187]
	v_pk_mul_f32 v[188:189], v[110:111], v[188:189]
	v_pk_mul_f32 v[190:191], v[106:107], v[190:191]
	v_cvt_pk_bf16_f32 v204, v184, v186
	v_cvt_pk_bf16_f32 v205, v188, v190
	v_add_u32_e32 v201, 0x8000, v200
	global_store_dwordx2 v201, v[204:205], s[24:25]
	v_cvt_pk_bf16_f32 v212, v185, v187
	v_cvt_pk_bf16_f32 v213, v189, v191
	global_store_dwordx2 v201, v[212:213], s[24:25] offset:2048
	v_pk_mul_f32 v[192:193], v[104:105], s[100:101] op_sel_hi:[1,0]
	v_pk_mul_f32 v[194:195], v[100:101], s[100:101] op_sel_hi:[1,0]
	v_pk_mul_f32 v[196:197], v[112:113], s[100:101] op_sel_hi:[1,0]
	v_pk_mul_f32 v[198:199], v[108:109], s[100:101] op_sel_hi:[1,0]
	v_exp_f32_e32 v192, v192
	v_exp_f32_e32 v193, v193
	v_exp_f32_e32 v194, v194
	v_exp_f32_e32 v195, v195
	v_exp_f32_e32 v196, v196
	v_exp_f32_e32 v197, v197
	v_exp_f32_e32 v198, v198
	v_exp_f32_e32 v199, v199
	v_pk_add_f32 v[192:193], v[192:193], 1.0 op_sel_hi:[1,0]
	v_pk_add_f32 v[194:195], v[194:195], 1.0 op_sel_hi:[1,0]
	v_pk_add_f32 v[196:197], v[196:197], 1.0 op_sel_hi:[1,0]
	v_pk_add_f32 v[198:199], v[198:199], 1.0 op_sel_hi:[1,0]
	v_rcp_f32_e32 v192, v192
	v_rcp_f32_e32 v193, v193
	v_rcp_f32_e32 v194, v194
	v_rcp_f32_e32 v195, v195
	v_rcp_f32_e32 v196, v196
	v_rcp_f32_e32 v197, v197
	v_rcp_f32_e32 v198, v198
	v_rcp_f32_e32 v199, v199
	v_pk_mul_f32 v[192:193], v[104:105], v[192:193]
	v_pk_mul_f32 v[194:195], v[100:101], v[194:195]
	v_pk_mul_f32 v[196:197], v[112:113], v[196:197]
; DEVINL float sigmoidf_(float x) { return __fdividef(1.f, 1.f + __expf(-x)); }
; DEVINL float siluf_(float x) { return __fdividef(x, 1.f + __expf(-x)); }
;   DEVINL void operator()(Acc& acc, int brow, int bcol) const {
;     ...
;       const int c0 = cbase + wc * 64 + fr * 4;
;       _Pragma("unroll") for (int ai = 0; ai < 2; ++ai) _Pragma("unroll") for (int m = 0; m < 4; ++m) _Pragma("unroll") for (int j = 0; j < 4; ++j) {
;         const int row = brow + ai * 128 + wr * 64 + m * 16 + fq * 4 + j;
;         float v[4] = {acc[ai][0][m][0][j], acc[ai][0][m][1][j], acc[ai][1][m][0][j], acc[ai][1][m][1][j]};
;         _Pragma("unroll") for (int k = 0; k < 4; ++k) v[k] = fn == 1 ? siluf_(v[k]) : (fn == 2 ? sigmoidf_(v[k]) : (fn == 3 ? v[k] * 0.125f : v[k]));
;         *(bf16x4*)(dst + (size_t)row * ld + c0) = pack4(v[0], v[1], v[2], v[3]);
;       }
	v_pk_mul_f32 v[198:199], v[108:109], v[198:199]
	v_cvt_pk_bf16_f32 v206, v192, v194
	v_cvt_pk_bf16_f32 v207, v196, v198
	v_add_u32_e32 v202, 0x9000, v200
	global_store_dwordx2 v202, v[206:207], s[24:25]
	v_cvt_pk_bf16_f32 v214, v193, v195
	v_cvt_pk_bf16_f32 v215, v197, v199
	global_store_dwordx2 v202, v[214:215], s[24:25] offset:2048
	v_pk_mul_f32 v[184:185], v[86:87], s[100:101] op_sel_hi:[1,0]
	v_pk_mul_f32 v[186:187], v[82:83], s[100:101] op_sel_hi:[1,0]
	v_pk_mul_f32 v[188:189], v[94:95], s[100:101] op_sel_hi:[1,0]
	v_pk_mul_f32 v[190:191], v[90:91], s[100:101] op_sel_hi:[1,0]
	v_exp_f32_e32 v184, v184
	v_exp_f32_e32 v185, v185
	v_exp_f32_e32 v186, v186
	v_exp_f32_e32 v187, v187
	v_exp_f32_e32 v188, v188
	v_exp_f32_e32 v189, v189
	v_exp_f32_e32 v190, v190
	v_exp_f32_e32 v191, v191
	v_pk_add_f32 v[184:185], v[184:185], 1.0 op_sel_hi:[1,0]
	v_pk_add_f32 v[186:187], v[186:187], 1.0 op_sel_hi:[1,0]
	v_pk_add_f32 v[188:189], v[188:189], 1.0 op_sel_hi:[1,0]
	v_pk_add_f32 v[190:191], v[190:191], 1.0 op_sel_hi:[1,0]
	v_rcp_f32_e32 v184, v184
	v_rcp_f32_e32 v185, v185
	v_rcp_f32_e32 v186, v186
	v_rcp_f32_e32 v187, v187
	v_rcp_f32_e32 v188, v188
	v_rcp_f32_e32 v189, v189
	v_rcp_f32_e32 v190, v190
	v_rcp_f32_e32 v191, v191
	v_pk_mul_f32 v[184:185], v[86:87], v[184:185]
	v_pk_mul_f32 v[186:187], v[82:83], v[186:187]
	v_pk_mul_f32 v[188:189], v[94:95], v[188:189]
	v_pk_mul_f32 v[190:191], v[90:91], v[190:191]
	v_cvt_pk_bf16_f32 v204, v184, v186
	v_cvt_pk_bf16_f32 v205, v188, v190
	v_add_u32_e32 v201, 0x10000, v200
	global_store_dwordx2 v201, v[204:205], s[24:25]
	v_cvt_pk_bf16_f32 v212, v185, v187
	v_cvt_pk_bf16_f32 v213, v189, v191
	global_store_dwordx2 v201, v[212:213], s[24:25] offset:2048
	v_pk_mul_f32 v[192:193], v[88:89], s[100:101] op_sel_hi:[1,0]
	v_pk_mul_f32 v[194:195], v[84:85], s[100:101] op_sel_hi:[1,0]
	v_pk_mul_f32 v[196:197], v[96:97], s[100:101] op_sel_hi:[1,0]
	v_pk_mul_f32 v[198:199], v[92:93], s[100:101] op_sel_hi:[1,0]
	v_exp_f32_e32 v192, v192
	v_exp_f32_e32 v193, v193
	v_exp_f32_e32 v194, v194
	v_exp_f32_e32 v195, v195
	v_exp_f32_e32 v196, v196
	v_exp_f32_e32 v197, v197
	v_exp_f32_e32 v198, v198
	v_exp_f32_e32 v199, v199
	v_pk_add_f32 v[192:193], v[192:193], 1.0 op_sel_hi:[1,0]
	v_pk_add_f32 v[194:195], v[194:195], 1.0 op_sel_hi:[1,0]
	v_pk_add_f32 v[196:197], v[196:197], 1.0 op_sel_hi:[1,0]
	v_pk_add_f32 v[198:199], v[198:199], 1.0 op_sel_hi:[1,0]
	v_rcp_f32_e32 v192, v192
	v_rcp_f32_e32 v193, v193
	v_rcp_f32_e32 v194, v194
	v_rcp_f32_e32 v195, v195
	v_rcp_f32_e32 v196, v196
	v_rcp_f32_e32 v197, v197
	v_rcp_f32_e32 v198, v198
	v_rcp_f32_e32 v199, v199
	v_pk_mul_f32 v[192:193], v[88:89], v[192:193]
	v_pk_mul_f32 v[194:195], v[84:85], v[194:195]
	v_pk_mul_f32 v[196:197], v[96:97], v[196:197]
	v_pk_mul_f32 v[198:199], v[92:93], v[198:199]
	v_cvt_pk_bf16_f32 v206, v192, v194
	v_cvt_pk_bf16_f32 v207, v196, v198
	v_add_u32_e32 v202, 0x11000, v200
	global_store_dwordx2 v202, v[206:207], s[24:25]
	v_cvt_pk_bf16_f32 v214, v193, v195
	v_cvt_pk_bf16_f32 v215, v197, v199
	global_store_dwordx2 v202, v[214:215], s[24:25] offset:2048
	v_pk_mul_f32 v[184:185], v[70:71], s[100:101] op_sel_hi:[1,0]
	v_pk_mul_f32 v[186:187], v[66:67], s[100:101] op_sel_hi:[1,0]
	v_pk_mul_f32 v[188:189], v[78:79], s[100:101] op_sel_hi:[1,0]
	v_pk_mul_f32 v[190:191], v[74:75], s[100:101] op_sel_hi:[1,0]
	v_exp_f32_e32 v184, v184
	v_exp_f32_e32 v185, v185
	v_exp_f32_e32 v186, v186
	v_exp_f32_e32 v187, v187
	v_exp_f32_e32 v188, v188
	v_exp_f32_e32 v189, v189
	v_exp_f32_e32 v190, v190
	v_exp_f32_e32 v191, v191
	v_pk_add_f32 v[184:185], v[184:185], 1.0 op_sel_hi:[1,0]
	v_pk_add_f32 v[186:187], v[186:187], 1.0 op_sel_hi:[1,0]
	v_pk_add_f32 v[188:189], v[188:189], 1.0 op_sel_hi:[1,0]
	v_pk_add_f32 v[190:191], v[190:191], 1.0 op_sel_hi:[1,0]
	v_rcp_f32_e32 v184, v184
	v_rcp_f32_e32 v185, v185
	v_rcp_f32_e32 v186, v186
	v_rcp_f32_e32 v187, v187
	v_rcp_f32_e32 v188, v188
	v_rcp_f32_e32 v189, v189
	v_rcp_f32_e32 v190, v190
	v_rcp_f32_e32 v191, v191
	v_pk_mul_f32 v[184:185], v[70:71], v[184:185]
	v_pk_mul_f32 v[186:187], v[66:67], v[186:187]
	v_pk_mul_f32 v[188:189], v[78:79], v[188:189]
	v_pk_mul_f32 v[190:191], v[74:75], v[190:191]
	v_cvt_pk_bf16_f32 v204, v184, v186
	v_cvt_pk_bf16_f32 v205, v188, v190
	v_add_u32_e32 v201, 0x18000, v200
	global_store_dwordx2 v201, v[204:205], s[24:25]
	v_cvt_pk_bf16_f32 v212, v185, v187
	v_cvt_pk_bf16_f32 v213, v189, v191
	global_store_dwordx2 v201, v[212:213], s[24:25] offset:2048
	v_pk_mul_f32 v[192:193], v[72:73], s[100:101] op_sel_hi:[1,0]
	v_pk_mul_f32 v[194:195], v[68:69], s[100:101] op_sel_hi:[1,0]
	v_pk_mul_f32 v[196:197], v[80:81], s[100:101] op_sel_hi:[1,0]
	v_pk_mul_f32 v[198:199], v[76:77], s[100:101] op_sel_hi:[1,0]
	v_exp_f32_e32 v192, v192
	v_exp_f32_e32 v193, v193
	v_exp_f32_e32 v194, v194
	v_exp_f32_e32 v195, v195
	v_exp_f32_e32 v196, v196
	v_exp_f32_e32 v197, v197
	v_exp_f32_e32 v198, v198
	v_exp_f32_e32 v199, v199
	v_pk_add_f32 v[192:193], v[192:193], 1.0 op_sel_hi:[1,0]
	v_pk_add_f32 v[194:195], v[194:195], 1.0 op_sel_hi:[1,0]
	v_pk_add_f32 v[196:197], v[196:197], 1.0 op_sel_hi:[1,0]
	v_pk_add_f32 v[198:199], v[198:199], 1.0 op_sel_hi:[1,0]
	v_rcp_f32_e32 v192, v192
	v_rcp_f32_e32 v193, v193
	v_rcp_f32_e32 v194, v194
	v_rcp_f32_e32 v195, v195
	v_rcp_f32_e32 v196, v196
	v_rcp_f32_e32 v197, v197
	v_rcp_f32_e32 v198, v198
	v_rcp_f32_e32 v199, v199
	v_pk_mul_f32 v[192:193], v[72:73], v[192:193]
	v_pk_mul_f32 v[194:195], v[68:69], v[194:195]
	v_pk_mul_f32 v[196:197], v[80:81], v[196:197]
	v_pk_mul_f32 v[198:199], v[76:77], v[198:199]
	v_cvt_pk_bf16_f32 v206, v192, v194
	v_cvt_pk_bf16_f32 v207, v196, v198
; DEVINL float sigmoidf_(float x) { return __fdividef(1.f, 1.f + __expf(-x)); }
; DEVINL float siluf_(float x) { return __fdividef(x, 1.f + __expf(-x)); }
;   DEVINL void operator()(Acc& acc, int brow, int bcol) const {
;     ...
;       const int c0 = cbase + wc * 64 + fr * 4;
;       _Pragma("unroll") for (int ai = 0; ai < 2; ++ai) _Pragma("unroll") for (int m = 0; m < 4; ++m) _Pragma("unroll") for (int j = 0; j < 4; ++j) {
;         const int row = brow + ai * 128 + wr * 64 + m * 16 + fq * 4 + j;
;         float v[4] = {acc[ai][0][m][0][j], acc[ai][0][m][1][j], acc[ai][1][m][0][j], acc[ai][1][m][1][j]};
;         _Pragma("unroll") for (int k = 0; k < 4; ++k) v[k] = fn == 1 ? siluf_(v[k]) : (fn == 2 ? sigmoidf_(v[k]) : (fn == 3 ? v[k] * 0.125f : v[k]));
;         *(bf16x4*)(dst + (size_t)row * ld + c0) = pack4(v[0], v[1], v[2], v[3]);
;       }
	v_add_u32_e32 v202, 0x19000, v200
	global_store_dwordx2 v202, v[206:207], s[24:25]
	v_cvt_pk_bf16_f32 v214, v193, v195
	v_cvt_pk_bf16_f32 v215, v197, v199
	global_store_dwordx2 v202, v[214:215], s[24:25] offset:2048
	v_pk_mul_f32 v[184:185], v[54:55], s[100:101] op_sel_hi:[1,0]
	v_pk_mul_f32 v[186:187], v[50:51], s[100:101] op_sel_hi:[1,0]
	v_pk_mul_f32 v[188:189], v[62:63], s[100:101] op_sel_hi:[1,0]
	v_pk_mul_f32 v[190:191], v[58:59], s[100:101] op_sel_hi:[1,0]
	v_exp_f32_e32 v184, v184
	v_exp_f32_e32 v185, v185
	v_exp_f32_e32 v186, v186
	v_exp_f32_e32 v187, v187
	v_exp_f32_e32 v188, v188
	v_exp_f32_e32 v189, v189
	v_exp_f32_e32 v190, v190
	v_exp_f32_e32 v191, v191
	v_pk_add_f32 v[184:185], v[184:185], 1.0 op_sel_hi:[1,0]
	v_pk_add_f32 v[186:187], v[186:187], 1.0 op_sel_hi:[1,0]
	v_pk_add_f32 v[188:189], v[188:189], 1.0 op_sel_hi:[1,0]
	v_pk_add_f32 v[190:191], v[190:191], 1.0 op_sel_hi:[1,0]
	v_rcp_f32_e32 v184, v184
	v_rcp_f32_e32 v185, v185
	v_rcp_f32_e32 v186, v186
	v_rcp_f32_e32 v187, v187
	v_rcp_f32_e32 v188, v188
	v_rcp_f32_e32 v189, v189
	v_rcp_f32_e32 v190, v190
	v_rcp_f32_e32 v191, v191
	v_pk_mul_f32 v[184:185], v[54:55], v[184:185]
	v_pk_mul_f32 v[186:187], v[50:51], v[186:187]
	v_pk_mul_f32 v[188:189], v[62:63], v[188:189]
	v_pk_mul_f32 v[190:191], v[58:59], v[190:191]
	v_cvt_pk_bf16_f32 v204, v184, v186
	v_cvt_pk_bf16_f32 v205, v188, v190
	v_add_u32_e32 v201, 0x40000, v200
	global_store_dwordx2 v201, v[204:205], s[24:25]
	v_cvt_pk_bf16_f32 v212, v185, v187
	v_cvt_pk_bf16_f32 v213, v189, v191
	global_store_dwordx2 v201, v[212:213], s[24:25] offset:2048
	v_pk_mul_f32 v[192:193], v[56:57], s[100:101] op_sel_hi:[1,0]
	v_pk_mul_f32 v[194:195], v[52:53], s[100:101] op_sel_hi:[1,0]
	v_pk_mul_f32 v[196:197], v[64:65], s[100:101] op_sel_hi:[1,0]
	v_pk_mul_f32 v[198:199], v[60:61], s[100:101] op_sel_hi:[1,0]
	v_exp_f32_e32 v192, v192
	v_exp_f32_e32 v193, v193
	v_exp_f32_e32 v194, v194
	v_exp_f32_e32 v195, v195
	v_exp_f32_e32 v196, v196
	v_exp_f32_e32 v197, v197
	v_exp_f32_e32 v198, v198
	v_exp_f32_e32 v199, v199
	v_pk_add_f32 v[192:193], v[192:193], 1.0 op_sel_hi:[1,0]
	v_pk_add_f32 v[194:195], v[194:195], 1.0 op_sel_hi:[1,0]
	v_pk_add_f32 v[196:197], v[196:197], 1.0 op_sel_hi:[1,0]
	v_pk_add_f32 v[198:199], v[198:199], 1.0 op_sel_hi:[1,0]
	v_rcp_f32_e32 v192, v192
	v_rcp_f32_e32 v193, v193
	v_rcp_f32_e32 v194, v194
	v_rcp_f32_e32 v195, v195
	v_rcp_f32_e32 v196, v196
	v_rcp_f32_e32 v197, v197
	v_rcp_f32_e32 v198, v198
	v_rcp_f32_e32 v199, v199
	v_pk_mul_f32 v[192:193], v[56:57], v[192:193]
	v_pk_mul_f32 v[194:195], v[52:53], v[194:195]
	v_pk_mul_f32 v[196:197], v[64:65], v[196:197]
	v_pk_mul_f32 v[198:199], v[60:61], v[198:199]
	v_cvt_pk_bf16_f32 v206, v192, v194
	v_cvt_pk_bf16_f32 v207, v196, v198
	v_add_u32_e32 v202, 0x41000, v200
	global_store_dwordx2 v202, v[206:207], s[24:25]
	v_cvt_pk_bf16_f32 v214, v193, v195
	v_cvt_pk_bf16_f32 v215, v197, v199
	global_store_dwordx2 v202, v[214:215], s[24:25] offset:2048
	v_pk_mul_f32 v[184:185], v[38:39], s[100:101] op_sel_hi:[1,0]
	v_pk_mul_f32 v[186:187], v[34:35], s[100:101] op_sel_hi:[1,0]
	v_pk_mul_f32 v[188:189], v[46:47], s[100:101] op_sel_hi:[1,0]
	v_pk_mul_f32 v[190:191], v[42:43], s[100:101] op_sel_hi:[1,0]
	v_exp_f32_e32 v184, v184
	v_exp_f32_e32 v185, v185
	v_exp_f32_e32 v186, v186
	v_exp_f32_e32 v187, v187
	v_exp_f32_e32 v188, v188
	v_exp_f32_e32 v189, v189
	v_exp_f32_e32 v190, v190
	v_exp_f32_e32 v191, v191
	v_pk_add_f32 v[184:185], v[184:185], 1.0 op_sel_hi:[1,0]
	v_pk_add_f32 v[186:187], v[186:187], 1.0 op_sel_hi:[1,0]
	v_pk_add_f32 v[188:189], v[188:189], 1.0 op_sel_hi:[1,0]
	v_pk_add_f32 v[190:191], v[190:191], 1.0 op_sel_hi:[1,0]
	v_rcp_f32_e32 v184, v184
	v_rcp_f32_e32 v185, v185
	v_rcp_f32_e32 v186, v186
	v_rcp_f32_e32 v187, v187
	v_rcp_f32_e32 v188, v188
	v_rcp_f32_e32 v189, v189
	v_rcp_f32_e32 v190, v190
	v_rcp_f32_e32 v191, v191
	v_pk_mul_f32 v[184:185], v[38:39], v[184:185]
	v_pk_mul_f32 v[186:187], v[34:35], v[186:187]
	v_pk_mul_f32 v[188:189], v[46:47], v[188:189]
	v_pk_mul_f32 v[190:191], v[42:43], v[190:191]
	v_cvt_pk_bf16_f32 v204, v184, v186
	v_cvt_pk_bf16_f32 v205, v188, v190
	v_add_u32_e32 v201, 0x48000, v200
	global_store_dwordx2 v201, v[204:205], s[24:25]
	v_cvt_pk_bf16_f32 v212, v185, v187
	v_cvt_pk_bf16_f32 v213, v189, v191
	global_store_dwordx2 v201, v[212:213], s[24:25] offset:2048
	v_pk_mul_f32 v[192:193], v[40:41], s[100:101] op_sel_hi:[1,0]
	v_pk_mul_f32 v[194:195], v[36:37], s[100:101] op_sel_hi:[1,0]
	v_pk_mul_f32 v[196:197], v[48:49], s[100:101] op_sel_hi:[1,0]
	v_pk_mul_f32 v[198:199], v[44:45], s[100:101] op_sel_hi:[1,0]
	v_exp_f32_e32 v192, v192
	v_exp_f32_e32 v193, v193
	v_exp_f32_e32 v194, v194
	v_exp_f32_e32 v195, v195
	v_exp_f32_e32 v196, v196
	v_exp_f32_e32 v197, v197
	v_exp_f32_e32 v198, v198
	v_exp_f32_e32 v199, v199
	v_pk_add_f32 v[192:193], v[192:193], 1.0 op_sel_hi:[1,0]
	v_pk_add_f32 v[194:195], v[194:195], 1.0 op_sel_hi:[1,0]
	v_pk_add_f32 v[196:197], v[196:197], 1.0 op_sel_hi:[1,0]
	v_pk_add_f32 v[198:199], v[198:199], 1.0 op_sel_hi:[1,0]
	v_rcp_f32_e32 v192, v192
	v_rcp_f32_e32 v193, v193
	v_rcp_f32_e32 v194, v194
	v_rcp_f32_e32 v195, v195
	v_rcp_f32_e32 v196, v196
	v_rcp_f32_e32 v197, v197
	v_rcp_f32_e32 v198, v198
	v_rcp_f32_e32 v199, v199
	v_pk_mul_f32 v[192:193], v[40:41], v[192:193]
	v_pk_mul_f32 v[194:195], v[36:37], v[194:195]
	v_pk_mul_f32 v[196:197], v[48:49], v[196:197]
	v_pk_mul_f32 v[198:199], v[44:45], v[198:199]
	v_cvt_pk_bf16_f32 v206, v192, v194
	v_cvt_pk_bf16_f32 v207, v196, v198
	v_add_u32_e32 v202, 0x49000, v200
	global_store_dwordx2 v202, v[206:207], s[24:25]
	v_cvt_pk_bf16_f32 v214, v193, v195
; DEVINL float sigmoidf_(float x) { return __fdividef(1.f, 1.f + __expf(-x)); }
; DEVINL float siluf_(float x) { return __fdividef(x, 1.f + __expf(-x)); }
;   DEVINL void operator()(Acc& acc, int brow, int bcol) const {
;     ...
;       const int c0 = cbase + wc * 64 + fr * 4;
;       _Pragma("unroll") for (int ai = 0; ai < 2; ++ai) _Pragma("unroll") for (int m = 0; m < 4; ++m) _Pragma("unroll") for (int j = 0; j < 4; ++j) {
;         const int row = brow + ai * 128 + wr * 64 + m * 16 + fq * 4 + j;
;         float v[4] = {acc[ai][0][m][0][j], acc[ai][0][m][1][j], acc[ai][1][m][0][j], acc[ai][1][m][1][j]};
;         _Pragma("unroll") for (int k = 0; k < 4; ++k) v[k] = fn == 1 ? siluf_(v[k]) : (fn == 2 ? sigmoidf_(v[k]) : (fn == 3 ? v[k] * 0.125f : v[k]));
;         *(bf16x4*)(dst + (size_t)row * ld + c0) = pack4(v[0], v[1], v[2], v[3]);
;       }
	v_cvt_pk_bf16_f32 v215, v197, v199
	global_store_dwordx2 v202, v[214:215], s[24:25] offset:2048
	v_pk_mul_f32 v[184:185], v[22:23], s[100:101] op_sel_hi:[1,0]
	v_pk_mul_f32 v[186:187], v[18:19], s[100:101] op_sel_hi:[1,0]
	v_pk_mul_f32 v[188:189], v[30:31], s[100:101] op_sel_hi:[1,0]
	v_pk_mul_f32 v[190:191], v[26:27], s[100:101] op_sel_hi:[1,0]
	v_exp_f32_e32 v184, v184
	v_exp_f32_e32 v185, v185
	v_exp_f32_e32 v186, v186
	v_exp_f32_e32 v187, v187
	v_exp_f32_e32 v188, v188
	v_exp_f32_e32 v189, v189
	v_exp_f32_e32 v190, v190
	v_exp_f32_e32 v191, v191
	v_pk_add_f32 v[184:185], v[184:185], 1.0 op_sel_hi:[1,0]
	v_pk_add_f32 v[186:187], v[186:187], 1.0 op_sel_hi:[1,0]
	v_pk_add_f32 v[188:189], v[188:189], 1.0 op_sel_hi:[1,0]
	v_pk_add_f32 v[190:191], v[190:191], 1.0 op_sel_hi:[1,0]
	v_rcp_f32_e32 v184, v184
	v_rcp_f32_e32 v185, v185
	v_rcp_f32_e32 v186, v186
	v_rcp_f32_e32 v187, v187
	v_rcp_f32_e32 v188, v188
	v_rcp_f32_e32 v189, v189
	v_rcp_f32_e32 v190, v190
	v_rcp_f32_e32 v191, v191
	v_pk_mul_f32 v[184:185], v[22:23], v[184:185]
	v_pk_mul_f32 v[186:187], v[18:19], v[186:187]
	v_pk_mul_f32 v[188:189], v[30:31], v[188:189]
	v_pk_mul_f32 v[190:191], v[26:27], v[190:191]
	v_cvt_pk_bf16_f32 v204, v184, v186
	v_cvt_pk_bf16_f32 v205, v188, v190
	v_add_u32_e32 v201, 0x50000, v200
	global_store_dwordx2 v201, v[204:205], s[24:25]
	v_cvt_pk_bf16_f32 v212, v185, v187
	v_cvt_pk_bf16_f32 v213, v189, v191
	global_store_dwordx2 v201, v[212:213], s[24:25] offset:2048
	v_pk_mul_f32 v[192:193], v[24:25], s[100:101] op_sel_hi:[1,0]
	v_pk_mul_f32 v[194:195], v[20:21], s[100:101] op_sel_hi:[1,0]
	v_pk_mul_f32 v[196:197], v[32:33], s[100:101] op_sel_hi:[1,0]
	v_pk_mul_f32 v[198:199], v[28:29], s[100:101] op_sel_hi:[1,0]
	v_exp_f32_e32 v192, v192
	v_exp_f32_e32 v193, v193
	v_exp_f32_e32 v194, v194
	v_exp_f32_e32 v195, v195
	v_exp_f32_e32 v196, v196
	v_exp_f32_e32 v197, v197
	v_exp_f32_e32 v198, v198
	v_exp_f32_e32 v199, v199
	v_pk_add_f32 v[192:193], v[192:193], 1.0 op_sel_hi:[1,0]
	v_pk_add_f32 v[194:195], v[194:195], 1.0 op_sel_hi:[1,0]
	v_pk_add_f32 v[196:197], v[196:197], 1.0 op_sel_hi:[1,0]
	v_pk_add_f32 v[198:199], v[198:199], 1.0 op_sel_hi:[1,0]
	v_rcp_f32_e32 v192, v192
	v_rcp_f32_e32 v193, v193
	v_rcp_f32_e32 v194, v194
	v_rcp_f32_e32 v195, v195
	v_rcp_f32_e32 v196, v196
	v_rcp_f32_e32 v197, v197
	v_rcp_f32_e32 v198, v198
	v_rcp_f32_e32 v199, v199
	v_pk_mul_f32 v[192:193], v[24:25], v[192:193]
	v_pk_mul_f32 v[194:195], v[20:21], v[194:195]
	v_pk_mul_f32 v[196:197], v[32:33], v[196:197]
	v_pk_mul_f32 v[198:199], v[28:29], v[198:199]
	v_cvt_pk_bf16_f32 v206, v192, v194
	v_cvt_pk_bf16_f32 v207, v196, v198
	v_add_u32_e32 v202, 0x51000, v200
	global_store_dwordx2 v202, v[206:207], s[24:25]
	v_cvt_pk_bf16_f32 v214, v193, v195
	v_cvt_pk_bf16_f32 v215, v197, v199
	global_store_dwordx2 v202, v[214:215], s[24:25] offset:2048
	v_pk_mul_f32 v[184:185], v[6:7], s[100:101] op_sel_hi:[1,0]
	v_pk_mul_f32 v[186:187], v[2:3], s[100:101] op_sel_hi:[1,0]
	v_pk_mul_f32 v[188:189], v[14:15], s[100:101] op_sel_hi:[1,0]
	v_pk_mul_f32 v[190:191], v[10:11], s[100:101] op_sel_hi:[1,0]
	v_exp_f32_e32 v184, v184
	v_exp_f32_e32 v185, v185
	v_exp_f32_e32 v186, v186
	v_exp_f32_e32 v187, v187
	v_exp_f32_e32 v188, v188
	v_exp_f32_e32 v189, v189
	v_exp_f32_e32 v190, v190
	v_exp_f32_e32 v191, v191
	v_pk_add_f32 v[184:185], v[184:185], 1.0 op_sel_hi:[1,0]
	v_pk_add_f32 v[186:187], v[186:187], 1.0 op_sel_hi:[1,0]
	v_pk_add_f32 v[188:189], v[188:189], 1.0 op_sel_hi:[1,0]
	v_pk_add_f32 v[190:191], v[190:191], 1.0 op_sel_hi:[1,0]
	v_rcp_f32_e32 v184, v184
	v_rcp_f32_e32 v185, v185
	v_rcp_f32_e32 v186, v186
	v_rcp_f32_e32 v187, v187
	v_rcp_f32_e32 v188, v188
	v_rcp_f32_e32 v189, v189
	v_rcp_f32_e32 v190, v190
	v_rcp_f32_e32 v191, v191
	v_pk_mul_f32 v[184:185], v[6:7], v[184:185]
	v_pk_mul_f32 v[186:187], v[2:3], v[186:187]
	v_pk_mul_f32 v[188:189], v[14:15], v[188:189]
	v_pk_mul_f32 v[190:191], v[10:11], v[190:191]
	v_cvt_pk_bf16_f32 v204, v184, v186
	v_cvt_pk_bf16_f32 v205, v188, v190
	v_add_u32_e32 v201, 0x58000, v200
	global_store_dwordx2 v201, v[204:205], s[24:25]
	v_cvt_pk_bf16_f32 v212, v185, v187
	v_cvt_pk_bf16_f32 v213, v189, v191
	global_store_dwordx2 v201, v[212:213], s[24:25] offset:2048
	v_pk_mul_f32 v[192:193], v[8:9], s[100:101] op_sel_hi:[1,0]
	v_pk_mul_f32 v[194:195], v[4:5], s[100:101] op_sel_hi:[1,0]
	v_pk_mul_f32 v[196:197], v[16:17], s[100:101] op_sel_hi:[1,0]
	v_pk_mul_f32 v[198:199], v[12:13], s[100:101] op_sel_hi:[1,0]
	v_exp_f32_e32 v192, v192
	v_exp_f32_e32 v193, v193
	v_exp_f32_e32 v194, v194
	v_exp_f32_e32 v195, v195
	v_exp_f32_e32 v196, v196
	v_exp_f32_e32 v197, v197
	v_exp_f32_e32 v198, v198
	v_exp_f32_e32 v199, v199
	v_pk_add_f32 v[192:193], v[192:193], 1.0 op_sel_hi:[1,0]
	v_pk_add_f32 v[194:195], v[194:195], 1.0 op_sel_hi:[1,0]
	v_pk_add_f32 v[196:197], v[196:197], 1.0 op_sel_hi:[1,0]
	v_pk_add_f32 v[198:199], v[198:199], 1.0 op_sel_hi:[1,0]
	v_rcp_f32_e32 v192, v192
	v_rcp_f32_e32 v193, v193
	v_rcp_f32_e32 v194, v194
	v_rcp_f32_e32 v195, v195
	v_rcp_f32_e32 v196, v196
	v_rcp_f32_e32 v197, v197
	v_rcp_f32_e32 v198, v198
	v_rcp_f32_e32 v199, v199
	v_pk_mul_f32 v[192:193], v[8:9], v[192:193]
	v_pk_mul_f32 v[194:195], v[4:5], v[194:195]
	v_pk_mul_f32 v[196:197], v[16:17], v[196:197]
	v_pk_mul_f32 v[198:199], v[12:13], v[198:199]
	v_cvt_pk_bf16_f32 v206, v192, v194
	v_cvt_pk_bf16_f32 v207, v196, v198
	v_add_u32_e32 v202, 0x59000, v200
	global_store_dwordx2 v202, v[206:207], s[24:25]
	v_cvt_pk_bf16_f32 v214, v193, v195
	v_cvt_pk_bf16_f32 v215, v197, v199
	global_store_dwordx2 v202, v[214:215], s[24:25] offset:2048
	s_branch .LBB0_445
; DEVINL float siluf_(float x) { return __fdividef(x, 1.f + __expf(-x)); }
; DEVINL float sigmoidf_(float x) { return __fdividef(1.f, 1.f + __expf(-x)); }
;   DEVINL void operator()(Acc& acc, int brow, int bcol) const {
;     ...
;       const int c0 = cbase + wc * 64 + fr * 4;
;       _Pragma("unroll") for (int ai = 0; ai < 2; ++ai) _Pragma("unroll") for (int m = 0; m < 4; ++m) _Pragma("unroll") for (int j = 0; j < 4; ++j) {
;         const int row = brow + ai * 128 + wr * 64 + m * 16 + fq * 4 + j;
;         float v[4] = {acc[ai][0][m][0][j], acc[ai][0][m][1][j], acc[ai][1][m][0][j], acc[ai][1][m][1][j]};
;         _Pragma("unroll") for (int k = 0; k < 4; ++k) v[k] = fn == 1 ? siluf_(v[k]) : (fn == 2 ? sigmoidf_(v[k]) : (fn == 3 ? v[k] * 0.125f : v[k]));
;         *(bf16x4*)(dst + (size_t)row * ld + c0) = pack4(v[0], v[1], v[2], v[3]);
;       }
.Lgw_sig:
	s_add_u32 s24, s88, s24
	s_addc_u32 s25, s89, s25
	s_load_dwordx2 s[24:25], s[24:25], 0x0
	s_add_i32 s13, s13, s22
	s_mov_b32 s100, 0xbfb8aa3b
	s_mov_b32 s101, 0xbfb8aa3b
	v_lshlrev_b32_e32 v0, 6, v149
	v_lshlrev_b32_e32 v142, 2, v146
	v_or3_b32 v142, v0, v142, s13
	v_lshl_add_u32 v0, v144, 6, s12
	v_lshl_or_b32 v0, v145, 2, v0
	v_lshlrev_b32_e32 v0, 10, v0
	v_add_lshl_u32 v200, v0, v142, 1
	s_waitcnt lgkmcnt(0)
	v_pk_mul_f32 v[184:185], v[118:119], s[100:101] op_sel_hi:[1,0]
	v_pk_mul_f32 v[186:187], v[114:115], s[100:101] op_sel_hi:[1,0]
	v_pk_mul_f32 v[188:189], v[126:127], s[100:101] op_sel_hi:[1,0]
	v_pk_mul_f32 v[190:191], v[122:123], s[100:101] op_sel_hi:[1,0]
	v_exp_f32_e32 v184, v184
	v_exp_f32_e32 v185, v185
	v_exp_f32_e32 v186, v186
	v_exp_f32_e32 v187, v187
	v_exp_f32_e32 v188, v188
	v_exp_f32_e32 v189, v189
	v_exp_f32_e32 v190, v190
	v_exp_f32_e32 v191, v191
	v_pk_add_f32 v[184:185], v[184:185], 1.0 op_sel_hi:[1,0]
	v_pk_add_f32 v[186:187], v[186:187], 1.0 op_sel_hi:[1,0]
	v_pk_add_f32 v[188:189], v[188:189], 1.0 op_sel_hi:[1,0]
	v_pk_add_f32 v[190:191], v[190:191], 1.0 op_sel_hi:[1,0]
	v_rcp_f32_e32 v184, v184
	v_rcp_f32_e32 v185, v185
	v_rcp_f32_e32 v186, v186
	v_rcp_f32_e32 v187, v187
	v_rcp_f32_e32 v188, v188
	v_rcp_f32_e32 v189, v189
	v_rcp_f32_e32 v190, v190
	v_rcp_f32_e32 v191, v191
	s_nop 0
	v_cvt_pk_bf16_f32 v204, v184, v186
	v_cvt_pk_bf16_f32 v205, v188, v190
	v_mov_b32_e32 v201, v200
	global_store_dwordx2 v201, v[204:205], s[24:25]
	v_cvt_pk_bf16_f32 v212, v185, v187
	v_cvt_pk_bf16_f32 v213, v189, v191
	global_store_dwordx2 v201, v[212:213], s[24:25] offset:2048
	v_pk_mul_f32 v[192:193], v[120:121], s[100:101] op_sel_hi:[1,0]
	v_pk_mul_f32 v[194:195], v[116:117], s[100:101] op_sel_hi:[1,0]
	v_pk_mul_f32 v[196:197], v[128:129], s[100:101] op_sel_hi:[1,0]
	v_pk_mul_f32 v[198:199], v[124:125], s[100:101] op_sel_hi:[1,0]
	v_exp_f32_e32 v192, v192
	v_exp_f32_e32 v193, v193
	v_exp_f32_e32 v194, v194
	v_exp_f32_e32 v195, v195
	v_exp_f32_e32 v196, v196
	v_exp_f32_e32 v197, v197
	v_exp_f32_e32 v198, v198
	v_exp_f32_e32 v199, v199
	v_pk_add_f32 v[192:193], v[192:193], 1.0 op_sel_hi:[1,0]
	v_pk_add_f32 v[194:195], v[194:195], 1.0 op_sel_hi:[1,0]
	v_pk_add_f32 v[196:197], v[196:197], 1.0 op_sel_hi:[1,0]
	v_pk_add_f32 v[198:199], v[198:199], 1.0 op_sel_hi:[1,0]
	v_rcp_f32_e32 v192, v192
	v_rcp_f32_e32 v193, v193
	v_rcp_f32_e32 v194, v194
	v_rcp_f32_e32 v195, v195
	v_rcp_f32_e32 v196, v196
	v_rcp_f32_e32 v197, v197
	v_rcp_f32_e32 v198, v198
	v_rcp_f32_e32 v199, v199
	s_nop 0
	v_cvt_pk_bf16_f32 v206, v192, v194
	v_cvt_pk_bf16_f32 v207, v196, v198
	v_add_u32_e32 v202, 0x1000, v200
	global_store_dwordx2 v202, v[206:207], s[24:25]
	v_cvt_pk_bf16_f32 v214, v193, v195
	v_cvt_pk_bf16_f32 v215, v197, v199
	global_store_dwordx2 v202, v[214:215], s[24:25] offset:2048
	v_pk_mul_f32 v[184:185], v[102:103], s[100:101] op_sel_hi:[1,0]
	v_pk_mul_f32 v[186:187], v[98:99], s[100:101] op_sel_hi:[1,0]
	v_pk_mul_f32 v[188:189], v[110:111], s[100:101] op_sel_hi:[1,0]
	v_pk_mul_f32 v[190:191], v[106:107], s[100:101] op_sel_hi:[1,0]
	v_exp_f32_e32 v184, v184
	v_exp_f32_e32 v185, v185
	v_exp_f32_e32 v186, v186
	v_exp_f32_e32 v187, v187
	v_exp_f32_e32 v188, v188
	v_exp_f32_e32 v189, v189
	v_exp_f32_e32 v190, v190
	v_exp_f32_e32 v191, v191
	v_pk_add_f32 v[184:185], v[184:185], 1.0 op_sel_hi:[1,0]
	v_pk_add_f32 v[186:187], v[186:187], 1.0 op_sel_hi:[1,0]
	v_pk_add_f32 v[188:189], v[188:189], 1.0 op_sel_hi:[1,0]
	v_pk_add_f32 v[190:191], v[190:191], 1.0 op_sel_hi:[1,0]
	v_rcp_f32_e32 v184, v184
	v_rcp_f32_e32 v185, v185
	v_rcp_f32_e32 v186, v186
	v_rcp_f32_e32 v187, v187
	v_rcp_f32_e32 v188, v188
	v_rcp_f32_e32 v189, v189
	v_rcp_f32_e32 v190, v190
	v_rcp_f32_e32 v191, v191
	s_nop 0
	v_cvt_pk_bf16_f32 v204, v184, v186
	v_cvt_pk_bf16_f32 v205, v188, v190
	v_add_u32_e32 v201, 0x8000, v200
	global_store_dwordx2 v201, v[204:205], s[24:25]
	v_cvt_pk_bf16_f32 v212, v185, v187
	v_cvt_pk_bf16_f32 v213, v189, v191
	global_store_dwordx2 v201, v[212:213], s[24:25] offset:2048
	v_pk_mul_f32 v[192:193], v[104:105], s[100:101] op_sel_hi:[1,0]
	v_pk_mul_f32 v[194:195], v[100:101], s[100:101] op_sel_hi:[1,0]
	v_pk_mul_f32 v[196:197], v[112:113], s[100:101] op_sel_hi:[1,0]
	v_pk_mul_f32 v[198:199], v[108:109], s[100:101] op_sel_hi:[1,0]
	v_exp_f32_e32 v192, v192
	v_exp_f32_e32 v193, v193
	v_exp_f32_e32 v194, v194
	v_exp_f32_e32 v195, v195
	v_exp_f32_e32 v196, v196
	v_exp_f32_e32 v197, v197
	v_exp_f32_e32 v198, v198
	v_exp_f32_e32 v199, v199
	v_pk_add_f32 v[192:193], v[192:193], 1.0 op_sel_hi:[1,0]
	v_pk_add_f32 v[194:195], v[194:195], 1.0 op_sel_hi:[1,0]
	v_pk_add_f32 v[196:197], v[196:197], 1.0 op_sel_hi:[1,0]
	v_pk_add_f32 v[198:199], v[198:199], 1.0 op_sel_hi:[1,0]
	v_rcp_f32_e32 v192, v192
	v_rcp_f32_e32 v193, v193
	v_rcp_f32_e32 v194, v194
	v_rcp_f32_e32 v195, v195
	v_rcp_f32_e32 v196, v196
	v_rcp_f32_e32 v197, v197
	v_rcp_f32_e32 v198, v198
	v_rcp_f32_e32 v199, v199
	s_nop 0
	v_cvt_pk_bf16_f32 v206, v192, v194
	v_cvt_pk_bf16_f32 v207, v196, v198
	v_add_u32_e32 v202, 0x9000, v200
	global_store_dwordx2 v202, v[206:207], s[24:25]
	v_cvt_pk_bf16_f32 v214, v193, v195
	v_cvt_pk_bf16_f32 v215, v197, v199
	global_store_dwordx2 v202, v[214:215], s[24:25] offset:2048
	v_pk_mul_f32 v[184:185], v[86:87], s[100:101] op_sel_hi:[1,0]
	v_pk_mul_f32 v[186:187], v[82:83], s[100:101] op_sel_hi:[1,0]
	v_pk_mul_f32 v[188:189], v[94:95], s[100:101] op_sel_hi:[1,0]
	v_pk_mul_f32 v[190:191], v[90:91], s[100:101] op_sel_hi:[1,0]
	v_exp_f32_e32 v184, v184
	v_exp_f32_e32 v185, v185
	v_exp_f32_e32 v186, v186
	v_exp_f32_e32 v187, v187
	v_exp_f32_e32 v188, v188
	v_exp_f32_e32 v189, v189
; DEVINL float siluf_(float x) { return __fdividef(x, 1.f + __expf(-x)); }
; DEVINL float sigmoidf_(float x) { return __fdividef(1.f, 1.f + __expf(-x)); }
;   DEVINL void operator()(Acc& acc, int brow, int bcol) const {
;     ...
;       const int c0 = cbase + wc * 64 + fr * 4;
;       _Pragma("unroll") for (int ai = 0; ai < 2; ++ai) _Pragma("unroll") for (int m = 0; m < 4; ++m) _Pragma("unroll") for (int j = 0; j < 4; ++j) {
;         const int row = brow + ai * 128 + wr * 64 + m * 16 + fq * 4 + j;
;         float v[4] = {acc[ai][0][m][0][j], acc[ai][0][m][1][j], acc[ai][1][m][0][j], acc[ai][1][m][1][j]};
;         _Pragma("unroll") for (int k = 0; k < 4; ++k) v[k] = fn == 1 ? siluf_(v[k]) : (fn == 2 ? sigmoidf_(v[k]) : (fn == 3 ? v[k] * 0.125f : v[k]));
;         *(bf16x4*)(dst + (size_t)row * ld + c0) = pack4(v[0], v[1], v[2], v[3]);
;       }
	v_exp_f32_e32 v190, v190
	v_exp_f32_e32 v191, v191
	v_pk_add_f32 v[184:185], v[184:185], 1.0 op_sel_hi:[1,0]
	v_pk_add_f32 v[186:187], v[186:187], 1.0 op_sel_hi:[1,0]
	v_pk_add_f32 v[188:189], v[188:189], 1.0 op_sel_hi:[1,0]
	v_pk_add_f32 v[190:191], v[190:191], 1.0 op_sel_hi:[1,0]
	v_rcp_f32_e32 v184, v184
	v_rcp_f32_e32 v185, v185
	v_rcp_f32_e32 v186, v186
	v_rcp_f32_e32 v187, v187
	v_rcp_f32_e32 v188, v188
	v_rcp_f32_e32 v189, v189
	v_rcp_f32_e32 v190, v190
	v_rcp_f32_e32 v191, v191
	s_nop 0
	v_cvt_pk_bf16_f32 v204, v184, v186
	v_cvt_pk_bf16_f32 v205, v188, v190
	v_add_u32_e32 v201, 0x10000, v200
	global_store_dwordx2 v201, v[204:205], s[24:25]
	v_cvt_pk_bf16_f32 v212, v185, v187
	v_cvt_pk_bf16_f32 v213, v189, v191
	global_store_dwordx2 v201, v[212:213], s[24:25] offset:2048
	v_pk_mul_f32 v[192:193], v[88:89], s[100:101] op_sel_hi:[1,0]
	v_pk_mul_f32 v[194:195], v[84:85], s[100:101] op_sel_hi:[1,0]
	v_pk_mul_f32 v[196:197], v[96:97], s[100:101] op_sel_hi:[1,0]
	v_pk_mul_f32 v[198:199], v[92:93], s[100:101] op_sel_hi:[1,0]
	v_exp_f32_e32 v192, v192
	v_exp_f32_e32 v193, v193
	v_exp_f32_e32 v194, v194
	v_exp_f32_e32 v195, v195
	v_exp_f32_e32 v196, v196
	v_exp_f32_e32 v197, v197
	v_exp_f32_e32 v198, v198
	v_exp_f32_e32 v199, v199
	v_pk_add_f32 v[192:193], v[192:193], 1.0 op_sel_hi:[1,0]
	v_pk_add_f32 v[194:195], v[194:195], 1.0 op_sel_hi:[1,0]
	v_pk_add_f32 v[196:197], v[196:197], 1.0 op_sel_hi:[1,0]
	v_pk_add_f32 v[198:199], v[198:199], 1.0 op_sel_hi:[1,0]
	v_rcp_f32_e32 v192, v192
	v_rcp_f32_e32 v193, v193
	v_rcp_f32_e32 v194, v194
	v_rcp_f32_e32 v195, v195
	v_rcp_f32_e32 v196, v196
	v_rcp_f32_e32 v197, v197
	v_rcp_f32_e32 v198, v198
	v_rcp_f32_e32 v199, v199
	s_nop 0
	v_cvt_pk_bf16_f32 v206, v192, v194
	v_cvt_pk_bf16_f32 v207, v196, v198
	v_add_u32_e32 v202, 0x11000, v200
	global_store_dwordx2 v202, v[206:207], s[24:25]
	v_cvt_pk_bf16_f32 v214, v193, v195
	v_cvt_pk_bf16_f32 v215, v197, v199
	global_store_dwordx2 v202, v[214:215], s[24:25] offset:2048
	v_pk_mul_f32 v[184:185], v[70:71], s[100:101] op_sel_hi:[1,0]
	v_pk_mul_f32 v[186:187], v[66:67], s[100:101] op_sel_hi:[1,0]
	v_pk_mul_f32 v[188:189], v[78:79], s[100:101] op_sel_hi:[1,0]
	v_pk_mul_f32 v[190:191], v[74:75], s[100:101] op_sel_hi:[1,0]
	v_exp_f32_e32 v184, v184
	v_exp_f32_e32 v185, v185
	v_exp_f32_e32 v186, v186
	v_exp_f32_e32 v187, v187
	v_exp_f32_e32 v188, v188
	v_exp_f32_e32 v189, v189
	v_exp_f32_e32 v190, v190
	v_exp_f32_e32 v191, v191
	v_pk_add_f32 v[184:185], v[184:185], 1.0 op_sel_hi:[1,0]
	v_pk_add_f32 v[186:187], v[186:187], 1.0 op_sel_hi:[1,0]
	v_pk_add_f32 v[188:189], v[188:189], 1.0 op_sel_hi:[1,0]
	v_pk_add_f32 v[190:191], v[190:191], 1.0 op_sel_hi:[1,0]
	v_rcp_f32_e32 v184, v184
	v_rcp_f32_e32 v185, v185
	v_rcp_f32_e32 v186, v186
	v_rcp_f32_e32 v187, v187
	v_rcp_f32_e32 v188, v188
	v_rcp_f32_e32 v189, v189
	v_rcp_f32_e32 v190, v190
	v_rcp_f32_e32 v191, v191
	s_nop 0
	v_cvt_pk_bf16_f32 v204, v184, v186
	v_cvt_pk_bf16_f32 v205, v188, v190
	v_add_u32_e32 v201, 0x18000, v200
	global_store_dwordx2 v201, v[204:205], s[24:25]
	v_cvt_pk_bf16_f32 v212, v185, v187
	v_cvt_pk_bf16_f32 v213, v189, v191
	global_store_dwordx2 v201, v[212:213], s[24:25] offset:2048
	v_pk_mul_f32 v[192:193], v[72:73], s[100:101] op_sel_hi:[1,0]
	v_pk_mul_f32 v[194:195], v[68:69], s[100:101] op_sel_hi:[1,0]
	v_pk_mul_f32 v[196:197], v[80:81], s[100:101] op_sel_hi:[1,0]
	v_pk_mul_f32 v[198:199], v[76:77], s[100:101] op_sel_hi:[1,0]
	v_exp_f32_e32 v192, v192
	v_exp_f32_e32 v193, v193
	v_exp_f32_e32 v194, v194
	v_exp_f32_e32 v195, v195
	v_exp_f32_e32 v196, v196
	v_exp_f32_e32 v197, v197
	v_exp_f32_e32 v198, v198
	v_exp_f32_e32 v199, v199
	v_pk_add_f32 v[192:193], v[192:193], 1.0 op_sel_hi:[1,0]
	v_pk_add_f32 v[194:195], v[194:195], 1.0 op_sel_hi:[1,0]
	v_pk_add_f32 v[196:197], v[196:197], 1.0 op_sel_hi:[1,0]
	v_pk_add_f32 v[198:199], v[198:199], 1.0 op_sel_hi:[1,0]
	v_rcp_f32_e32 v192, v192
	v_rcp_f32_e32 v193, v193
	v_rcp_f32_e32 v194, v194
	v_rcp_f32_e32 v195, v195
	v_rcp_f32_e32 v196, v196
	v_rcp_f32_e32 v197, v197
	v_rcp_f32_e32 v198, v198
	v_rcp_f32_e32 v199, v199
	s_nop 0
	v_cvt_pk_bf16_f32 v206, v192, v194
	v_cvt_pk_bf16_f32 v207, v196, v198
	v_add_u32_e32 v202, 0x19000, v200
	global_store_dwordx2 v202, v[206:207], s[24:25]
	v_cvt_pk_bf16_f32 v214, v193, v195
	v_cvt_pk_bf16_f32 v215, v197, v199
	global_store_dwordx2 v202, v[214:215], s[24:25] offset:2048
	v_pk_mul_f32 v[184:185], v[54:55], s[100:101] op_sel_hi:[1,0]
	v_pk_mul_f32 v[186:187], v[50:51], s[100:101] op_sel_hi:[1,0]
	v_pk_mul_f32 v[188:189], v[62:63], s[100:101] op_sel_hi:[1,0]
	v_pk_mul_f32 v[190:191], v[58:59], s[100:101] op_sel_hi:[1,0]
	v_exp_f32_e32 v184, v184
	v_exp_f32_e32 v185, v185
	v_exp_f32_e32 v186, v186
	v_exp_f32_e32 v187, v187
	v_exp_f32_e32 v188, v188
	v_exp_f32_e32 v189, v189
	v_exp_f32_e32 v190, v190
	v_exp_f32_e32 v191, v191
	v_pk_add_f32 v[184:185], v[184:185], 1.0 op_sel_hi:[1,0]
	v_pk_add_f32 v[186:187], v[186:187], 1.0 op_sel_hi:[1,0]
	v_pk_add_f32 v[188:189], v[188:189], 1.0 op_sel_hi:[1,0]
	v_pk_add_f32 v[190:191], v[190:191], 1.0 op_sel_hi:[1,0]
	v_rcp_f32_e32 v184, v184
	v_rcp_f32_e32 v185, v185
	v_rcp_f32_e32 v186, v186
	v_rcp_f32_e32 v187, v187
	v_rcp_f32_e32 v188, v188
	v_rcp_f32_e32 v189, v189
	v_rcp_f32_e32 v190, v190
	v_rcp_f32_e32 v191, v191
	s_nop 0
	v_cvt_pk_bf16_f32 v204, v184, v186
	v_cvt_pk_bf16_f32 v205, v188, v190
	v_add_u32_e32 v201, 0x40000, v200
	global_store_dwordx2 v201, v[204:205], s[24:25]
	v_cvt_pk_bf16_f32 v212, v185, v187
	v_cvt_pk_bf16_f32 v213, v189, v191
	global_store_dwordx2 v201, v[212:213], s[24:25] offset:2048
	v_pk_mul_f32 v[192:193], v[56:57], s[100:101] op_sel_hi:[1,0]
; DEVINL float siluf_(float x) { return __fdividef(x, 1.f + __expf(-x)); }
; DEVINL float sigmoidf_(float x) { return __fdividef(1.f, 1.f + __expf(-x)); }
;   DEVINL void operator()(Acc& acc, int brow, int bcol) const {
;     ...
;       const int c0 = cbase + wc * 64 + fr * 4;
;       _Pragma("unroll") for (int ai = 0; ai < 2; ++ai) _Pragma("unroll") for (int m = 0; m < 4; ++m) _Pragma("unroll") for (int j = 0; j < 4; ++j) {
;         const int row = brow + ai * 128 + wr * 64 + m * 16 + fq * 4 + j;
;         float v[4] = {acc[ai][0][m][0][j], acc[ai][0][m][1][j], acc[ai][1][m][0][j], acc[ai][1][m][1][j]};
;         _Pragma("unroll") for (int k = 0; k < 4; ++k) v[k] = fn == 1 ? siluf_(v[k]) : (fn == 2 ? sigmoidf_(v[k]) : (fn == 3 ? v[k] * 0.125f : v[k]));
;         *(bf16x4*)(dst + (size_t)row * ld + c0) = pack4(v[0], v[1], v[2], v[3]);
;       }
	v_pk_mul_f32 v[194:195], v[52:53], s[100:101] op_sel_hi:[1,0]
	v_pk_mul_f32 v[196:197], v[64:65], s[100:101] op_sel_hi:[1,0]
	v_pk_mul_f32 v[198:199], v[60:61], s[100:101] op_sel_hi:[1,0]
	v_exp_f32_e32 v192, v192
	v_exp_f32_e32 v193, v193
	v_exp_f32_e32 v194, v194
	v_exp_f32_e32 v195, v195
	v_exp_f32_e32 v196, v196
	v_exp_f32_e32 v197, v197
	v_exp_f32_e32 v198, v198
	v_exp_f32_e32 v199, v199
	v_pk_add_f32 v[192:193], v[192:193], 1.0 op_sel_hi:[1,0]
	v_pk_add_f32 v[194:195], v[194:195], 1.0 op_sel_hi:[1,0]
	v_pk_add_f32 v[196:197], v[196:197], 1.0 op_sel_hi:[1,0]
	v_pk_add_f32 v[198:199], v[198:199], 1.0 op_sel_hi:[1,0]
	v_rcp_f32_e32 v192, v192
	v_rcp_f32_e32 v193, v193
	v_rcp_f32_e32 v194, v194
	v_rcp_f32_e32 v195, v195
	v_rcp_f32_e32 v196, v196
	v_rcp_f32_e32 v197, v197
	v_rcp_f32_e32 v198, v198
	v_rcp_f32_e32 v199, v199
	s_nop 0
	v_cvt_pk_bf16_f32 v206, v192, v194
	v_cvt_pk_bf16_f32 v207, v196, v198
	v_add_u32_e32 v202, 0x41000, v200
	global_store_dwordx2 v202, v[206:207], s[24:25]
	v_cvt_pk_bf16_f32 v214, v193, v195
	v_cvt_pk_bf16_f32 v215, v197, v199
	global_store_dwordx2 v202, v[214:215], s[24:25] offset:2048
	v_pk_mul_f32 v[184:185], v[38:39], s[100:101] op_sel_hi:[1,0]
	v_pk_mul_f32 v[186:187], v[34:35], s[100:101] op_sel_hi:[1,0]
	v_pk_mul_f32 v[188:189], v[46:47], s[100:101] op_sel_hi:[1,0]
	v_pk_mul_f32 v[190:191], v[42:43], s[100:101] op_sel_hi:[1,0]
	v_exp_f32_e32 v184, v184
	v_exp_f32_e32 v185, v185
	v_exp_f32_e32 v186, v186
	v_exp_f32_e32 v187, v187
	v_exp_f32_e32 v188, v188
	v_exp_f32_e32 v189, v189
	v_exp_f32_e32 v190, v190
	v_exp_f32_e32 v191, v191
	v_pk_add_f32 v[184:185], v[184:185], 1.0 op_sel_hi:[1,0]
	v_pk_add_f32 v[186:187], v[186:187], 1.0 op_sel_hi:[1,0]
	v_pk_add_f32 v[188:189], v[188:189], 1.0 op_sel_hi:[1,0]
	v_pk_add_f32 v[190:191], v[190:191], 1.0 op_sel_hi:[1,0]
	v_rcp_f32_e32 v184, v184
	v_rcp_f32_e32 v185, v185
	v_rcp_f32_e32 v186, v186
	v_rcp_f32_e32 v187, v187
	v_rcp_f32_e32 v188, v188
	v_rcp_f32_e32 v189, v189
	v_rcp_f32_e32 v190, v190
	v_rcp_f32_e32 v191, v191
	s_nop 0
	v_cvt_pk_bf16_f32 v204, v184, v186
	v_cvt_pk_bf16_f32 v205, v188, v190
	v_add_u32_e32 v201, 0x48000, v200
	global_store_dwordx2 v201, v[204:205], s[24:25]
	v_cvt_pk_bf16_f32 v212, v185, v187
	v_cvt_pk_bf16_f32 v213, v189, v191
	global_store_dwordx2 v201, v[212:213], s[24:25] offset:2048
	v_pk_mul_f32 v[192:193], v[40:41], s[100:101] op_sel_hi:[1,0]
	v_pk_mul_f32 v[194:195], v[36:37], s[100:101] op_sel_hi:[1,0]
	v_pk_mul_f32 v[196:197], v[48:49], s[100:101] op_sel_hi:[1,0]
	v_pk_mul_f32 v[198:199], v[44:45], s[100:101] op_sel_hi:[1,0]
	v_exp_f32_e32 v192, v192
	v_exp_f32_e32 v193, v193
	v_exp_f32_e32 v194, v194
	v_exp_f32_e32 v195, v195
	v_exp_f32_e32 v196, v196
	v_exp_f32_e32 v197, v197
	v_exp_f32_e32 v198, v198
	v_exp_f32_e32 v199, v199
	v_pk_add_f32 v[192:193], v[192:193], 1.0 op_sel_hi:[1,0]
	v_pk_add_f32 v[194:195], v[194:195], 1.0 op_sel_hi:[1,0]
	v_pk_add_f32 v[196:197], v[196:197], 1.0 op_sel_hi:[1,0]
	v_pk_add_f32 v[198:199], v[198:199], 1.0 op_sel_hi:[1,0]
	v_rcp_f32_e32 v192, v192
	v_rcp_f32_e32 v193, v193
	v_rcp_f32_e32 v194, v194
	v_rcp_f32_e32 v195, v195
	v_rcp_f32_e32 v196, v196
	v_rcp_f32_e32 v197, v197
	v_rcp_f32_e32 v198, v198
	v_rcp_f32_e32 v199, v199
	s_nop 0
	v_cvt_pk_bf16_f32 v206, v192, v194
	v_cvt_pk_bf16_f32 v207, v196, v198
	v_add_u32_e32 v202, 0x49000, v200
	global_store_dwordx2 v202, v[206:207], s[24:25]
	v_cvt_pk_bf16_f32 v214, v193, v195
	v_cvt_pk_bf16_f32 v215, v197, v199
	global_store_dwordx2 v202, v[214:215], s[24:25] offset:2048
	v_pk_mul_f32 v[184:185], v[22:23], s[100:101] op_sel_hi:[1,0]
	v_pk_mul_f32 v[186:187], v[18:19], s[100:101] op_sel_hi:[1,0]
	v_pk_mul_f32 v[188:189], v[30:31], s[100:101] op_sel_hi:[1,0]
	v_pk_mul_f32 v[190:191], v[26:27], s[100:101] op_sel_hi:[1,0]
	v_exp_f32_e32 v184, v184
	v_exp_f32_e32 v185, v185
	v_exp_f32_e32 v186, v186
	v_exp_f32_e32 v187, v187
	v_exp_f32_e32 v188, v188
	v_exp_f32_e32 v189, v189
	v_exp_f32_e32 v190, v190
	v_exp_f32_e32 v191, v191
	v_pk_add_f32 v[184:185], v[184:185], 1.0 op_sel_hi:[1,0]
	v_pk_add_f32 v[186:187], v[186:187], 1.0 op_sel_hi:[1,0]
	v_pk_add_f32 v[188:189], v[188:189], 1.0 op_sel_hi:[1,0]
; DEVINL float siluf_(float x) { return __fdividef(x, 1.f + __expf(-x)); }
; DEVINL float sigmoidf_(float x) { return __fdividef(1.f, 1.f + __expf(-x)); }
;   DEVINL void operator()(Acc& acc, int brow, int bcol) const {
;     ...
;       const int c0 = cbase + wc * 64 + fr * 4;
;       _Pragma("unroll") for (int ai = 0; ai < 2; ++ai) _Pragma("unroll") for (int m = 0; m < 4; ++m) _Pragma("unroll") for (int j = 0; j < 4; ++j) {
;         const int row = brow + ai * 128 + wr * 64 + m * 16 + fq * 4 + j;
;         float v[4] = {acc[ai][0][m][0][j], acc[ai][0][m][1][j], acc[ai][1][m][0][j], acc[ai][1][m][1][j]};
;         _Pragma("unroll") for (int k = 0; k < 4; ++k) v[k] = fn == 1 ? siluf_(v[k]) : (fn == 2 ? sigmoidf_(v[k]) : (fn == 3 ? v[k] * 0.125f : v[k]));
;         *(bf16x4*)(dst + (size_t)row * ld + c0) = pack4(v[0], v[1], v[2], v[3]);
;       }
	v_pk_add_f32 v[190:191], v[190:191], 1.0 op_sel_hi:[1,0]
	v_rcp_f32_e32 v184, v184
	v_rcp_f32_e32 v185, v185
	v_rcp_f32_e32 v186, v186
	v_rcp_f32_e32 v187, v187
	v_rcp_f32_e32 v188, v188
	v_rcp_f32_e32 v189, v189
	v_rcp_f32_e32 v190, v190
	v_rcp_f32_e32 v191, v191
	s_nop 0
	v_cvt_pk_bf16_f32 v204, v184, v186
	v_cvt_pk_bf16_f32 v205, v188, v190
	v_add_u32_e32 v201, 0x50000, v200
	global_store_dwordx2 v201, v[204:205], s[24:25]
	v_cvt_pk_bf16_f32 v212, v185, v187
	v_cvt_pk_bf16_f32 v213, v189, v191
	global_store_dwordx2 v201, v[212:213], s[24:25] offset:2048
	v_pk_mul_f32 v[192:193], v[24:25], s[100:101] op_sel_hi:[1,0]
	v_pk_mul_f32 v[194:195], v[20:21], s[100:101] op_sel_hi:[1,0]
	v_pk_mul_f32 v[196:197], v[32:33], s[100:101] op_sel_hi:[1,0]
	v_pk_mul_f32 v[198:199], v[28:29], s[100:101] op_sel_hi:[1,0]
	v_exp_f32_e32 v192, v192
	v_exp_f32_e32 v193, v193
	v_exp_f32_e32 v194, v194
	v_exp_f32_e32 v195, v195
	v_exp_f32_e32 v196, v196
	v_exp_f32_e32 v197, v197
	v_exp_f32_e32 v198, v198
	v_exp_f32_e32 v199, v199
	v_pk_add_f32 v[192:193], v[192:193], 1.0 op_sel_hi:[1,0]
	v_pk_add_f32 v[194:195], v[194:195], 1.0 op_sel_hi:[1,0]
	v_pk_add_f32 v[196:197], v[196:197], 1.0 op_sel_hi:[1,0]
	v_pk_add_f32 v[198:199], v[198:199], 1.0 op_sel_hi:[1,0]
	v_rcp_f32_e32 v192, v192
	v_rcp_f32_e32 v193, v193
	v_rcp_f32_e32 v194, v194
	v_rcp_f32_e32 v195, v195
	v_rcp_f32_e32 v196, v196
	v_rcp_f32_e32 v197, v197
	v_rcp_f32_e32 v198, v198
	v_rcp_f32_e32 v199, v199
	s_nop 0
	v_cvt_pk_bf16_f32 v206, v192, v194
	v_cvt_pk_bf16_f32 v207, v196, v198
	v_add_u32_e32 v202, 0x51000, v200
	global_store_dwordx2 v202, v[206:207], s[24:25]
	v_cvt_pk_bf16_f32 v214, v193, v195
	v_cvt_pk_bf16_f32 v215, v197, v199
	global_store_dwordx2 v202, v[214:215], s[24:25] offset:2048
	v_pk_mul_f32 v[184:185], v[6:7], s[100:101] op_sel_hi:[1,0]
	v_pk_mul_f32 v[186:187], v[2:3], s[100:101] op_sel_hi:[1,0]
	v_pk_mul_f32 v[188:189], v[14:15], s[100:101] op_sel_hi:[1,0]
	v_pk_mul_f32 v[190:191], v[10:11], s[100:101] op_sel_hi:[1,0]
	v_exp_f32_e32 v184, v184
	v_exp_f32_e32 v185, v185
	v_exp_f32_e32 v186, v186
	v_exp_f32_e32 v187, v187
	v_exp_f32_e32 v188, v188
	v_exp_f32_e32 v189, v189
	v_exp_f32_e32 v190, v190
	v_exp_f32_e32 v191, v191
	v_pk_add_f32 v[184:185], v[184:185], 1.0 op_sel_hi:[1,0]
	v_pk_add_f32 v[186:187], v[186:187], 1.0 op_sel_hi:[1,0]
	v_pk_add_f32 v[188:189], v[188:189], 1.0 op_sel_hi:[1,0]
	v_pk_add_f32 v[190:191], v[190:191], 1.0 op_sel_hi:[1,0]
	v_rcp_f32_e32 v184, v184
	v_rcp_f32_e32 v185, v185
	v_rcp_f32_e32 v186, v186
	v_rcp_f32_e32 v187, v187
	v_rcp_f32_e32 v188, v188
	v_rcp_f32_e32 v189, v189
	v_rcp_f32_e32 v190, v190
	v_rcp_f32_e32 v191, v191
	s_nop 0
	v_cvt_pk_bf16_f32 v204, v184, v186
	v_cvt_pk_bf16_f32 v205, v188, v190
	v_add_u32_e32 v201, 0x58000, v200
	global_store_dwordx2 v201, v[204:205], s[24:25]
	v_cvt_pk_bf16_f32 v212, v185, v187
	v_cvt_pk_bf16_f32 v213, v189, v191
	global_store_dwordx2 v201, v[212:213], s[24:25] offset:2048
	v_pk_mul_f32 v[192:193], v[8:9], s[100:101] op_sel_hi:[1,0]
	v_pk_mul_f32 v[194:195], v[4:5], s[100:101] op_sel_hi:[1,0]
	v_pk_mul_f32 v[196:197], v[16:17], s[100:101] op_sel_hi:[1,0]
	v_pk_mul_f32 v[198:199], v[12:13], s[100:101] op_sel_hi:[1,0]
	v_exp_f32_e32 v192, v192
	v_exp_f32_e32 v193, v193
	v_exp_f32_e32 v194, v194
	v_exp_f32_e32 v195, v195
	v_exp_f32_e32 v196, v196
	v_exp_f32_e32 v197, v197
	v_exp_f32_e32 v198, v198
	v_exp_f32_e32 v199, v199
	v_pk_add_f32 v[192:193], v[192:193], 1.0 op_sel_hi:[1,0]
	v_pk_add_f32 v[194:195], v[194:195], 1.0 op_sel_hi:[1,0]
	v_pk_add_f32 v[196:197], v[196:197], 1.0 op_sel_hi:[1,0]
	v_pk_add_f32 v[198:199], v[198:199], 1.0 op_sel_hi:[1,0]
	v_rcp_f32_e32 v192, v192
	v_rcp_f32_e32 v193, v193
	v_rcp_f32_e32 v194, v194
	v_rcp_f32_e32 v195, v195
	v_rcp_f32_e32 v196, v196
	v_rcp_f32_e32 v197, v197
	v_rcp_f32_e32 v198, v198
	v_rcp_f32_e32 v199, v199
	s_nop 0
	v_cvt_pk_bf16_f32 v206, v192, v194
	v_cvt_pk_bf16_f32 v207, v196, v198
	v_add_u32_e32 v202, 0x59000, v200
	global_store_dwordx2 v202, v[206:207], s[24:25]
	v_cvt_pk_bf16_f32 v214, v193, v195
	v_cvt_pk_bf16_f32 v215, v197, v199
	global_store_dwordx2 v202, v[214:215], s[24:25] offset:2048
	s_branch .LBB0_445

; DEVINL float wave_sum(float v, int lane) {
; #pragma unroll
;   for (int o = 32; o > 0; o >>= 1) v += shflx(v, o, lane);
;   return v;
; template <bool FINAL>
; DEVINL void norm_phase(CParams& p, const Ctx& cx, bool from_x, int row0, int nrows, u16* dst, const float* gain, int l, int shi) {
;     ...
;   for (int row = cx.bid * 8 + wave; row < nrows; row += nw) {
;     const int grow = row0 + row;
;     const float4* xr = (const float4*)(from_x ? x_row(p, grow) : p.out + (size_t)grow * DM);
;     float4 v[4]; float ss = 0.f;
; #pragma unroll
;     for (int i = 0; i < 4; ++i) { v[i] = xr[lane + 64 * i]; ss += v[i].x * v[i].x + v[i].y * v[i].y + v[i].z * v[i].z + v[i].w * v[i].w; }
;     ss = wave_sum(ss, lane);
;     const float r = rsqrtf(ss * (1.f / DM) + 1e-6f);
;     if (FINAL) {
; #pragma unroll
;       for (int i = 0; i < 4; ++i) {
;         const int c = (lane + 64 * i) * 4;
;         const float4 g = *(const float4*)(gain + c);
;         float4 o; o.x = v[i].x * r * g.x; o.y = v[i].y * r * g.y; o.z = v[i].z * r * g.z; o.w = v[i].w * r * g.w;
;         *(float4*)(p.out + (size_t)grow * DM + c) = o;
;       }
.LBB0_1531:
	global_load_dwordx4 v[14:17], v[4:5], off offset:-2048
	global_load_dwordx4 v[18:21], v[4:5], off offset:-1024
	global_load_dwordx4 v[22:25], v[4:5], off
	global_load_dwordx4 v[26:29], v[4:5], off offset:1024
	global_load_dwordx4 v[30:33], v[2:3], off
	v_add_u32_e32 v6, s12, v6
	s_waitcnt vmcnt(0)
	v_mov_b32_e32 v36, v15
	v_mov_b32_e32 v37, v19
	v_mov_b32_e32 v34, v14
	v_mov_b32_e32 v35, v18
	v_mov_b32_e32 v44, v23
	v_mov_b32_e32 v45, v27
	v_pk_mul_f32 v[36:37], v[36:37], v[36:37]
	v_mov_b32_e32 v38, v16
	v_mov_b32_e32 v39, v20
	v_mov_b32_e32 v42, v22
	v_mov_b32_e32 v43, v26
	v_pk_mul_f32 v[44:45], v[44:45], v[44:45]
	v_pk_fma_f32 v[34:35], v[34:35], v[34:35], v[36:37]
	v_mov_b32_e32 v40, v17
	v_mov_b32_e32 v41, v21
	v_mov_b32_e32 v46, v24
	v_mov_b32_e32 v47, v28
	v_pk_fma_f32 v[36:37], v[42:43], v[42:43], v[44:45]
	v_pk_fma_f32 v[34:35], v[38:39], v[38:39], v[34:35]
	v_mov_b32_e32 v48, v25
	v_mov_b32_e32 v49, v29
	v_pk_fma_f32 v[36:37], v[46:47], v[46:47], v[36:37]
	v_pk_fma_f32 v[34:35], v[40:41], v[40:41], v[34:35]
	v_pk_fma_f32 v[36:37], v[48:49], v[48:49], v[36:37]
	v_add_f32_e32 v0, v34, v35
	v_add_f32_e32 v0, v0, v36
	v_add_f32_e32 v0, v0, v37
	v_mov_b32_e32 v13, v0
	s_nop 1
	v_permlane32_swap_b32_e32 v13, v0
	s_waitcnt lgkmcnt(0)
	v_add_f32_e32 v0, v0, v13
	v_mov_b32_e32 v13, v0
	s_nop 1
	v_permlane16_swap_b32_e32 v0, v13
	s_waitcnt lgkmcnt(0)
	v_add_f32_e32 v0, v0, v13
	s_nop 1
	v_mov_b32_dpp v13, v0 row_ror:8 row_mask:0xf bank_mask:0xf
	s_waitcnt lgkmcnt(0)
	v_add_f32_e32 v0, v0, v13
	s_nop 1
	v_mov_b32_dpp v13, v0 row_shl:4 row_mask:0xf bank_mask:0x5
	v_mov_b32_dpp v13, v0 row_shr:4 row_mask:0xf bank_mask:0xa
	s_waitcnt lgkmcnt(0)
	v_add_f32_e32 v0, v0, v13
	s_nop 1
	v_mov_b32_dpp v13, v0 quad_perm:[2,3,0,1] row_mask:0xf bank_mask:0xf
	s_waitcnt lgkmcnt(0)
	v_add_f32_e32 v0, v0, v13
	s_nop 1
	v_mov_b32_dpp v13, v0 quad_perm:[1,0,3,2] row_mask:0xf bank_mask:0xf
	s_waitcnt lgkmcnt(0)
	v_add_f32_e32 v0, v0, v13
	v_fmamk_f32 v0, v0, 0x3a800000, v243
	v_mul_f32_e32 v13, 0x4b800000, v0
	v_cmp_gt_f32_e32 vcc, s13, v0
	s_nop 1
	v_cndmask_b32_e32 v0, v0, v13, vcc
	v_rsq_f32_e32 v0, v0
	s_nop 0
	v_mul_f32_e32 v13, 0x45800000, v0
	v_cndmask_b32_e32 v0, v0, v13, vcc
	v_pk_mul_f32 v[14:15], v[14:15], v[0:1] op_sel_hi:[1,0]
	v_pk_mul_f32 v[16:17], v[16:17], v[0:1] op_sel_hi:[1,0]
	v_pk_mul_f32 v[14:15], v[30:31], v[14:15]
	v_pk_mul_f32 v[16:17], v[32:33], v[16:17]
	global_store_dwordx4 v[4:5], v[14:17], off offset:-2048
	global_load_dwordx4 v[14:17], v[2:3], off offset:1024
	v_pk_mul_f32 v[18:19], v[18:19], v[0:1] op_sel_hi:[1,0]
	v_pk_mul_f32 v[20:21], v[20:21], v[0:1] op_sel_hi:[1,0]
	v_cmp_lt_i32_e32 vcc, s27, v6
	s_or_b64 s[6:7], vcc, s[6:7]
	s_waitcnt vmcnt(0)
	v_pk_mul_f32 v[14:15], v[14:15], v[18:19]
	v_pk_mul_f32 v[16:17], v[16:17], v[20:21]
	global_store_dwordx4 v[4:5], v[14:17], off offset:-1024
	global_load_dwordx4 v[14:17], v[2:3], off offset:2048
	v_pk_mul_f32 v[18:19], v[22:23], v[0:1] op_sel_hi:[1,0]
	v_pk_mul_f32 v[20:21], v[24:25], v[0:1] op_sel_hi:[1,0]
	s_waitcnt vmcnt(0)
	v_pk_mul_f32 v[14:15], v[18:19], v[14:15]
	v_pk_mul_f32 v[16:17], v[20:21], v[16:17]
	global_store_dwordx4 v[4:5], v[14:17], off
	global_load_dwordx4 v[14:17], v[2:3], off offset:3072
	v_pk_mul_f32 v[18:19], v[26:27], v[0:1] op_sel_hi:[1,0]
	v_pk_mul_f32 v[20:21], v[28:29], v[0:1] op_sel_hi:[1,0]
	s_waitcnt vmcnt(0)
	v_pk_mul_f32 v[14:15], v[18:19], v[14:15]
	v_pk_mul_f32 v[16:17], v[20:21], v[16:17]
	global_store_dwordx4 v[4:5], v[14:17], off offset:1024
	v_lshl_add_u64 v[4:5], v[4:5], 0, s[30:31]
	s_andn2_b64 exec, exec, s[6:7]
	s_cbranch_execnz .LBB0_1531

; #define GSYNC() xcd_barrier(p.bar)
; #define GSYNC() grid.sync()
; __global__ void __launch_bounds__(512, 2) mega_kernel(Params p) {
;   cg::grid_group grid = cg::this_grid();
;     ...
;   if (p.ph_hi < 0) grid.sync();
;     ...
;   for (int ph = p.ph_lo; ph < p.ph_hi; ++ph) {
;     const bool worked = run_phase(ph, 0);
;     if (worked && ph + 1 < p.ph_hi) GSYNC();
;   }
; }
	.amdhsa_kernel _Z11mega_kernel6Params
		.amdhsa_group_segment_fixed_size 0
		.amdhsa_private_segment_fixed_size 0
		.amdhsa_kernarg_size 792
		.amdhsa_user_sgpr_count 2
		.amdhsa_user_sgpr_dispatch_ptr 0
		.amdhsa_user_sgpr_queue_ptr 0
		.amdhsa_user_sgpr_kernarg_segment_ptr 1
		.amdhsa_user_sgpr_dispatch_id 0
		.amdhsa_user_sgpr_kernarg_preload_length 0
		.amdhsa_user_sgpr_kernarg_preload_offset 0
		.amdhsa_user_sgpr_private_segment_size 0
		.amdhsa_uses_dynamic_stack 0
		.amdhsa_enable_private_segment 0
		.amdhsa_system_sgpr_workgroup_id_x 1
		.amdhsa_system_sgpr_workgroup_id_y 0
		.amdhsa_system_sgpr_workgroup_id_z 0
		.amdhsa_system_sgpr_workgroup_info 0
		.amdhsa_system_vgpr_workitem_id 2
		.amdhsa_next_free_vgpr 256
		.amdhsa_next_free_sgpr 102
		.amdhsa_accum_offset 256
		.amdhsa_reserve_vcc 1
		.amdhsa_float_round_mode_32 0
		.amdhsa_float_round_mode_16_64 0
		.amdhsa_float_denorm_mode_32 3
		.amdhsa_float_denorm_mode_16_64 3
		.amdhsa_dx10_clamp 1
		.amdhsa_ieee_mode 1
		.amdhsa_fp16_overflow 0
		.amdhsa_tg_split 0
		.amdhsa_exception_fp_ieee_invalid_op 0
		.amdhsa_exception_fp_denorm_src 0
		.amdhsa_exception_fp_ieee_div_zero 0
		.amdhsa_exception_fp_ieee_overflow 0
		.amdhsa_exception_fp_ieee_underflow 0
		.amdhsa_exception_fp_ieee_inexact 0
		.amdhsa_exception_int_div_zero 0
	.end_amdhsa_kernel

; #define GSYNC() xcd_barrier(p.bar)
; #define GSYNC() grid.sync()
; __global__ void __launch_bounds__(512, 2) mega_kernel(Params p) {
;   cg::grid_group grid = cg::this_grid();
;     ...
;   if (p.ph_hi < 0) grid.sync();
;     ...
;   for (int ph = p.ph_lo; ph < p.ph_hi; ++ph) {
;     const bool worked = run_phase(ph, 0);
;     if (worked && ph + 1 < p.ph_hi) GSYNC();
;   }
; }
amdhsa.kernels:
  - .agpr_count:     0
    .args:
      - .offset:         0
        .size:           536
        .value_kind:     by_value
      - .offset:         536
        .size:           4
        .value_kind:     hidden_block_count_x
      - .offset:         540
        .size:           4
        .value_kind:     hidden_block_count_y
      - .offset:         544
        .size:           4
        .value_kind:     hidden_block_count_z
      - .offset:         548
        .size:           2
        .value_kind:     hidden_group_size_x
      - .offset:         550
        .size:           2
        .value_kind:     hidden_group_size_y
      - .offset:         552
        .size:           2
        .value_kind:     hidden_group_size_z
      - .offset:         554
        .size:           2
        .value_kind:     hidden_remainder_x
      - .offset:         556
        .size:           2
        .value_kind:     hidden_remainder_y
      - .offset:         558
        .size:           2
        .value_kind:     hidden_remainder_z
      - .offset:         576
        .size:           8
        .value_kind:     hidden_global_offset_x
      - .offset:         584
        .size:           8
        .value_kind:     hidden_global_offset_y
      - .offset:         592
        .size:           8
        .value_kind:     hidden_global_offset_z
      - .offset:         600
        .size:           2
        .value_kind:     hidden_grid_dims
      - .offset:         624
        .size:           8
        .value_kind:     hidden_multigrid_sync_arg
      - .offset:         656
        .size:           4
        .value_kind:     hidden_dynamic_lds_size
    .group_segment_fixed_size: 0
    .kernarg_segment_align: 8
    .kernarg_segment_size: 792
    .language:       OpenCL C
    .language_version:
      - 2
      - 0
    .max_flat_workgroup_size: 512
    .name:           _Z11mega_kernel6Params
    .private_segment_fixed_size: 0
    .sgpr_count:     108
    .sgpr_spill_count: 64
    .symbol:         _Z11mega_kernel6Params.kd
    .uniform_work_group_size: 1
    .uses_dynamic_stack: false
    .vgpr_count:     256
    .vgpr_spill_count: 0
    .wavefront_size: 64
